# Hyena FFT stagger: waves 4-7 sleep 8x64 cycles only at the head of the two barrier-free three-pass chains per channel
# speedup vs baseline: 1.0137x; 1.0137x over previous
; #define LAS __attribute__((address_space(3)))
; #define WG_SYNC() do { asm volatile("s_waitcnt lgkmcnt(0)" ::: "memory"); __builtin_amdgcn_s_barrier(); asm volatile("" ::: "memory"); } while (0)
; __device__ __forceinline__ void hy_stage(LAS float* plane, const bf16_t* PHY, int cg, int jc, int tid) {
;     asm volatile("" : "+v"(tid));
;     const u32x4* src = (const u32x4*)(PHY + (size_t)cg * MT * 4);
; #pragma unroll
;     for (int k = 0; k < 8; ++k) { const int i = tid + 512 * k; const u32x4 v = src[i];
;         const unsigned w0 = (jc & 2) ? v.y : v.x, w1 = (jc & 2) ? v.w : v.z;
;         f32x2 o; o.x = (jc & 1) ? bf_hi(w0) : bf_lo(w0); o.y = (jc & 1) ? bf_hi(w1) : bf_lo(w1);
;         *(LAS f32x2*)(plane + 2 * i) = o; }
; }
; __device__ __forceinline__ void hyena_fft(LAS unsigned char* lds, int layer, int G, const int wave_s) {
;     ...
;         for (int c = c_lo; c < c_hi; ++c) { const int unit = c >> 2, jc = c & 3;
;             WG_SYNC();
;             { f32x2 x[16]; const unsigned* tf = TF + (size_t)c * SEQ; const unsigned* tb = TB + (size_t)c * SEQ;
; #pragma unroll
;               for (int r = 0; r < 8; ++r) { const unsigned w = tf[n2 + 512 * r]; x[r] = (f32x2){bf_lo(w), bf_hi(w)}; }
; #pragma unroll
;               for (int r = 8; r < 16; ++r) { const int l = FN - 512 * r - n2; const unsigned w = l < SEQ ? tb[l] : 0u; x[r] = (f32x2){bf_lo(w), bf_hi(w)}; }
;               __builtin_amdgcn_sched_barrier(0); fft_fwd1<false>(x, Fb, n2, w1p); __builtin_amdgcn_sched_barrier(0); }
.Lhfft_loop:
	s_lshr_b32 s43, s80, 2
	s_mul_i32 s73, s43, 0x11000
	s_and_b32 s43, s80, 2
	s_lshl_b32 s43, s43, 1
	s_add_u32 s73, s73, s43
	s_and_b32 s43, s80, 1
	s_mov_b32 s15, 0x1000c0c
	s_cmp_eq_u32 s43, 0
	s_cselect_b32 s15, s15, 0x3020c0c
	s_lshl_b32 s43, s80, 14
	s_add_u32 s46, s36, s43
	s_addc_u32 s47, s37, 0
	s_add_u32 s50, s46, 0x4000000
	s_addc_u32 s51, s47, 0
	s_waitcnt lgkmcnt(0)
	s_barrier
	s_add_u32 s60, s46, 0
	s_addc_u32 s61, s47, 0
	global_load_dword v176, v212, s[60:61]
	global_load_dword v178, v212, s[60:61] offset:2048
	s_add_u32 s60, s46, 0x1000
	s_addc_u32 s61, s47, 0
	global_load_dword v180, v212, s[60:61]
	global_load_dword v182, v212, s[60:61] offset:2048
	s_add_u32 s60, s46, 0x2000
	s_addc_u32 s61, s47, 0
	global_load_dword v184, v212, s[60:61]
	global_load_dword v186, v212, s[60:61] offset:2048
	s_add_u32 s60, s46, 0x3000
	s_addc_u32 s61, s47, 0
	global_load_dword v188, v212, s[60:61]
	global_load_dword v166, v212, s[60:61] offset:2048
	s_add_u32 s62, s50, 0x3000
	s_addc_u32 s63, s51, 0
	global_load_dword v177, v214, s[62:63] offset:2048
	global_load_dword v179, v214, s[62:63]
	s_add_u32 s62, s50, 0x2000
	s_addc_u32 s63, s51, 0
	global_load_dword v181, v214, s[62:63] offset:2048
	global_load_dword v183, v214, s[62:63]
	s_add_u32 s62, s50, 0x1000
	s_addc_u32 s63, s51, 0
	global_load_dword v185, v214, s[62:63] offset:2048
	global_load_dword v187, v214, s[62:63]
	s_add_u32 s62, s50, 0
	s_addc_u32 s63, s51, 0
	global_load_dword v189, v214, s[62:63] offset:2048
	global_load_dword v167, v214, s[62:63]
	s_add_u32 s56, s38, s73
	s_addc_u32 s57, s39, 0
	s_add_u32 s56, s56, 0x2200000
	s_addc_u32 s57, s57, 0
	global_load_dwordx3 v[58:60], v216, s[56:57]
	global_load_dwordx3 v[62:64], v218, s[56:57]
	global_load_dwordx3 v[66:68], v220, s[56:57]
	global_load_dwordx3 v[70:72], v222, s[56:57]
	global_load_dwordx3 v[74:76], v240, s[56:57]
	global_load_dwordx3 v[78:80], v242, s[56:57]
	global_load_dwordx3 v[82:84], v244, s[56:57]
	global_load_dwordx3 v[86:88], v61, s[56:57]
	s_waitcnt vmcnt(23)
	v_and_b32_e32 v101, 0xffff0000, v176
	v_lshlrev_b32_e32 v100, 16, v176
	s_waitcnt vmcnt(22)
	v_and_b32_e32 v103, 0xffff0000, v178
	v_lshlrev_b32_e32 v102, 16, v178
	s_waitcnt vmcnt(21)
	v_and_b32_e32 v105, 0xffff0000, v180
	v_lshlrev_b32_e32 v104, 16, v180
	s_waitcnt vmcnt(20)
	v_and_b32_e32 v107, 0xffff0000, v182
	v_lshlrev_b32_e32 v106, 16, v182
	s_waitcnt vmcnt(19)
	v_and_b32_e32 v109, 0xffff0000, v184
	v_lshlrev_b32_e32 v108, 16, v184
	s_waitcnt vmcnt(18)
	v_and_b32_e32 v111, 0xffff0000, v186
	v_lshlrev_b32_e32 v110, 16, v186
	s_waitcnt vmcnt(17)
	v_and_b32_e32 v113, 0xffff0000, v188
	v_lshlrev_b32_e32 v112, 16, v188
	s_waitcnt vmcnt(16)
	v_and_b32_e32 v115, 0xffff0000, v166
	v_lshlrev_b32_e32 v114, 16, v166
	s_waitcnt vmcnt(15)
	v_cndmask_b32_e64 v177, v177, 0, s[10:11]
	v_and_b32_e32 v117, 0xffff0000, v177
	v_lshlrev_b32_e32 v116, 16, v177
	s_waitcnt vmcnt(14)
	v_and_b32_e32 v119, 0xffff0000, v179
	v_lshlrev_b32_e32 v118, 16, v179
	s_waitcnt vmcnt(13)
	v_and_b32_e32 v121, 0xffff0000, v181
	v_lshlrev_b32_e32 v120, 16, v181
	s_waitcnt vmcnt(12)
	v_and_b32_e32 v123, 0xffff0000, v183
	v_lshlrev_b32_e32 v122, 16, v183
	s_waitcnt vmcnt(11)
	v_and_b32_e32 v125, 0xffff0000, v185
	v_lshlrev_b32_e32 v124, 16, v185
	s_waitcnt vmcnt(10)
	v_and_b32_e32 v127, 0xffff0000, v187
	v_lshlrev_b32_e32 v126, 16, v187
	s_waitcnt vmcnt(9)
	v_and_b32_e32 v129, 0xffff0000, v189
	v_lshlrev_b32_e32 v128, 16, v189
	s_waitcnt vmcnt(8)
	v_and_b32_e32 v131, 0xffff0000, v167
	v_lshlrev_b32_e32 v130, 16, v167
	v_pk_add_f32 v[168:169], v[100:101], v[116:117]
	v_pk_add_f32 v[174:175], v[100:101], v[116:117] neg_lo:[0,1] neg_hi:[0,1]
	v_pk_add_f32 v[176:177], v[108:109], v[124:125]
	v_pk_add_f32 v[178:179], v[108:109], v[124:125] neg_lo:[0,1] neg_hi:[0,1]
	v_pk_add_f32 v[100:101], v[168:169], v[176:177]
	v_pk_add_f32 v[116:117], v[168:169], v[176:177] neg_lo:[0,1] neg_hi:[0,1]
	v_pk_add_f32 v[108:109], v[174:175], v[178:179] op_sel:[0,1] op_sel_hi:[1,0] neg_hi:[0,1]
	v_pk_add_f32 v[124:125], v[174:175], v[178:179] op_sel:[0,1] op_sel_hi:[1,0] neg_lo:[0,1]
	v_pk_add_f32 v[180:181], v[102:103], v[118:119]
	v_pk_add_f32 v[182:183], v[102:103], v[118:119] neg_lo:[0,1] neg_hi:[0,1]
	v_pk_add_f32 v[184:185], v[110:111], v[126:127]
	v_pk_add_f32 v[186:187], v[110:111], v[126:127] neg_lo:[0,1] neg_hi:[0,1]
	v_pk_add_f32 v[102:103], v[180:181], v[184:185]
	v_pk_add_f32 v[118:119], v[180:181], v[184:185] neg_lo:[0,1] neg_hi:[0,1]
	v_pk_add_f32 v[110:111], v[182:183], v[186:187] op_sel:[0,1] op_sel_hi:[1,0] neg_hi:[0,1]
	v_pk_add_f32 v[126:127], v[182:183], v[186:187] op_sel:[0,1] op_sel_hi:[1,0] neg_lo:[0,1]
	v_pk_add_f32 v[188:189], v[104:105], v[120:121]
	v_pk_add_f32 v[166:167], v[104:105], v[120:121] neg_lo:[0,1] neg_hi:[0,1]
	v_pk_add_f32 v[168:169], v[112:113], v[128:129]
	v_pk_add_f32 v[174:175], v[112:113], v[128:129] neg_lo:[0,1] neg_hi:[0,1]
	v_pk_add_f32 v[104:105], v[188:189], v[168:169]
	v_pk_add_f32 v[120:121], v[188:189], v[168:169] neg_lo:[0,1] neg_hi:[0,1]
	v_pk_add_f32 v[112:113], v[166:167], v[174:175] op_sel:[0,1] op_sel_hi:[1,0] neg_hi:[0,1]
	v_pk_add_f32 v[128:129], v[166:167], v[174:175] op_sel:[0,1] op_sel_hi:[1,0] neg_lo:[0,1]
	v_pk_add_f32 v[176:177], v[106:107], v[122:123]
	v_pk_add_f32 v[178:179], v[106:107], v[122:123] neg_lo:[0,1] neg_hi:[0,1]
	v_pk_add_f32 v[180:181], v[114:115], v[130:131]
	v_pk_add_f32 v[182:183], v[114:115], v[130:131] neg_lo:[0,1] neg_hi:[0,1]
	v_pk_add_f32 v[106:107], v[176:177], v[180:181]
	v_pk_add_f32 v[122:123], v[176:177], v[180:181] neg_lo:[0,1] neg_hi:[0,1]
	v_pk_add_f32 v[114:115], v[178:179], v[182:183] op_sel:[0,1] op_sel_hi:[1,0] neg_hi:[0,1]
; #define LAS __attribute__((address_space(3)))
; __device__ __forceinline__ f32x2 cmul(f32x2 a, f32x2 b) { return (f32x2){a.x * b.x - a.y * b.y, a.x * b.y + a.y * b.x}; }
; template <bool INV> __device__ __forceinline__ f32x2 cmul_tw(f32x2 a, f32x2 w) { return INV ? cmulc(a, w) : cmul(a, w); }
; template <bool INV> __device__ __forceinline__ void dft16(f32x2 (&x)[16]) {
;     constexpr float C1 = 0.92387953251128674f, S1 = 0.38268343236508977f, C2 = 0.70710678118654752f;
; #pragma unroll
;     for (int b = 0; b < 4; ++b) dft4<INV>(x[b], x[4 + b], x[8 + b], x[12 + b]);
;     const f32x2 w1 = {C1, -S1}, w2 = {C2, -C2}, w3 = {S1, -C1}, w4 = {0.f, -1.f}, w6 = {-C2, -C2}, w9 = {-C1, S1};
;     x[4 * 1 + 1] = cmul_tw<INV>(x[5], w1); x[4 * 1 + 2] = cmul_tw<INV>(x[6], w2); x[4 * 1 + 3] = cmul_tw<INV>(x[7], w3);
;     x[4 * 2 + 1] = cmul_tw<INV>(x[9], w2); x[4 * 2 + 2] = cmul_tw<INV>(x[10], w4); x[4 * 2 + 3] = cmul_tw<INV>(x[11], w6);
;     x[4 * 3 + 1] = cmul_tw<INV>(x[13], w3); x[4 * 3 + 2] = cmul_tw<INV>(x[14], w6); x[4 * 3 + 3] = cmul_tw<INV>(x[15], w9);
; #pragma unroll
;     for (int c = 0; c < 4; ++c) dft4<INV>(x[4 * c], x[4 * c + 1], x[4 * c + 2], x[4 * c + 3]);
;     f32x2 y[16];
; #pragma unroll
;     for (int k = 0; k < 16; ++k) y[k] = x[4 * (k & 3) + (k >> 2)];
; #pragma unroll
;     for (int k = 0; k < 16; ++k) x[k] = y[k];
; template <bool LO> __device__ __forceinline__ void fft_fwd1(f32x2 (&x)[16], LAS f32x2* B, int n2, const f32x2 (&w)[16]) {
;     asm volatile("" : "+v"(n2));
;     if (LO) dft16_fwd_lo(x); else dft16<false>(x);
;     B[fpad(n2)] = x[0];
; #pragma unroll
;     for (int k = 1; k < 16; ++k) B[fpad(512 * k + n2)] = cmul(x[k], w[k]);
; }
	v_pk_add_f32 v[130:131], v[178:179], v[182:183] op_sel:[0,1] op_sel_hi:[1,0] neg_lo:[0,1]
	v_pk_mul_f32 v[184:185], v[110:111], s[68:69] op_sel:[1,1] op_sel_hi:[0,1]
	v_pk_fma_f32 v[110:111], v[110:111], s[68:69], v[184:185] op_sel_hi:[1,0,1] neg_lo:[0,0,1]
	v_pk_mul_f32 v[186:187], v[112:113], s[84:85] op_sel:[1,1] op_sel_hi:[0,1]
	v_pk_fma_f32 v[112:113], v[112:113], s[84:85], v[186:187] op_sel_hi:[1,0,1] neg_lo:[0,0,1]
	v_pk_mul_f32 v[188:189], v[114:115], s[88:89] op_sel:[1,1] op_sel_hi:[0,1]
	v_pk_fma_f32 v[114:115], v[114:115], s[88:89], v[188:189] op_sel_hi:[1,0,1] neg_lo:[0,0,1]
	v_pk_mul_f32 v[166:167], v[118:119], s[84:85] op_sel:[1,1] op_sel_hi:[0,1]
	v_pk_fma_f32 v[118:119], v[118:119], s[84:85], v[166:167] op_sel_hi:[1,0,1] neg_lo:[0,0,1]
	v_pk_mul_f32 v[168:169], v[122:123], s[90:91] op_sel:[1,1] op_sel_hi:[0,1]
	v_pk_fma_f32 v[122:123], v[122:123], s[90:91], v[168:169] op_sel_hi:[1,0,1] neg_lo:[0,0,1]
	v_pk_mul_f32 v[174:175], v[126:127], s[88:89] op_sel:[1,1] op_sel_hi:[0,1]
	v_pk_fma_f32 v[126:127], v[126:127], s[88:89], v[174:175] op_sel_hi:[1,0,1] neg_lo:[0,0,1]
	v_pk_mul_f32 v[176:177], v[128:129], s[90:91] op_sel:[1,1] op_sel_hi:[0,1]
	v_pk_fma_f32 v[128:129], v[128:129], s[90:91], v[176:177] op_sel_hi:[1,0,1] neg_lo:[0,0,1]
	v_pk_mul_f32 v[178:179], v[130:131], s[98:99] op_sel:[1,1] op_sel_hi:[0,1]
	v_pk_fma_f32 v[130:131], v[130:131], s[98:99], v[178:179] op_sel_hi:[1,0,1] neg_lo:[0,0,1]
	v_pk_add_f32 v[180:181], v[100:101], v[104:105]
	v_pk_add_f32 v[182:183], v[100:101], v[104:105] neg_lo:[0,1] neg_hi:[0,1]
	v_pk_add_f32 v[184:185], v[102:103], v[106:107]
	v_pk_add_f32 v[186:187], v[102:103], v[106:107] neg_lo:[0,1] neg_hi:[0,1]
	v_pk_add_f32 v[100:101], v[180:181], v[184:185]
	v_pk_add_f32 v[104:105], v[180:181], v[184:185] neg_lo:[0,1] neg_hi:[0,1]
	v_pk_add_f32 v[102:103], v[182:183], v[186:187] op_sel:[0,1] op_sel_hi:[1,0] neg_hi:[0,1]
	v_pk_add_f32 v[106:107], v[182:183], v[186:187] op_sel:[0,1] op_sel_hi:[1,0] neg_lo:[0,1]
	v_pk_add_f32 v[188:189], v[108:109], v[112:113]
	v_pk_add_f32 v[166:167], v[108:109], v[112:113] neg_lo:[0,1] neg_hi:[0,1]
	v_pk_add_f32 v[168:169], v[110:111], v[114:115]
	v_pk_add_f32 v[174:175], v[110:111], v[114:115] neg_lo:[0,1] neg_hi:[0,1]
	v_pk_add_f32 v[108:109], v[188:189], v[168:169]
	v_pk_add_f32 v[112:113], v[188:189], v[168:169] neg_lo:[0,1] neg_hi:[0,1]
	v_pk_add_f32 v[110:111], v[166:167], v[174:175] op_sel:[0,1] op_sel_hi:[1,0] neg_hi:[0,1]
	v_pk_add_f32 v[114:115], v[166:167], v[174:175] op_sel:[0,1] op_sel_hi:[1,0] neg_lo:[0,1]
	v_pk_add_f32 v[176:177], v[116:117], v[120:121] op_sel:[0,1] op_sel_hi:[1,0] neg_hi:[0,1]
	v_pk_add_f32 v[178:179], v[116:117], v[120:121] op_sel:[0,1] op_sel_hi:[1,0] neg_lo:[0,1]
	v_pk_add_f32 v[180:181], v[118:119], v[122:123]
	v_pk_add_f32 v[182:183], v[118:119], v[122:123] neg_lo:[0,1] neg_hi:[0,1]
	v_pk_add_f32 v[116:117], v[176:177], v[180:181]
	v_pk_add_f32 v[120:121], v[176:177], v[180:181] neg_lo:[0,1] neg_hi:[0,1]
	v_pk_add_f32 v[118:119], v[178:179], v[182:183] op_sel:[0,1] op_sel_hi:[1,0] neg_hi:[0,1]
	v_pk_add_f32 v[122:123], v[178:179], v[182:183] op_sel:[0,1] op_sel_hi:[1,0] neg_lo:[0,1]
	v_pk_add_f32 v[184:185], v[124:125], v[128:129]
	v_pk_add_f32 v[186:187], v[124:125], v[128:129] neg_lo:[0,1] neg_hi:[0,1]
	v_pk_add_f32 v[188:189], v[126:127], v[130:131]
	v_pk_add_f32 v[166:167], v[126:127], v[130:131] neg_lo:[0,1] neg_hi:[0,1]
	v_pk_add_f32 v[124:125], v[184:185], v[188:189]
	v_pk_add_f32 v[128:129], v[184:185], v[188:189] neg_lo:[0,1] neg_hi:[0,1]
	v_pk_add_f32 v[126:127], v[186:187], v[166:167] op_sel:[0,1] op_sel_hi:[1,0] neg_hi:[0,1]
	v_pk_add_f32 v[130:131], v[186:187], v[166:167] op_sel:[0,1] op_sel_hi:[1,0] neg_lo:[0,1]
	v_add_u32_e32 v65, 0x10800, v3
	ds_write_b64 v65, v[100:101]
	v_pk_mul_f32 v[174:175], v[108:109], v[6:7] op_sel:[1,1] op_sel_hi:[0,1]
	v_pk_fma_f32 v[168:169], v[108:109], v[6:7], v[174:175] op_sel_hi:[1,0,1] neg_lo:[0,0,1]
	ds_write_b64 v65, v[168:169] offset:4224
	v_pk_mul_f32 v[178:179], v[116:117], v[8:9] op_sel:[1,1] op_sel_hi:[0,1]
	v_pk_fma_f32 v[176:177], v[116:117], v[8:9], v[178:179] op_sel_hi:[1,0,1] neg_lo:[0,0,1]
	ds_write_b64 v65, v[176:177] offset:8448
	v_pk_mul_f32 v[182:183], v[124:125], v[10:11] op_sel:[1,1] op_sel_hi:[0,1]
	v_pk_fma_f32 v[180:181], v[124:125], v[10:11], v[182:183] op_sel_hi:[1,0,1] neg_lo:[0,0,1]
	ds_write_b64 v65, v[180:181] offset:12672
	v_pk_mul_f32 v[186:187], v[102:103], v[12:13] op_sel:[1,1] op_sel_hi:[0,1]
	v_pk_fma_f32 v[184:185], v[102:103], v[12:13], v[186:187] op_sel_hi:[1,0,1] neg_lo:[0,0,1]
	ds_write_b64 v65, v[184:185] offset:16896
	v_pk_mul_f32 v[166:167], v[110:111], v[14:15] op_sel:[1,1] op_sel_hi:[0,1]
	v_pk_fma_f32 v[188:189], v[110:111], v[14:15], v[166:167] op_sel_hi:[1,0,1] neg_lo:[0,0,1]
	ds_write_b64 v65, v[188:189] offset:21120
	v_pk_mul_f32 v[168:169], v[118:119], v[16:17] op_sel:[1,1] op_sel_hi:[0,1]
	v_pk_fma_f32 v[174:175], v[118:119], v[16:17], v[168:169] op_sel_hi:[1,0,1] neg_lo:[0,0,1]
	ds_write_b64 v65, v[174:175] offset:25344
	v_pk_mul_f32 v[176:177], v[126:127], v[18:19] op_sel:[1,1] op_sel_hi:[0,1]
	v_pk_fma_f32 v[178:179], v[126:127], v[18:19], v[176:177] op_sel_hi:[1,0,1] neg_lo:[0,0,1]
	ds_write_b64 v65, v[178:179] offset:29568
	v_pk_mul_f32 v[180:181], v[104:105], v[20:21] op_sel:[1,1] op_sel_hi:[0,1]
	v_pk_fma_f32 v[182:183], v[104:105], v[20:21], v[180:181] op_sel_hi:[1,0,1] neg_lo:[0,0,1]
	ds_write_b64 v65, v[182:183] offset:33792
	v_pk_mul_f32 v[184:185], v[112:113], v[22:23] op_sel:[1,1] op_sel_hi:[0,1]
	v_pk_fma_f32 v[186:187], v[112:113], v[22:23], v[184:185] op_sel_hi:[1,0,1] neg_lo:[0,0,1]
	ds_write_b64 v65, v[186:187] offset:38016
	v_pk_mul_f32 v[188:189], v[120:121], v[24:25] op_sel:[1,1] op_sel_hi:[0,1]
	v_pk_fma_f32 v[166:167], v[120:121], v[24:25], v[188:189] op_sel_hi:[1,0,1] neg_lo:[0,0,1]
	ds_write_b64 v65, v[166:167] offset:42240
	v_pk_mul_f32 v[174:175], v[128:129], v[26:27] op_sel:[1,1] op_sel_hi:[0,1]
	v_pk_fma_f32 v[168:169], v[128:129], v[26:27], v[174:175] op_sel_hi:[1,0,1] neg_lo:[0,0,1]
	ds_write_b64 v65, v[168:169] offset:46464
	v_pk_mul_f32 v[178:179], v[106:107], v[28:29] op_sel:[1,1] op_sel_hi:[0,1]
	v_pk_fma_f32 v[176:177], v[106:107], v[28:29], v[178:179] op_sel_hi:[1,0,1] neg_lo:[0,0,1]
	ds_write_b64 v65, v[176:177] offset:50688
	v_pk_mul_f32 v[182:183], v[114:115], v[30:31] op_sel:[1,1] op_sel_hi:[0,1]
	v_pk_fma_f32 v[180:181], v[114:115], v[30:31], v[182:183] op_sel_hi:[1,0,1] neg_lo:[0,0,1]
	ds_write_b64 v65, v[180:181] offset:54912
	v_pk_mul_f32 v[186:187], v[122:123], v[32:33] op_sel:[1,1] op_sel_hi:[0,1]
	v_pk_fma_f32 v[184:185], v[122:123], v[32:33], v[186:187] op_sel_hi:[1,0,1] neg_lo:[0,0,1]
	ds_write_b64 v65, v[184:185] offset:59136
	v_pk_mul_f32 v[166:167], v[130:131], v[34:35] op_sel:[1,1] op_sel_hi:[0,1]
	v_pk_fma_f32 v[188:189], v[130:131], v[34:35], v[166:167] op_sel_hi:[1,0,1] neg_lo:[0,0,1]
	ds_write_b64 v65, v[188:189] offset:63360
	s_waitcnt vmcnt(7)
; #define LAS __attribute__((address_space(3)))
; #define WG_SYNC() do { asm volatile("s_waitcnt lgkmcnt(0)" ::: "memory"); __builtin_amdgcn_s_barrier(); asm volatile("" ::: "memory"); } while (0)
; __device__ __forceinline__ void hy_stage(LAS float* plane, const bf16_t* PHY, int cg, int jc, int tid) {
;     asm volatile("" : "+v"(tid));
;     const u32x4* src = (const u32x4*)(PHY + (size_t)cg * MT * 4);
; #pragma unroll
;     for (int k = 0; k < 8; ++k) { const int i = tid + 512 * k; const u32x4 v = src[i];
;         const unsigned w0 = (jc & 2) ? v.y : v.x, w1 = (jc & 2) ? v.w : v.z;
;         f32x2 o; o.x = (jc & 1) ? bf_hi(w0) : bf_lo(w0); o.y = (jc & 1) ? bf_hi(w1) : bf_lo(w1);
;         *(LAS f32x2*)(plane + 2 * i) = o; }
; }
; __device__ __forceinline__ void hy_sconv(const LAS float* plane, float w0, float w1, float w2, float cb, int n2, float (&u)[8][2]) {
;     asm volatile("" : "+v"(n2));
; #pragma unroll
;     for (int r = 0; r < 8; ++r)
; #pragma unroll
;         for (int b = 0; b < 2; ++b) { const int t = n2 + 512 * r, row = b * SEQ + t;
;             float a = cb + w1 * plane[row];
;             if (t > 0) a += w0 * plane[row - 1];
;             if (t < SEQ - 1) a += w2 * plane[row + 1];
;             u[r][b] = a; }
; }
; __device__ __forceinline__ void hyena_fft(LAS unsigned char* lds, int layer, int G, const int wave_s) {
;     ...
;             hy_stage(pl0, PHY, 2 * (HY / 4) + unit, jc, tid); __builtin_amdgcn_sched_barrier(0); hy_stage(pl1, PHY, unit, jc, tid); __builtin_amdgcn_sched_barrier(0);
;             WG_SYNC();
;             float uz[8][2], ux[8][2];
;             hy_sconv(pl0, cw[2 * HY + c], cw[3 * HY + 2 * HY + c], cw[6 * HY + 2 * HY + c], cb[2 * HY + c], n2, uz);
	v_perm_b32 v174, 0, v58, s15
	v_perm_b32 v175, 0, v60, s15
	ds_write_b64 v206, v[174:175]
	s_waitcnt vmcnt(6)
	v_perm_b32 v168, 0, v62, s15
	v_perm_b32 v169, 0, v64, s15
	ds_write_b64 v206, v[168:169] offset:4096
	s_waitcnt vmcnt(5)
	v_perm_b32 v178, 0, v66, s15
	v_perm_b32 v179, 0, v68, s15
	ds_write_b64 v206, v[178:179] offset:8192
	s_waitcnt vmcnt(4)
	v_perm_b32 v176, 0, v70, s15
	v_perm_b32 v177, 0, v72, s15
	ds_write_b64 v206, v[176:177] offset:12288
	s_waitcnt vmcnt(3)
	v_perm_b32 v182, 0, v74, s15
	v_perm_b32 v183, 0, v76, s15
	ds_write_b64 v206, v[182:183] offset:16384
	s_waitcnt vmcnt(2)
	v_perm_b32 v180, 0, v78, s15
	v_perm_b32 v181, 0, v80, s15
	ds_write_b64 v206, v[180:181] offset:20480
	s_waitcnt vmcnt(1)
	v_perm_b32 v186, 0, v82, s15
	v_perm_b32 v187, 0, v84, s15
	ds_write_b64 v206, v[186:187] offset:24576
	s_waitcnt vmcnt(0)
	v_perm_b32 v184, 0, v86, s15
	v_perm_b32 v185, 0, v88, s15
	ds_write_b64 v206, v[184:185] offset:28672
	s_add_u32 s56, s38, s73
	s_addc_u32 s57, s39, 0
	global_load_dwordx3 v[58:60], v216, s[56:57]
	global_load_dwordx3 v[62:64], v218, s[56:57]
	global_load_dwordx3 v[66:68], v220, s[56:57]
	global_load_dwordx3 v[70:72], v222, s[56:57]
	global_load_dwordx3 v[74:76], v240, s[56:57]
	global_load_dwordx3 v[78:80], v242, s[56:57]
	global_load_dwordx3 v[82:84], v244, s[56:57]
	global_load_dwordx3 v[86:88], v61, s[56:57]
	s_load_dwordx2 s[60:61], s[94:95], 0x48
	s_load_dwordx2 s[62:63], s[94:95], 0x50
	s_load_dwordx2 s[50:51], s[94:95], 0x88
	s_lshl_b32 s43, s80, 2
	s_mul_i32 s53, s76, 0x9000
	s_add_u32 s53, s53, s43
	s_mul_i32 s55, s76, 0x3000
	s_add_u32 s55, s55, s43
	s_waitcnt lgkmcnt(0)
	s_add_u32 s60, s60, s53
	s_addc_u32 s61, s61, 0
	s_add_u32 s62, s62, s55
	s_addc_u32 s63, s63, 0
	s_mul_i32 s53, s76, 0x2000
	s_add_u32 s53, s53, s43
	s_add_u32 s50, s50, s53
	s_addc_u32 s51, s51, 0
	s_load_dword s17, s[60:61], 0x2000
	s_load_dword s23, s[60:61], 0x5000
	s_load_dword s25, s[60:61], 0x8000
	s_load_dword s26, s[62:63], 0x2000
	s_waitcnt lgkmcnt(0)
	s_barrier
	v_mov_b32_e32 v166, s17
	v_mov_b32_e32 v167, s23
	v_mov_b32_e32 v188, s25
	v_mov_b32_e32 v189, s26
	ds_read_b32 v174, v208
	ds_read_b32 v168, v210
	ds_read_b32 v178, v208 offset:4
	ds_read_b32 v175, v208 offset:16384
	ds_read_b32 v169, v210 offset:16384
	ds_read_b32 v179, v208 offset:16388
	ds_read_b32 v176, v208 offset:2048
	ds_read_b32 v182, v208 offset:2044
	ds_read_b32 v180, v208 offset:2052
	ds_read_b32 v177, v208 offset:18432
	ds_read_b32 v183, v208 offset:18428
	ds_read_b32 v181, v208 offset:18436
	s_waitcnt lgkmcnt(10)
	v_cndmask_b32_e64 v168, v168, 0, s[10:11]
	s_waitcnt lgkmcnt(7)
	v_cndmask_b32_e64 v169, v169, 0, s[10:11]
	v_pk_fma_f32 v[132:133], v[166:167], v[174:175], v[188:189] op_sel:[1,0,1]
	v_pk_fma_f32 v[132:133], v[166:167], v[168:169], v[132:133] op_sel_hi:[0,1,1]
	s_waitcnt lgkmcnt(6)
	v_pk_fma_f32 v[132:133], v[188:189], v[178:179], v[132:133] op_sel_hi:[0,1,1]
	s_waitcnt lgkmcnt(2)
	v_pk_fma_f32 v[134:135], v[166:167], v[176:177], v[188:189] op_sel:[1,0,1]
	s_waitcnt lgkmcnt(1)
	v_pk_fma_f32 v[134:135], v[166:167], v[182:183], v[134:135] op_sel_hi:[0,1,1]
	s_waitcnt lgkmcnt(0)
	v_pk_fma_f32 v[134:135], v[188:189], v[180:181], v[134:135] op_sel_hi:[0,1,1]
	ds_read_b32 v186, v208 offset:4096
	ds_read_b32 v184, v208 offset:4092
	ds_read_b32 v174, v208 offset:4100
	ds_read_b32 v187, v208 offset:20480
	ds_read_b32 v185, v208 offset:20476
	ds_read_b32 v175, v208 offset:20484
	ds_read_b32 v168, v208 offset:6144
	ds_read_b32 v178, v208 offset:6140
	ds_read_b32 v176, v208 offset:6148
	ds_read_b32 v169, v208 offset:22528
	ds_read_b32 v179, v208 offset:22524
	ds_read_b32 v177, v208 offset:22532
	s_waitcnt lgkmcnt(8)
	v_pk_fma_f32 v[136:137], v[166:167], v[186:187], v[188:189] op_sel:[1,0,1]
	s_waitcnt lgkmcnt(7)
	v_pk_fma_f32 v[136:137], v[166:167], v[184:185], v[136:137] op_sel_hi:[0,1,1]
	s_waitcnt lgkmcnt(6)
	v_pk_fma_f32 v[136:137], v[188:189], v[174:175], v[136:137] op_sel_hi:[0,1,1]
	s_waitcnt lgkmcnt(2)
	v_pk_fma_f32 v[138:139], v[166:167], v[168:169], v[188:189] op_sel:[1,0,1]
	s_waitcnt lgkmcnt(1)
	v_pk_fma_f32 v[138:139], v[166:167], v[178:179], v[138:139] op_sel_hi:[0,1,1]
	s_waitcnt lgkmcnt(0)
	v_pk_fma_f32 v[138:139], v[188:189], v[176:177], v[138:139] op_sel_hi:[0,1,1]
	ds_read_b32 v182, v208 offset:8192
	ds_read_b32 v180, v208 offset:8188
	ds_read_b32 v186, v208 offset:8196
	ds_read_b32 v183, v208 offset:24576
	ds_read_b32 v181, v208 offset:24572
	ds_read_b32 v187, v208 offset:24580
	ds_read_b32 v184, v208 offset:10240
	ds_read_b32 v174, v208 offset:10236
	ds_read_b32 v168, v208 offset:10244
	ds_read_b32 v185, v208 offset:26624
	ds_read_b32 v175, v208 offset:26620
	ds_read_b32 v169, v208 offset:26628
	s_waitcnt lgkmcnt(8)
	v_pk_fma_f32 v[140:141], v[166:167], v[182:183], v[188:189] op_sel:[1,0,1]
	s_waitcnt lgkmcnt(7)
	v_pk_fma_f32 v[140:141], v[166:167], v[180:181], v[140:141] op_sel_hi:[0,1,1]
	s_waitcnt lgkmcnt(6)
	v_pk_fma_f32 v[140:141], v[188:189], v[186:187], v[140:141] op_sel_hi:[0,1,1]
	s_waitcnt lgkmcnt(2)
	v_pk_fma_f32 v[142:143], v[166:167], v[184:185], v[188:189] op_sel:[1,0,1]
	s_waitcnt lgkmcnt(1)
	v_pk_fma_f32 v[142:143], v[166:167], v[174:175], v[142:143] op_sel_hi:[0,1,1]
	s_waitcnt lgkmcnt(0)
	v_pk_fma_f32 v[142:143], v[188:189], v[168:169], v[142:143] op_sel_hi:[0,1,1]
	ds_read_b32 v178, v208 offset:12288
	ds_read_b32 v176, v208 offset:12284
	ds_read_b32 v182, v208 offset:12292
	ds_read_b32 v179, v208 offset:28672
	ds_read_b32 v177, v208 offset:28668
	ds_read_b32 v183, v208 offset:28676
	ds_read_b32 v180, v208 offset:14336
	ds_read_b32 v186, v208 offset:14332
	ds_read_b32 v184, v208 offset:14340
	ds_read_b32 v181, v208 offset:30720
	ds_read_b32 v187, v208 offset:30716
	ds_read_b32 v185, v208 offset:30724
	s_waitcnt lgkmcnt(8)
; #define LAS __attribute__((address_space(3)))
; __device__ __forceinline__ void fft_fwd2(LAS f32x2* B, const LAS f32x2* TW2, int tid) {
;     asm volatile("" : "+v"(tid));
;     const int b = tid >> 5, n2 = tid & 31, base = 512 * b + n2; f32x2 x[16];
; #pragma unroll
;     for (int r = 0; r < 16; ++r) x[r] = B[fpad(base + 32 * r)];
;     dft16<false>(x);
; __device__ __forceinline__ void hy_stage(LAS float* plane, const bf16_t* PHY, int cg, int jc, int tid) {
;     asm volatile("" : "+v"(tid));
;     const u32x4* src = (const u32x4*)(PHY + (size_t)cg * MT * 4);
; #pragma unroll
;     for (int k = 0; k < 8; ++k) { const int i = tid + 512 * k; const u32x4 v = src[i];
;         const unsigned w0 = (jc & 2) ? v.y : v.x, w1 = (jc & 2) ? v.w : v.z;
;         f32x2 o; o.x = (jc & 1) ? bf_hi(w0) : bf_lo(w0); o.y = (jc & 1) ? bf_hi(w1) : bf_lo(w1);
;         *(LAS f32x2*)(plane + 2 * i) = o; }
; }
	v_pk_fma_f32 v[144:145], v[166:167], v[178:179], v[188:189] op_sel:[1,0,1]
	s_waitcnt lgkmcnt(7)
	v_pk_fma_f32 v[144:145], v[166:167], v[176:177], v[144:145] op_sel_hi:[0,1,1]
	s_waitcnt lgkmcnt(6)
	v_pk_fma_f32 v[144:145], v[188:189], v[182:183], v[144:145] op_sel_hi:[0,1,1]
	s_waitcnt lgkmcnt(3)
	v_cndmask_b32_e64 v184, v184, 0, s[28:29]
	s_waitcnt lgkmcnt(0)
	v_cndmask_b32_e64 v185, v185, 0, s[28:29]
	v_pk_fma_f32 v[146:147], v[166:167], v[180:181], v[188:189] op_sel:[1,0,1]
	v_pk_fma_f32 v[146:147], v[166:167], v[186:187], v[146:147] op_sel_hi:[0,1,1]
	v_pk_fma_f32 v[146:147], v[188:189], v[184:185], v[146:147] op_sel_hi:[0,1,1]
	s_load_dword s17, s[60:61], 0x0
	s_load_dword s23, s[60:61], 0x3000
	s_load_dword s25, s[60:61], 0x6000
	s_load_dword s26, s[62:63], 0x0
	s_waitcnt vmcnt(7)
	v_perm_b32 v174, 0, v58, s15
	v_perm_b32 v175, 0, v60, s15
	ds_write_b64 v206, v[174:175] offset:32768
	s_waitcnt vmcnt(6)
	v_perm_b32 v168, 0, v62, s15
	v_perm_b32 v169, 0, v64, s15
	ds_write_b64 v206, v[168:169] offset:36864
	s_waitcnt vmcnt(5)
	v_perm_b32 v178, 0, v66, s15
	v_perm_b32 v179, 0, v68, s15
	ds_write_b64 v206, v[178:179] offset:40960
	s_waitcnt vmcnt(4)
	v_perm_b32 v176, 0, v70, s15
	v_perm_b32 v177, 0, v72, s15
	ds_write_b64 v206, v[176:177] offset:45056
	s_waitcnt vmcnt(3)
	v_perm_b32 v182, 0, v74, s15
	v_perm_b32 v183, 0, v76, s15
	ds_write_b64 v206, v[182:183] offset:49152
	s_waitcnt vmcnt(2)
	v_perm_b32 v180, 0, v78, s15
	v_perm_b32 v181, 0, v80, s15
	ds_write_b64 v206, v[180:181] offset:53248
	s_waitcnt vmcnt(1)
	v_perm_b32 v186, 0, v82, s15
	v_perm_b32 v187, 0, v84, s15
	ds_write_b64 v206, v[186:187] offset:57344
	s_waitcnt vmcnt(0)
	v_perm_b32 v184, 0, v86, s15
	v_perm_b32 v185, 0, v88, s15
	ds_write_b64 v206, v[184:185] offset:61440
	s_add_u32 s56, s38, s73
	s_addc_u32 s57, s39, 0
	s_add_u32 s56, s56, 0x1100000
	s_addc_u32 s57, s57, 0
	global_load_dwordx3 v[58:60], v216, s[56:57]
	global_load_dwordx3 v[62:64], v218, s[56:57]
	global_load_dwordx3 v[66:68], v220, s[56:57]
	global_load_dwordx3 v[70:72], v222, s[56:57]
	global_load_dwordx3 v[74:76], v240, s[56:57]
	global_load_dwordx3 v[78:80], v242, s[56:57]
	global_load_dwordx3 v[82:84], v244, s[56:57]
	global_load_dwordx3 v[86:88], v61, s[56:57]
	v_add_u32_e32 v65, 0x10800, v5
	ds_read_b64 v[100:101], v65
	ds_read_b64 v[102:103], v65 offset:1056
	ds_read_b64 v[104:105], v65 offset:2112
	ds_read_b64 v[106:107], v65 offset:3168
	ds_read_b64 v[108:109], v65 offset:264
	ds_read_b64 v[110:111], v65 offset:1320
	ds_read_b64 v[112:113], v65 offset:2376
	ds_read_b64 v[114:115], v65 offset:3432
	ds_read_b64 v[116:117], v65 offset:528
	ds_read_b64 v[118:119], v65 offset:1584
	ds_read_b64 v[120:121], v65 offset:2640
	ds_read_b64 v[122:123], v65 offset:3696
	s_waitcnt lgkmcnt(8)
	ds_read_b64 v[124:125], v65 offset:792
	ds_read_b64 v[126:127], v65 offset:1848
	ds_read_b64 v[128:129], v65 offset:2904
	ds_read_b64 v[130:131], v65 offset:3960
	v_pk_add_f32 v[166:167], v[100:101], v[104:105]
	v_pk_add_f32 v[188:189], v[100:101], v[104:105] neg_lo:[0,1] neg_hi:[0,1]
	v_pk_add_f32 v[174:175], v[102:103], v[106:107]
	v_pk_add_f32 v[168:169], v[102:103], v[106:107] neg_lo:[0,1] neg_hi:[0,1]
	v_pk_add_f32 v[100:101], v[166:167], v[174:175]
	v_pk_add_f32 v[104:105], v[166:167], v[174:175] neg_lo:[0,1] neg_hi:[0,1]
	v_pk_add_f32 v[102:103], v[188:189], v[168:169] op_sel:[0,1] op_sel_hi:[1,0] neg_hi:[0,1]
	v_pk_add_f32 v[106:107], v[188:189], v[168:169] op_sel:[0,1] op_sel_hi:[1,0] neg_lo:[0,1]
	s_waitcnt lgkmcnt(9)
	v_pk_add_f32 v[178:179], v[108:109], v[112:113]
	v_pk_add_f32 v[176:177], v[108:109], v[112:113] neg_lo:[0,1] neg_hi:[0,1]
	s_waitcnt lgkmcnt(8)
	v_pk_add_f32 v[182:183], v[110:111], v[114:115]
	v_pk_add_f32 v[180:181], v[110:111], v[114:115] neg_lo:[0,1] neg_hi:[0,1]
	v_pk_add_f32 v[108:109], v[178:179], v[182:183]
	v_pk_add_f32 v[112:113], v[178:179], v[182:183] neg_lo:[0,1] neg_hi:[0,1]
	v_pk_add_f32 v[110:111], v[176:177], v[180:181] op_sel:[0,1] op_sel_hi:[1,0] neg_hi:[0,1]
	v_pk_add_f32 v[114:115], v[176:177], v[180:181] op_sel:[0,1] op_sel_hi:[1,0] neg_lo:[0,1]
	s_waitcnt lgkmcnt(5)
	v_pk_add_f32 v[186:187], v[116:117], v[120:121]
	v_pk_add_f32 v[184:185], v[116:117], v[120:121] neg_lo:[0,1] neg_hi:[0,1]
	s_waitcnt lgkmcnt(4)
	v_pk_add_f32 v[166:167], v[118:119], v[122:123]
	v_pk_add_f32 v[188:189], v[118:119], v[122:123] neg_lo:[0,1] neg_hi:[0,1]
	v_pk_add_f32 v[116:117], v[186:187], v[166:167]
	v_pk_add_f32 v[120:121], v[186:187], v[166:167] neg_lo:[0,1] neg_hi:[0,1]
	v_pk_add_f32 v[118:119], v[184:185], v[188:189] op_sel:[0,1] op_sel_hi:[1,0] neg_hi:[0,1]
	v_pk_add_f32 v[122:123], v[184:185], v[188:189] op_sel:[0,1] op_sel_hi:[1,0] neg_lo:[0,1]
	s_waitcnt lgkmcnt(1)
	v_pk_add_f32 v[174:175], v[124:125], v[128:129]
	v_pk_add_f32 v[168:169], v[124:125], v[128:129] neg_lo:[0,1] neg_hi:[0,1]
	s_waitcnt lgkmcnt(0)
; #define LAS __attribute__((address_space(3)))
; __device__ __forceinline__ f32x2 cmul(f32x2 a, f32x2 b) { return (f32x2){a.x * b.x - a.y * b.y, a.x * b.y + a.y * b.x}; }
; __device__ __forceinline__ void fft_fwd2(LAS f32x2* B, const LAS f32x2* TW2, int tid) {
;     asm volatile("" : "+v"(tid));
;     const int b = tid >> 5, n2 = tid & 31, base = 512 * b + n2; f32x2 x[16];
; #pragma unroll
;     for (int r = 0; r < 16; ++r) x[r] = B[fpad(base + 32 * r)];
;     dft16<false>(x);
;     B[fpad(base)] = x[0];
; #pragma unroll
;     for (int k = 1; k < 16; ++k) B[fpad(base + 32 * k)] = cmul(x[k], TW2[k * 32 + n2]);
; }
	v_pk_add_f32 v[178:179], v[126:127], v[130:131]
	v_pk_add_f32 v[176:177], v[126:127], v[130:131] neg_lo:[0,1] neg_hi:[0,1]
	v_pk_add_f32 v[124:125], v[174:175], v[178:179]
	v_pk_add_f32 v[128:129], v[174:175], v[178:179] neg_lo:[0,1] neg_hi:[0,1]
	v_pk_add_f32 v[126:127], v[168:169], v[176:177] op_sel:[0,1] op_sel_hi:[1,0] neg_hi:[0,1]
	v_pk_add_f32 v[130:131], v[168:169], v[176:177] op_sel:[0,1] op_sel_hi:[1,0] neg_lo:[0,1]
	v_pk_mul_f32 v[182:183], v[110:111], s[68:69] op_sel:[1,1] op_sel_hi:[0,1]
	v_pk_fma_f32 v[110:111], v[110:111], s[68:69], v[182:183] op_sel_hi:[1,0,1] neg_lo:[0,0,1]
	v_pk_mul_f32 v[180:181], v[118:119], s[84:85] op_sel:[1,1] op_sel_hi:[0,1]
	v_pk_fma_f32 v[118:119], v[118:119], s[84:85], v[180:181] op_sel_hi:[1,0,1] neg_lo:[0,0,1]
	v_pk_mul_f32 v[186:187], v[126:127], s[88:89] op_sel:[1,1] op_sel_hi:[0,1]
	v_pk_fma_f32 v[126:127], v[126:127], s[88:89], v[186:187] op_sel_hi:[1,0,1] neg_lo:[0,0,1]
	v_pk_mul_f32 v[184:185], v[112:113], s[84:85] op_sel:[1,1] op_sel_hi:[0,1]
	v_pk_fma_f32 v[112:113], v[112:113], s[84:85], v[184:185] op_sel_hi:[1,0,1] neg_lo:[0,0,1]
	v_pk_mul_f32 v[166:167], v[128:129], s[90:91] op_sel:[1,1] op_sel_hi:[0,1]
	v_pk_fma_f32 v[128:129], v[128:129], s[90:91], v[166:167] op_sel_hi:[1,0,1] neg_lo:[0,0,1]
	v_pk_mul_f32 v[188:189], v[114:115], s[88:89] op_sel:[1,1] op_sel_hi:[0,1]
	v_pk_fma_f32 v[114:115], v[114:115], s[88:89], v[188:189] op_sel_hi:[1,0,1] neg_lo:[0,0,1]
	v_pk_mul_f32 v[174:175], v[122:123], s[90:91] op_sel:[1,1] op_sel_hi:[0,1]
	v_pk_fma_f32 v[122:123], v[122:123], s[90:91], v[174:175] op_sel_hi:[1,0,1] neg_lo:[0,0,1]
	v_pk_mul_f32 v[168:169], v[130:131], s[98:99] op_sel:[1,1] op_sel_hi:[0,1]
	v_pk_fma_f32 v[130:131], v[130:131], s[98:99], v[168:169] op_sel_hi:[1,0,1] neg_lo:[0,0,1]
	v_pk_add_f32 v[178:179], v[100:101], v[116:117]
	v_pk_add_f32 v[176:177], v[100:101], v[116:117] neg_lo:[0,1] neg_hi:[0,1]
	v_pk_add_f32 v[182:183], v[108:109], v[124:125]
	v_pk_add_f32 v[180:181], v[108:109], v[124:125] neg_lo:[0,1] neg_hi:[0,1]
	v_pk_add_f32 v[100:101], v[178:179], v[182:183]
	v_pk_add_f32 v[116:117], v[178:179], v[182:183] neg_lo:[0,1] neg_hi:[0,1]
	v_pk_add_f32 v[108:109], v[176:177], v[180:181] op_sel:[0,1] op_sel_hi:[1,0] neg_hi:[0,1]
	v_pk_add_f32 v[124:125], v[176:177], v[180:181] op_sel:[0,1] op_sel_hi:[1,0] neg_lo:[0,1]
	v_pk_add_f32 v[186:187], v[102:103], v[118:119]
	v_pk_add_f32 v[184:185], v[102:103], v[118:119] neg_lo:[0,1] neg_hi:[0,1]
	v_pk_add_f32 v[166:167], v[110:111], v[126:127]
	v_pk_add_f32 v[188:189], v[110:111], v[126:127] neg_lo:[0,1] neg_hi:[0,1]
	v_pk_add_f32 v[102:103], v[186:187], v[166:167]
	v_pk_add_f32 v[118:119], v[186:187], v[166:167] neg_lo:[0,1] neg_hi:[0,1]
	v_pk_add_f32 v[110:111], v[184:185], v[188:189] op_sel:[0,1] op_sel_hi:[1,0] neg_hi:[0,1]
	v_pk_add_f32 v[126:127], v[184:185], v[188:189] op_sel:[0,1] op_sel_hi:[1,0] neg_lo:[0,1]
	v_pk_add_f32 v[174:175], v[104:105], v[120:121] op_sel:[0,1] op_sel_hi:[1,0] neg_hi:[0,1]
	v_pk_add_f32 v[168:169], v[104:105], v[120:121] op_sel:[0,1] op_sel_hi:[1,0] neg_lo:[0,1]
	v_pk_add_f32 v[178:179], v[112:113], v[128:129]
	v_pk_add_f32 v[176:177], v[112:113], v[128:129] neg_lo:[0,1] neg_hi:[0,1]
	v_pk_add_f32 v[104:105], v[174:175], v[178:179]
	v_pk_add_f32 v[120:121], v[174:175], v[178:179] neg_lo:[0,1] neg_hi:[0,1]
	v_pk_add_f32 v[112:113], v[168:169], v[176:177] op_sel:[0,1] op_sel_hi:[1,0] neg_hi:[0,1]
	v_pk_add_f32 v[128:129], v[168:169], v[176:177] op_sel:[0,1] op_sel_hi:[1,0] neg_lo:[0,1]
	v_pk_add_f32 v[182:183], v[106:107], v[122:123]
	v_pk_add_f32 v[180:181], v[106:107], v[122:123] neg_lo:[0,1] neg_hi:[0,1]
	v_pk_add_f32 v[186:187], v[114:115], v[130:131]
	v_pk_add_f32 v[184:185], v[114:115], v[130:131] neg_lo:[0,1] neg_hi:[0,1]
	v_pk_add_f32 v[106:107], v[182:183], v[186:187]
	v_pk_add_f32 v[122:123], v[182:183], v[186:187] neg_lo:[0,1] neg_hi:[0,1]
	v_pk_add_f32 v[114:115], v[180:181], v[184:185] op_sel:[0,1] op_sel_hi:[1,0] neg_hi:[0,1]
	v_pk_add_f32 v[130:131], v[180:181], v[184:185] op_sel:[0,1] op_sel_hi:[1,0] neg_lo:[0,1]
	ds_write_b64 v65, v[100:101]
	ds_read_b64 v[166:167], v56 offset:256
	ds_read_b64 v[188:189], v56 offset:512
	ds_read_b64 v[174:175], v56 offset:768
	ds_read_b64 v[168:169], v56 offset:1024
	s_waitcnt lgkmcnt(3)
	v_pk_mul_f32 v[178:179], v[102:103], v[166:167] op_sel:[1,1] op_sel_hi:[0,1]
	v_pk_fma_f32 v[102:103], v[102:103], v[166:167], v[178:179] op_sel_hi:[1,0,1] neg_lo:[0,0,1]
	ds_write_b64 v65, v[102:103] offset:264
	s_waitcnt lgkmcnt(3)
	v_pk_mul_f32 v[176:177], v[104:105], v[188:189] op_sel:[1,1] op_sel_hi:[0,1]
	v_pk_fma_f32 v[104:105], v[104:105], v[188:189], v[176:177] op_sel_hi:[1,0,1] neg_lo:[0,0,1]
	ds_write_b64 v65, v[104:105] offset:528
	s_waitcnt lgkmcnt(3)
	v_pk_mul_f32 v[182:183], v[106:107], v[174:175] op_sel:[1,1] op_sel_hi:[0,1]
	v_pk_fma_f32 v[106:107], v[106:107], v[174:175], v[182:183] op_sel_hi:[1,0,1] neg_lo:[0,0,1]
	ds_write_b64 v65, v[106:107] offset:792
	s_waitcnt lgkmcnt(3)
	v_pk_mul_f32 v[180:181], v[108:109], v[168:169] op_sel:[1,1] op_sel_hi:[0,1]
	v_pk_fma_f32 v[108:109], v[108:109], v[168:169], v[180:181] op_sel_hi:[1,0,1] neg_lo:[0,0,1]
	ds_write_b64 v65, v[108:109] offset:1056
	ds_read_b64 v[186:187], v56 offset:1280
	ds_read_b64 v[184:185], v56 offset:1536
	ds_read_b64 v[178:179], v56 offset:1792
	ds_read_b64 v[176:177], v56 offset:2048
	s_waitcnt lgkmcnt(3)
	v_pk_mul_f32 v[182:183], v[110:111], v[186:187] op_sel:[1,1] op_sel_hi:[0,1]
	v_pk_fma_f32 v[110:111], v[110:111], v[186:187], v[182:183] op_sel_hi:[1,0,1] neg_lo:[0,0,1]
	ds_write_b64 v65, v[110:111] offset:1320
	s_waitcnt lgkmcnt(3)
; #define LAS __attribute__((address_space(3)))
; #define WG_SYNC() do { asm volatile("s_waitcnt lgkmcnt(0)" ::: "memory"); __builtin_amdgcn_s_barrier(); asm volatile("" ::: "memory"); } while (0)
; __device__ __forceinline__ void hy_sconv(const LAS float* plane, float w0, float w1, float w2, float cb, int n2, float (&u)[8][2]) {
;     asm volatile("" : "+v"(n2));
; #pragma unroll
;     for (int r = 0; r < 8; ++r)
; #pragma unroll
;         for (int b = 0; b < 2; ++b) { const int t = n2 + 512 * r, row = b * SEQ + t;
;             float a = cb + w1 * plane[row];
;             if (t > 0) a += w0 * plane[row - 1];
;             if (t < SEQ - 1) a += w2 * plane[row + 1];
;             u[r][b] = a; }
; }
; __device__ __forceinline__ void hyena_fft(LAS unsigned char* lds, int layer, int G, const int wave_s) {
;     ...
;             WG_SYNC();
;             float uz[8][2], ux[8][2];
;             hy_sconv(pl0, cw[2 * HY + c], cw[3 * HY + 2 * HY + c], cw[6 * HY + 2 * HY + c], cb[2 * HY + c], n2, uz);
;             __builtin_amdgcn_sched_barrier(0); hy_sconv(pl1, cw[c], cw[3 * HY + c], cw[6 * HY + c], cb[c], n2, ux); __builtin_amdgcn_sched_barrier(0);
	v_pk_mul_f32 v[180:181], v[112:113], v[184:185] op_sel:[1,1] op_sel_hi:[0,1]
	v_pk_fma_f32 v[112:113], v[112:113], v[184:185], v[180:181] op_sel_hi:[1,0,1] neg_lo:[0,0,1]
	ds_write_b64 v65, v[112:113] offset:1584
	s_waitcnt lgkmcnt(3)
	v_pk_mul_f32 v[166:167], v[114:115], v[178:179] op_sel:[1,1] op_sel_hi:[0,1]
	v_pk_fma_f32 v[114:115], v[114:115], v[178:179], v[166:167] op_sel_hi:[1,0,1] neg_lo:[0,0,1]
	ds_write_b64 v65, v[114:115] offset:1848
	s_waitcnt lgkmcnt(3)
	v_pk_mul_f32 v[188:189], v[116:117], v[176:177] op_sel:[1,1] op_sel_hi:[0,1]
	v_pk_fma_f32 v[116:117], v[116:117], v[176:177], v[188:189] op_sel_hi:[1,0,1] neg_lo:[0,0,1]
	ds_write_b64 v65, v[116:117] offset:2112
	ds_read_b64 v[174:175], v56 offset:2304
	ds_read_b64 v[168:169], v56 offset:2560
	ds_read_b64 v[182:183], v56 offset:2816
	ds_read_b64 v[180:181], v56 offset:3072
	s_waitcnt lgkmcnt(3)
	v_pk_mul_f32 v[166:167], v[118:119], v[174:175] op_sel:[1,1] op_sel_hi:[0,1]
	v_pk_fma_f32 v[118:119], v[118:119], v[174:175], v[166:167] op_sel_hi:[1,0,1] neg_lo:[0,0,1]
	ds_write_b64 v65, v[118:119] offset:2376
	s_waitcnt lgkmcnt(3)
	v_pk_mul_f32 v[188:189], v[120:121], v[168:169] op_sel:[1,1] op_sel_hi:[0,1]
	v_pk_fma_f32 v[120:121], v[120:121], v[168:169], v[188:189] op_sel_hi:[1,0,1] neg_lo:[0,0,1]
	ds_write_b64 v65, v[120:121] offset:2640
	s_waitcnt lgkmcnt(3)
	v_pk_mul_f32 v[186:187], v[122:123], v[182:183] op_sel:[1,1] op_sel_hi:[0,1]
	v_pk_fma_f32 v[122:123], v[122:123], v[182:183], v[186:187] op_sel_hi:[1,0,1] neg_lo:[0,0,1]
	ds_write_b64 v65, v[122:123] offset:2904
	s_waitcnt lgkmcnt(3)
	v_pk_mul_f32 v[184:185], v[124:125], v[180:181] op_sel:[1,1] op_sel_hi:[0,1]
	v_pk_fma_f32 v[124:125], v[124:125], v[180:181], v[184:185] op_sel_hi:[1,0,1] neg_lo:[0,0,1]
	ds_write_b64 v65, v[124:125] offset:3168
	ds_read_b64 v[178:179], v56 offset:3328
	ds_read_b64 v[176:177], v56 offset:3584
	ds_read_b64 v[166:167], v56 offset:3840
	s_waitcnt lgkmcnt(2)
	v_pk_mul_f32 v[188:189], v[126:127], v[178:179] op_sel:[1,1] op_sel_hi:[0,1]
	v_pk_fma_f32 v[126:127], v[126:127], v[178:179], v[188:189] op_sel_hi:[1,0,1] neg_lo:[0,0,1]
	ds_write_b64 v65, v[126:127] offset:3432
	s_waitcnt lgkmcnt(2)
	v_pk_mul_f32 v[186:187], v[128:129], v[176:177] op_sel:[1,1] op_sel_hi:[0,1]
	v_pk_fma_f32 v[128:129], v[128:129], v[176:177], v[186:187] op_sel_hi:[1,0,1] neg_lo:[0,0,1]
	ds_write_b64 v65, v[128:129] offset:3696
	s_waitcnt lgkmcnt(2)
	v_pk_mul_f32 v[184:185], v[130:131], v[166:167] op_sel:[1,1] op_sel_hi:[0,1]
	v_pk_fma_f32 v[130:131], v[130:131], v[166:167], v[184:185] op_sel_hi:[1,0,1] neg_lo:[0,0,1]
	ds_write_b64 v65, v[130:131] offset:3960
	s_waitcnt lgkmcnt(0)
	s_barrier
	v_mov_b32_e32 v174, s17
	v_mov_b32_e32 v175, s23
	v_mov_b32_e32 v168, s25
	v_mov_b32_e32 v169, s26
	ds_read_b32 v182, v208 offset:32768
	ds_read_b32 v180, v210 offset:32768
	ds_read_b32 v188, v208 offset:32772
	ds_read_b32 v183, v208 offset:49152
	ds_read_b32 v181, v210 offset:49152
	ds_read_b32 v189, v208 offset:49156
	ds_read_b32 v186, v208 offset:34816
	ds_read_b32 v184, v208 offset:34812
	ds_read_b32 v178, v208 offset:34820
	ds_read_b32 v187, v208 offset:51200
	ds_read_b32 v185, v208 offset:51196
	ds_read_b32 v179, v208 offset:51204
	s_waitcnt lgkmcnt(10)
	v_cndmask_b32_e64 v180, v180, 0, s[10:11]
	s_waitcnt lgkmcnt(7)
	v_cndmask_b32_e64 v181, v181, 0, s[10:11]
	v_pk_fma_f32 v[148:149], v[174:175], v[182:183], v[168:169] op_sel:[1,0,1]
	v_pk_fma_f32 v[148:149], v[174:175], v[180:181], v[148:149] op_sel_hi:[0,1,1]
	s_waitcnt lgkmcnt(6)
	v_pk_fma_f32 v[148:149], v[168:169], v[188:189], v[148:149] op_sel_hi:[0,1,1]
	s_waitcnt lgkmcnt(2)
	v_pk_fma_f32 v[150:151], v[174:175], v[186:187], v[168:169] op_sel:[1,0,1]
	s_waitcnt lgkmcnt(1)
	v_pk_fma_f32 v[150:151], v[174:175], v[184:185], v[150:151] op_sel_hi:[0,1,1]
	s_waitcnt lgkmcnt(0)
	v_pk_fma_f32 v[150:151], v[168:169], v[178:179], v[150:151] op_sel_hi:[0,1,1]
	ds_read_b32 v176, v208 offset:36864
	ds_read_b32 v166, v208 offset:36860
	ds_read_b32 v182, v208 offset:36868
	ds_read_b32 v177, v208 offset:53248
	ds_read_b32 v167, v208 offset:53244
	ds_read_b32 v183, v208 offset:53252
	ds_read_b32 v180, v208 offset:38912
	ds_read_b32 v188, v208 offset:38908
	ds_read_b32 v186, v208 offset:38916
	ds_read_b32 v181, v208 offset:55296
	ds_read_b32 v189, v208 offset:55292
	ds_read_b32 v187, v208 offset:55300
	s_waitcnt lgkmcnt(8)
	v_pk_fma_f32 v[152:153], v[174:175], v[176:177], v[168:169] op_sel:[1,0,1]
	s_waitcnt lgkmcnt(7)
	v_pk_fma_f32 v[152:153], v[174:175], v[166:167], v[152:153] op_sel_hi:[0,1,1]
	s_waitcnt lgkmcnt(6)
	v_pk_fma_f32 v[152:153], v[168:169], v[182:183], v[152:153] op_sel_hi:[0,1,1]
	s_waitcnt lgkmcnt(2)
	v_pk_fma_f32 v[154:155], v[174:175], v[180:181], v[168:169] op_sel:[1,0,1]
	s_waitcnt lgkmcnt(1)
	v_pk_fma_f32 v[154:155], v[174:175], v[188:189], v[154:155] op_sel_hi:[0,1,1]
	s_waitcnt lgkmcnt(0)
	v_pk_fma_f32 v[154:155], v[168:169], v[186:187], v[154:155] op_sel_hi:[0,1,1]
	ds_read_b32 v184, v208 offset:40960
	ds_read_b32 v178, v208 offset:40956
	ds_read_b32 v176, v208 offset:40964
	ds_read_b32 v185, v208 offset:57344
	ds_read_b32 v179, v208 offset:57340
	ds_read_b32 v177, v208 offset:57348
	ds_read_b32 v166, v208 offset:43008
	ds_read_b32 v182, v208 offset:43004
	ds_read_b32 v180, v208 offset:43012
	ds_read_b32 v167, v208 offset:59392
	ds_read_b32 v183, v208 offset:59388
	ds_read_b32 v181, v208 offset:59396
	s_waitcnt lgkmcnt(8)
	v_pk_fma_f32 v[158:159], v[174:175], v[184:185], v[168:169] op_sel:[1,0,1]
	s_waitcnt lgkmcnt(7)
	v_pk_fma_f32 v[158:159], v[174:175], v[178:179], v[158:159] op_sel_hi:[0,1,1]
	s_waitcnt lgkmcnt(6)
; #define LAS __attribute__((address_space(3)))
; __device__ __forceinline__ f32x2 cmul(f32x2 a, f32x2 b) { return (f32x2){a.x * b.x - a.y * b.y, a.x * b.y + a.y * b.x}; }
; template <int MODE> __device__ __forceinline__ void fft_pair32(LAS f32x2* B, const LAS f32x2* F, int wave, int lane) {
;     ...
;     const int hi = lane >> 5, blk = 32 * wave + (lane & 31); const float sg = hi ? -1.f : 1.f;
;     LAS f32x2* p = B + 33 * blk; f32x2 v[16];
; #pragma unroll
;     for (int j = 0; j < 16; ++j) { const f32x2 d = p[j] + p[j + 16] * sg;
;         const f32x2 w = {hi ? CS[j] : 1.f, hi ? -SN[j] : 0.f}; v[j] = j == 0 ? d : cmul(d, w); }
;     dft16<false>(v);
; __device__ __forceinline__ void hy_sconv(const LAS float* plane, float w0, float w1, float w2, float cb, int n2, float (&u)[8][2]) {
;     asm volatile("" : "+v"(n2));
; #pragma unroll
;     for (int r = 0; r < 8; ++r)
; #pragma unroll
;         for (int b = 0; b < 2; ++b) { const int t = n2 + 512 * r, row = b * SEQ + t;
;             float a = cb + w1 * plane[row];
;             if (t > 0) a += w0 * plane[row - 1];
;             if (t < SEQ - 1) a += w2 * plane[row + 1];
;             u[r][b] = a; }
; }
	v_pk_fma_f32 v[158:159], v[168:169], v[176:177], v[158:159] op_sel_hi:[0,1,1]
	s_waitcnt lgkmcnt(2)
	v_pk_fma_f32 v[160:161], v[174:175], v[166:167], v[168:169] op_sel:[1,0,1]
	s_waitcnt lgkmcnt(1)
	v_pk_fma_f32 v[160:161], v[174:175], v[182:183], v[160:161] op_sel_hi:[0,1,1]
	s_waitcnt lgkmcnt(0)
	v_pk_fma_f32 v[160:161], v[168:169], v[180:181], v[160:161] op_sel_hi:[0,1,1]
	ds_read_b32 v188, v208 offset:45056
	ds_read_b32 v186, v208 offset:45052
	ds_read_b32 v184, v208 offset:45060
	ds_read_b32 v189, v208 offset:61440
	ds_read_b32 v187, v208 offset:61436
	ds_read_b32 v185, v208 offset:61444
	ds_read_b32 v178, v208 offset:47104
	ds_read_b32 v176, v208 offset:47100
	ds_read_b32 v166, v208 offset:47108
	ds_read_b32 v179, v208 offset:63488
	ds_read_b32 v177, v208 offset:63484
	ds_read_b32 v167, v208 offset:63492
	s_waitcnt lgkmcnt(8)
	v_pk_fma_f32 v[162:163], v[174:175], v[188:189], v[168:169] op_sel:[1,0,1]
	s_waitcnt lgkmcnt(7)
	v_pk_fma_f32 v[162:163], v[174:175], v[186:187], v[162:163] op_sel_hi:[0,1,1]
	s_waitcnt lgkmcnt(6)
	v_pk_fma_f32 v[162:163], v[168:169], v[184:185], v[162:163] op_sel_hi:[0,1,1]
	s_waitcnt lgkmcnt(3)
	v_cndmask_b32_e64 v166, v166, 0, s[28:29]
	s_waitcnt lgkmcnt(0)
	v_cndmask_b32_e64 v167, v167, 0, s[28:29]
	v_pk_fma_f32 v[164:165], v[174:175], v[178:179], v[168:169] op_sel:[1,0,1]
	v_pk_fma_f32 v[164:165], v[174:175], v[176:177], v[164:165] op_sel_hi:[0,1,1]
	v_pk_fma_f32 v[164:165], v[168:169], v[166:167], v[164:165] op_sel_hi:[0,1,1]
	s_load_dword s17, s[60:61], 0x1000
	s_load_dword s23, s[60:61], 0x4000
	s_load_dword s25, s[60:61], 0x7000
	s_load_dword s26, s[62:63], 0x1000
	v_add_u32_e32 v65, 0x10800, v156
	v_add_u32_e32 v69, 0x10800, v196
	ds_read_b64 v[100:101], v65
	ds_read_b64 v[182:183], v65 offset:128
	ds_read_b64 v[102:103], v65 offset:8
	ds_read_b64 v[180:181], v65 offset:136
	ds_read_b64 v[104:105], v65 offset:16
	ds_read_b64 v[188:189], v65 offset:144
	ds_read_b64 v[106:107], v65 offset:24
	ds_read_b64 v[186:187], v65 offset:152
	s_waitcnt lgkmcnt(0)
	v_pk_fma_f32 v[100:101], v[182:183], v[190:191], v[100:101] op_sel_hi:[1,0,1]
	v_pk_fma_f32 v[102:103], v[180:181], v[190:191], v[102:103] op_sel_hi:[1,0,1]
	v_pk_mul_f32 v[184:185], v[102:103], v[36:37] op_sel:[1,1] op_sel_hi:[0,1]
	v_pk_fma_f32 v[102:103], v[102:103], v[36:37], v[184:185] op_sel_hi:[1,0,1] neg_lo:[0,0,1]
	v_pk_fma_f32 v[104:105], v[188:189], v[190:191], v[104:105] op_sel_hi:[1,0,1]
	v_pk_mul_f32 v[178:179], v[104:105], v[38:39] op_sel:[1,1] op_sel_hi:[0,1]
	v_pk_fma_f32 v[104:105], v[104:105], v[38:39], v[178:179] op_sel_hi:[1,0,1] neg_lo:[0,0,1]
	v_pk_fma_f32 v[106:107], v[186:187], v[190:191], v[106:107] op_sel_hi:[1,0,1]
	v_pk_mul_f32 v[176:177], v[106:107], v[40:41] op_sel:[1,1] op_sel_hi:[0,1]
	v_pk_fma_f32 v[106:107], v[106:107], v[40:41], v[176:177] op_sel_hi:[1,0,1] neg_lo:[0,0,1]
	ds_read_b64 v[108:109], v65 offset:32
	ds_read_b64 v[166:167], v65 offset:160
	ds_read_b64 v[110:111], v65 offset:40
	ds_read_b64 v[174:175], v65 offset:168
	ds_read_b64 v[112:113], v65 offset:48
	ds_read_b64 v[168:169], v65 offset:176
	ds_read_b64 v[114:115], v65 offset:56
	ds_read_b64 v[184:185], v65 offset:184
	s_waitcnt lgkmcnt(6)
	v_pk_fma_f32 v[108:109], v[166:167], v[190:191], v[108:109] op_sel_hi:[1,0,1]
	v_pk_mul_f32 v[178:179], v[108:109], v[42:43] op_sel:[1,1] op_sel_hi:[0,1]
	v_pk_fma_f32 v[108:109], v[108:109], v[42:43], v[178:179] op_sel_hi:[1,0,1] neg_lo:[0,0,1]
	s_waitcnt lgkmcnt(4)
	v_pk_fma_f32 v[110:111], v[174:175], v[190:191], v[110:111] op_sel_hi:[1,0,1]
	v_pk_mul_f32 v[176:177], v[110:111], v[44:45] op_sel:[1,1] op_sel_hi:[0,1]
	v_pk_fma_f32 v[110:111], v[110:111], v[44:45], v[176:177] op_sel_hi:[1,0,1] neg_lo:[0,0,1]
	s_waitcnt lgkmcnt(2)
	v_pk_fma_f32 v[112:113], v[168:169], v[190:191], v[112:113] op_sel_hi:[1,0,1]
	v_pk_mul_f32 v[182:183], v[112:113], v[46:47] op_sel:[1,1] op_sel_hi:[0,1]
	v_pk_fma_f32 v[112:113], v[112:113], v[46:47], v[182:183] op_sel_hi:[1,0,1] neg_lo:[0,0,1]
	s_waitcnt lgkmcnt(0)
	v_pk_fma_f32 v[114:115], v[184:185], v[190:191], v[114:115] op_sel_hi:[1,0,1]
	v_pk_mul_f32 v[180:181], v[114:115], v[48:49] op_sel:[1,1] op_sel_hi:[0,1]
	v_pk_fma_f32 v[114:115], v[114:115], v[48:49], v[180:181] op_sel_hi:[1,0,1] neg_lo:[0,0,1]
	ds_read_b64 v[116:117], v65 offset:64
	ds_read_b64 v[188:189], v65 offset:192
	ds_read_b64 v[118:119], v65 offset:72
	ds_read_b64 v[186:187], v65 offset:200
	ds_read_b64 v[120:121], v65 offset:80
	ds_read_b64 v[178:179], v65 offset:208
	ds_read_b64 v[122:123], v65 offset:88
	ds_read_b64 v[176:177], v65 offset:216
	s_waitcnt lgkmcnt(6)
	v_pk_fma_f32 v[116:117], v[188:189], v[190:191], v[116:117] op_sel_hi:[1,0,1]
	v_pk_mul_f32 v[182:183], v[116:117], v[50:51] op_sel:[1,1] op_sel_hi:[0,1]
	v_pk_fma_f32 v[116:117], v[116:117], v[50:51], v[182:183] op_sel_hi:[1,0,1] neg_lo:[0,0,1]
	s_waitcnt lgkmcnt(4)
	v_pk_fma_f32 v[118:119], v[186:187], v[190:191], v[118:119] op_sel_hi:[1,0,1]
	v_pk_mul_f32 v[180:181], v[118:119], v[52:53] op_sel:[1,1] op_sel_hi:[0,1]
	v_pk_fma_f32 v[118:119], v[118:119], v[52:53], v[180:181] op_sel_hi:[1,0,1] neg_lo:[0,0,1]
	s_waitcnt lgkmcnt(2)
	v_pk_fma_f32 v[120:121], v[178:179], v[190:191], v[120:121] op_sel_hi:[1,0,1]
	v_pk_mul_f32 v[166:167], v[120:121], v[54:55] op_sel:[1,1] op_sel_hi:[0,1]
	v_pk_fma_f32 v[120:121], v[120:121], v[54:55], v[166:167] op_sel_hi:[1,0,1] neg_lo:[0,0,1]
	s_waitcnt lgkmcnt(0)
; #define LAS __attribute__((address_space(3)))
; __device__ __forceinline__ f32x2 cmul(f32x2 a, f32x2 b) { return (f32x2){a.x * b.x - a.y * b.y, a.x * b.y + a.y * b.x}; }
; template <bool INV> __device__ __forceinline__ f32x2 cmul_tw(f32x2 a, f32x2 w) { return INV ? cmulc(a, w) : cmul(a, w); }
; template <bool INV> __device__ __forceinline__ void dft16(f32x2 (&x)[16]) {
;     constexpr float C1 = 0.92387953251128674f, S1 = 0.38268343236508977f, C2 = 0.70710678118654752f;
; #pragma unroll
;     for (int b = 0; b < 4; ++b) dft4<INV>(x[b], x[4 + b], x[8 + b], x[12 + b]);
;     const f32x2 w1 = {C1, -S1}, w2 = {C2, -C2}, w3 = {S1, -C1}, w4 = {0.f, -1.f}, w6 = {-C2, -C2}, w9 = {-C1, S1};
;     x[4 * 1 + 1] = cmul_tw<INV>(x[5], w1); x[4 * 1 + 2] = cmul_tw<INV>(x[6], w2); x[4 * 1 + 3] = cmul_tw<INV>(x[7], w3);
;     x[4 * 2 + 1] = cmul_tw<INV>(x[9], w2); x[4 * 2 + 2] = cmul_tw<INV>(x[10], w4); x[4 * 2 + 3] = cmul_tw<INV>(x[11], w6);
;     x[4 * 3 + 1] = cmul_tw<INV>(x[13], w3); x[4 * 3 + 2] = cmul_tw<INV>(x[14], w6); x[4 * 3 + 3] = cmul_tw<INV>(x[15], w9);
; #pragma unroll
;     for (int c = 0; c < 4; ++c) dft4<INV>(x[4 * c], x[4 * c + 1], x[4 * c + 2], x[4 * c + 3]);
;     f32x2 y[16];
; #pragma unroll
;     for (int k = 0; k < 16; ++k) y[k] = x[4 * (k & 3) + (k >> 2)];
; #pragma unroll
;     for (int k = 0; k < 16; ++k) x[k] = y[k];
; template <int MODE> __device__ __forceinline__ void fft_pair32(LAS f32x2* B, const LAS f32x2* F, int wave, int lane) {
;     ...
;     const int hi = lane >> 5, blk = 32 * wave + (lane & 31); const float sg = hi ? -1.f : 1.f;
;     LAS f32x2* p = B + 33 * blk; f32x2 v[16];
; #pragma unroll
;     for (int j = 0; j < 16; ++j) { const f32x2 d = p[j] + p[j + 16] * sg;
;         const f32x2 w = {hi ? CS[j] : 1.f, hi ? -SN[j] : 0.f}; v[j] = j == 0 ? d : cmul(d, w); }
;     dft16<false>(v);
	v_pk_fma_f32 v[122:123], v[176:177], v[190:191], v[122:123] op_sel_hi:[1,0,1]
	v_pk_mul_f32 v[174:175], v[122:123], v[90:91] op_sel:[1,1] op_sel_hi:[0,1]
	v_pk_fma_f32 v[122:123], v[122:123], v[90:91], v[174:175] op_sel_hi:[1,0,1] neg_lo:[0,0,1]
	ds_read_b64 v[124:125], v65 offset:96
	ds_read_b64 v[168:169], v65 offset:224
	ds_read_b64 v[126:127], v65 offset:104
	ds_read_b64 v[184:185], v65 offset:232
	ds_read_b64 v[128:129], v65 offset:112
	ds_read_b64 v[182:183], v65 offset:240
	ds_read_b64 v[130:131], v65 offset:120
	ds_read_b64 v[180:181], v65 offset:248
	s_waitcnt lgkmcnt(6)
	v_pk_fma_f32 v[124:125], v[168:169], v[190:191], v[124:125] op_sel_hi:[1,0,1]
	v_pk_mul_f32 v[166:167], v[124:125], v[92:93] op_sel:[1,1] op_sel_hi:[0,1]
	v_pk_fma_f32 v[124:125], v[124:125], v[92:93], v[166:167] op_sel_hi:[1,0,1] neg_lo:[0,0,1]
	s_waitcnt lgkmcnt(4)
	v_pk_fma_f32 v[126:127], v[184:185], v[190:191], v[126:127] op_sel_hi:[1,0,1]
	v_pk_mul_f32 v[174:175], v[126:127], v[94:95] op_sel:[1,1] op_sel_hi:[0,1]
	v_pk_fma_f32 v[126:127], v[126:127], v[94:95], v[174:175] op_sel_hi:[1,0,1] neg_lo:[0,0,1]
	s_waitcnt lgkmcnt(2)
	v_pk_fma_f32 v[128:129], v[182:183], v[190:191], v[128:129] op_sel_hi:[1,0,1]
	v_pk_mul_f32 v[188:189], v[128:129], v[96:97] op_sel:[1,1] op_sel_hi:[0,1]
	v_pk_fma_f32 v[128:129], v[128:129], v[96:97], v[188:189] op_sel_hi:[1,0,1] neg_lo:[0,0,1]
	s_waitcnt lgkmcnt(0)
	v_pk_fma_f32 v[130:131], v[180:181], v[190:191], v[130:131] op_sel_hi:[1,0,1]
	v_pk_mul_f32 v[186:187], v[130:131], v[98:99] op_sel:[1,1] op_sel_hi:[0,1]
	v_pk_fma_f32 v[130:131], v[130:131], v[98:99], v[186:187] op_sel_hi:[1,0,1] neg_lo:[0,0,1]
	v_pk_add_f32 v[178:179], v[100:101], v[116:117]
	v_pk_add_f32 v[176:177], v[100:101], v[116:117] neg_lo:[0,1] neg_hi:[0,1]
	v_pk_add_f32 v[166:167], v[108:109], v[124:125]
	v_pk_add_f32 v[174:175], v[108:109], v[124:125] neg_lo:[0,1] neg_hi:[0,1]
	v_pk_add_f32 v[100:101], v[178:179], v[166:167]
	v_pk_add_f32 v[116:117], v[178:179], v[166:167] neg_lo:[0,1] neg_hi:[0,1]
	v_pk_add_f32 v[108:109], v[176:177], v[174:175] op_sel:[0,1] op_sel_hi:[1,0] neg_hi:[0,1]
	v_pk_add_f32 v[124:125], v[176:177], v[174:175] op_sel:[0,1] op_sel_hi:[1,0] neg_lo:[0,1]
	v_pk_add_f32 v[188:189], v[102:103], v[118:119]
	v_pk_add_f32 v[186:187], v[102:103], v[118:119] neg_lo:[0,1] neg_hi:[0,1]
	v_pk_add_f32 v[168:169], v[110:111], v[126:127]
	v_pk_add_f32 v[184:185], v[110:111], v[126:127] neg_lo:[0,1] neg_hi:[0,1]
	v_pk_add_f32 v[102:103], v[188:189], v[168:169]
	v_pk_add_f32 v[118:119], v[188:189], v[168:169] neg_lo:[0,1] neg_hi:[0,1]
	v_pk_add_f32 v[110:111], v[186:187], v[184:185] op_sel:[0,1] op_sel_hi:[1,0] neg_hi:[0,1]
	v_pk_add_f32 v[126:127], v[186:187], v[184:185] op_sel:[0,1] op_sel_hi:[1,0] neg_lo:[0,1]
	v_pk_add_f32 v[182:183], v[104:105], v[120:121]
	v_pk_add_f32 v[180:181], v[104:105], v[120:121] neg_lo:[0,1] neg_hi:[0,1]
	v_pk_add_f32 v[178:179], v[112:113], v[128:129]
	v_pk_add_f32 v[176:177], v[112:113], v[128:129] neg_lo:[0,1] neg_hi:[0,1]
	v_pk_add_f32 v[104:105], v[182:183], v[178:179]
	v_pk_add_f32 v[120:121], v[182:183], v[178:179] neg_lo:[0,1] neg_hi:[0,1]
	v_pk_add_f32 v[112:113], v[180:181], v[176:177] op_sel:[0,1] op_sel_hi:[1,0] neg_hi:[0,1]
	v_pk_add_f32 v[128:129], v[180:181], v[176:177] op_sel:[0,1] op_sel_hi:[1,0] neg_lo:[0,1]
	v_pk_add_f32 v[166:167], v[106:107], v[122:123]
	v_pk_add_f32 v[174:175], v[106:107], v[122:123] neg_lo:[0,1] neg_hi:[0,1]
	v_pk_add_f32 v[188:189], v[114:115], v[130:131]
	v_pk_add_f32 v[186:187], v[114:115], v[130:131] neg_lo:[0,1] neg_hi:[0,1]
	v_pk_add_f32 v[106:107], v[166:167], v[188:189]
	v_pk_add_f32 v[122:123], v[166:167], v[188:189] neg_lo:[0,1] neg_hi:[0,1]
	v_pk_add_f32 v[114:115], v[174:175], v[186:187] op_sel:[0,1] op_sel_hi:[1,0] neg_hi:[0,1]
	v_pk_add_f32 v[130:131], v[174:175], v[186:187] op_sel:[0,1] op_sel_hi:[1,0] neg_lo:[0,1]
	v_pk_mul_f32 v[168:169], v[110:111], s[68:69] op_sel:[1,1] op_sel_hi:[0,1]
	v_pk_fma_f32 v[110:111], v[110:111], s[68:69], v[168:169] op_sel_hi:[1,0,1] neg_lo:[0,0,1]
	v_pk_mul_f32 v[184:185], v[112:113], s[84:85] op_sel:[1,1] op_sel_hi:[0,1]
	v_pk_fma_f32 v[112:113], v[112:113], s[84:85], v[184:185] op_sel_hi:[1,0,1] neg_lo:[0,0,1]
	v_pk_mul_f32 v[182:183], v[114:115], s[88:89] op_sel:[1,1] op_sel_hi:[0,1]
	v_pk_fma_f32 v[114:115], v[114:115], s[88:89], v[182:183] op_sel_hi:[1,0,1] neg_lo:[0,0,1]
	v_pk_mul_f32 v[180:181], v[118:119], s[84:85] op_sel:[1,1] op_sel_hi:[0,1]
	v_pk_fma_f32 v[118:119], v[118:119], s[84:85], v[180:181] op_sel_hi:[1,0,1] neg_lo:[0,0,1]
	v_pk_mul_f32 v[178:179], v[122:123], s[90:91] op_sel:[1,1] op_sel_hi:[0,1]
	v_pk_fma_f32 v[122:123], v[122:123], s[90:91], v[178:179] op_sel_hi:[1,0,1] neg_lo:[0,0,1]
	v_pk_mul_f32 v[176:177], v[126:127], s[88:89] op_sel:[1,1] op_sel_hi:[0,1]
	v_pk_fma_f32 v[126:127], v[126:127], s[88:89], v[176:177] op_sel_hi:[1,0,1] neg_lo:[0,0,1]
	v_pk_mul_f32 v[166:167], v[128:129], s[90:91] op_sel:[1,1] op_sel_hi:[0,1]
	v_pk_fma_f32 v[128:129], v[128:129], s[90:91], v[166:167] op_sel_hi:[1,0,1] neg_lo:[0,0,1]
	v_pk_mul_f32 v[174:175], v[130:131], s[98:99] op_sel:[1,1] op_sel_hi:[0,1]
	v_pk_fma_f32 v[130:131], v[130:131], s[98:99], v[174:175] op_sel_hi:[1,0,1] neg_lo:[0,0,1]
	v_pk_add_f32 v[188:189], v[100:101], v[104:105]
	v_pk_add_f32 v[186:187], v[100:101], v[104:105] neg_lo:[0,1] neg_hi:[0,1]
	v_pk_add_f32 v[168:169], v[102:103], v[106:107]
	v_pk_add_f32 v[184:185], v[102:103], v[106:107] neg_lo:[0,1] neg_hi:[0,1]
	v_pk_add_f32 v[100:101], v[188:189], v[168:169]
	v_pk_add_f32 v[104:105], v[188:189], v[168:169] neg_lo:[0,1] neg_hi:[0,1]
	v_pk_add_f32 v[102:103], v[186:187], v[184:185] op_sel:[0,1] op_sel_hi:[1,0] neg_hi:[0,1]
; __device__ __forceinline__ f32x2 cmul(f32x2 a, f32x2 b) { return (f32x2){a.x * b.x - a.y * b.y, a.x * b.y + a.y * b.x}; }
; __device__ __forceinline__ void dft16_fwd_lo(f32x2 (&x)[16]) {
;     constexpr float C1 = 0.92387953251128674f, S1 = 0.38268343236508977f, C2 = 0.70710678118654752f;
; #pragma unroll
;     for (int b = 0; b < 4; ++b) { const f32x2 x0 = x[b], x1 = x[4 + b]; const f32x2 j1 = {x1.y, -x1.x};
;         x[b] = x0 + x1; x[4 + b] = x0 + j1; x[8 + b] = x0 - x1; x[12 + b] = x0 - j1; }
;     const f32x2 w1 = {C1, -S1}, w2 = {C2, -C2}, w3 = {S1, -C1}, w4 = {0.f, -1.f}, w6 = {-C2, -C2}, w9 = {-C1, S1};
;     x[5] = cmul(x[5], w1); x[6] = cmul(x[6], w2); x[7] = cmul(x[7], w3);
;     x[9] = cmul(x[9], w2); x[10] = cmul(x[10], w4); x[11] = cmul(x[11], w6);
;     x[13] = cmul(x[13], w3); x[14] = cmul(x[14], w6); x[15] = cmul(x[15], w9);
; template <int MODE> __device__ __forceinline__ void fft_pair32(LAS f32x2* B, const LAS f32x2* F, int wave, int lane) {
;     ...
;     if (MODE == 2) {
; #pragma unroll
;         for (int k = 0; k < 16; ++k) p[2 * k + hi] = v[k];
;         return; }
	v_pk_add_f32 v[106:107], v[186:187], v[184:185] op_sel:[0,1] op_sel_hi:[1,0] neg_lo:[0,1]
	v_pk_add_f32 v[182:183], v[108:109], v[112:113]
	v_pk_add_f32 v[180:181], v[108:109], v[112:113] neg_lo:[0,1] neg_hi:[0,1]
	v_pk_add_f32 v[178:179], v[110:111], v[114:115]
	v_pk_add_f32 v[176:177], v[110:111], v[114:115] neg_lo:[0,1] neg_hi:[0,1]
	v_pk_add_f32 v[108:109], v[182:183], v[178:179]
	v_pk_add_f32 v[112:113], v[182:183], v[178:179] neg_lo:[0,1] neg_hi:[0,1]
	v_pk_add_f32 v[110:111], v[180:181], v[176:177] op_sel:[0,1] op_sel_hi:[1,0] neg_hi:[0,1]
	v_pk_add_f32 v[114:115], v[180:181], v[176:177] op_sel:[0,1] op_sel_hi:[1,0] neg_lo:[0,1]
	v_pk_add_f32 v[166:167], v[116:117], v[120:121] op_sel:[0,1] op_sel_hi:[1,0] neg_hi:[0,1]
	v_pk_add_f32 v[174:175], v[116:117], v[120:121] op_sel:[0,1] op_sel_hi:[1,0] neg_lo:[0,1]
	v_pk_add_f32 v[188:189], v[118:119], v[122:123]
	v_pk_add_f32 v[186:187], v[118:119], v[122:123] neg_lo:[0,1] neg_hi:[0,1]
	v_pk_add_f32 v[116:117], v[166:167], v[188:189]
	v_pk_add_f32 v[120:121], v[166:167], v[188:189] neg_lo:[0,1] neg_hi:[0,1]
	v_pk_add_f32 v[118:119], v[174:175], v[186:187] op_sel:[0,1] op_sel_hi:[1,0] neg_hi:[0,1]
	v_pk_add_f32 v[122:123], v[174:175], v[186:187] op_sel:[0,1] op_sel_hi:[1,0] neg_lo:[0,1]
	v_pk_add_f32 v[168:169], v[124:125], v[128:129]
	v_pk_add_f32 v[184:185], v[124:125], v[128:129] neg_lo:[0,1] neg_hi:[0,1]
	v_pk_add_f32 v[182:183], v[126:127], v[130:131]
	v_pk_add_f32 v[180:181], v[126:127], v[130:131] neg_lo:[0,1] neg_hi:[0,1]
	v_pk_add_f32 v[124:125], v[168:169], v[182:183]
	v_pk_add_f32 v[128:129], v[168:169], v[182:183] neg_lo:[0,1] neg_hi:[0,1]
	v_pk_add_f32 v[126:127], v[184:185], v[180:181] op_sel:[0,1] op_sel_hi:[1,0] neg_hi:[0,1]
	v_pk_add_f32 v[130:131], v[184:185], v[180:181] op_sel:[0,1] op_sel_hi:[1,0] neg_lo:[0,1]
	v_pk_mul_f32 v[100:101], v[100:101], v[192:193] op_sel_hi:[1,0]
	ds_write_b64 v69, v[100:101]
	v_pk_mul_f32 v[108:109], v[108:109], v[192:193] op_sel_hi:[1,0]
	ds_write_b64 v69, v[108:109] offset:16
	v_pk_mul_f32 v[116:117], v[116:117], v[192:193] op_sel_hi:[1,0]
	ds_write_b64 v69, v[116:117] offset:32
	v_pk_mul_f32 v[124:125], v[124:125], v[192:193] op_sel_hi:[1,0]
	ds_write_b64 v69, v[124:125] offset:48
	v_pk_mul_f32 v[102:103], v[102:103], v[192:193] op_sel_hi:[1,0]
	ds_write_b64 v69, v[102:103] offset:64
	v_pk_mul_f32 v[110:111], v[110:111], v[192:193] op_sel_hi:[1,0]
	ds_write_b64 v69, v[110:111] offset:80
	v_pk_mul_f32 v[118:119], v[118:119], v[192:193] op_sel_hi:[1,0]
	ds_write_b64 v69, v[118:119] offset:96
	v_pk_mul_f32 v[126:127], v[126:127], v[192:193] op_sel_hi:[1,0]
	ds_write_b64 v69, v[126:127] offset:112
	v_pk_mul_f32 v[104:105], v[104:105], v[192:193] op_sel_hi:[1,0]
	ds_write_b64 v69, v[104:105] offset:128
	v_pk_mul_f32 v[112:113], v[112:113], v[192:193] op_sel_hi:[1,0]
	ds_write_b64 v69, v[112:113] offset:144
	v_pk_mul_f32 v[120:121], v[120:121], v[192:193] op_sel_hi:[1,0]
	ds_write_b64 v69, v[120:121] offset:160
	v_pk_mul_f32 v[128:129], v[128:129], v[192:193] op_sel_hi:[1,0]
	ds_write_b64 v69, v[128:129] offset:176
	v_pk_mul_f32 v[106:107], v[106:107], v[192:193] op_sel_hi:[1,0]
	ds_write_b64 v69, v[106:107] offset:192
	v_pk_mul_f32 v[114:115], v[114:115], v[192:193] op_sel_hi:[1,0]
	ds_write_b64 v69, v[114:115] offset:208
	v_pk_mul_f32 v[122:123], v[122:123], v[192:193] op_sel_hi:[1,0]
	ds_write_b64 v69, v[122:123] offset:224
	v_pk_mul_f32 v[130:131], v[130:131], v[192:193] op_sel_hi:[1,0]
	ds_write_b64 v69, v[130:131] offset:240
	s_waitcnt lgkmcnt(0)
	s_barrier
	v_pk_add_f32 v[104:105], v[132:133], v[140:141] neg_lo:[0,1] neg_hi:[0,1]
	v_pk_add_f32 v[106:107], v[132:133], v[140:141] op_sel:[0,1] op_sel_hi:[1,0] neg_lo:[0,1]
	v_pk_add_f32 v[178:179], v[132:133], v[140:141] op_sel:[0,1] op_sel_hi:[1,0] neg_hi:[0,1]
	v_pk_add_f32 v[100:101], v[132:133], v[140:141]
	v_pk_add_f32 v[112:113], v[134:135], v[142:143] neg_lo:[0,1] neg_hi:[0,1]
	v_pk_add_f32 v[114:115], v[134:135], v[142:143] op_sel:[0,1] op_sel_hi:[1,0] neg_lo:[0,1]
	v_pk_add_f32 v[176:177], v[134:135], v[142:143] op_sel:[0,1] op_sel_hi:[1,0] neg_hi:[0,1]
	v_pk_add_f32 v[108:109], v[134:135], v[142:143]
	v_pk_add_f32 v[120:121], v[136:137], v[144:145] neg_lo:[0,1] neg_hi:[0,1]
	v_pk_add_f32 v[122:123], v[136:137], v[144:145] op_sel:[0,1] op_sel_hi:[1,0] neg_lo:[0,1]
	v_pk_add_f32 v[166:167], v[136:137], v[144:145] op_sel:[0,1] op_sel_hi:[1,0] neg_hi:[0,1]
	v_pk_add_f32 v[116:117], v[136:137], v[144:145]
	v_pk_add_f32 v[128:129], v[138:139], v[146:147] neg_lo:[0,1] neg_hi:[0,1]
	v_pk_add_f32 v[130:131], v[138:139], v[146:147] op_sel:[0,1] op_sel_hi:[1,0] neg_lo:[0,1]
	v_pk_add_f32 v[174:175], v[138:139], v[146:147] op_sel:[0,1] op_sel_hi:[1,0] neg_hi:[0,1]
	v_pk_add_f32 v[124:125], v[138:139], v[146:147]
	v_pk_mul_f32 v[188:189], v[176:177], s[68:69] op_sel:[1,1] op_sel_hi:[0,1]
	v_pk_fma_f32 v[176:177], v[176:177], s[68:69], v[188:189] op_sel_hi:[1,0,1] neg_lo:[0,0,1]
	v_pk_mul_f32 v[186:187], v[166:167], s[84:85] op_sel:[1,1] op_sel_hi:[0,1]
	v_pk_fma_f32 v[166:167], v[166:167], s[84:85], v[186:187] op_sel_hi:[1,0,1] neg_lo:[0,0,1]
	v_pk_mul_f32 v[168:169], v[174:175], s[88:89] op_sel:[1,1] op_sel_hi:[0,1]
	v_pk_fma_f32 v[174:175], v[174:175], s[88:89], v[168:169] op_sel_hi:[1,0,1] neg_lo:[0,0,1]
	v_pk_mul_f32 v[184:185], v[112:113], s[84:85] op_sel:[1,1] op_sel_hi:[0,1]
	v_pk_fma_f32 v[112:113], v[112:113], s[84:85], v[184:185] op_sel_hi:[1,0,1] neg_lo:[0,0,1]
	v_pk_mul_f32 v[182:183], v[128:129], s[90:91] op_sel:[1,1] op_sel_hi:[0,1]
	v_pk_fma_f32 v[128:129], v[128:129], s[90:91], v[182:183] op_sel_hi:[1,0,1] neg_lo:[0,0,1]
	v_pk_mul_f32 v[180:181], v[114:115], s[88:89] op_sel:[1,1] op_sel_hi:[0,1]
; #define LAS __attribute__((address_space(3)))
; __device__ __forceinline__ f32x2 cmul(f32x2 a, f32x2 b) { return (f32x2){a.x * b.x - a.y * b.y, a.x * b.y + a.y * b.x}; }
; __device__ __forceinline__ void dft16_fwd_lo(f32x2 (&x)[16]) {
;     constexpr float C1 = 0.92387953251128674f, S1 = 0.38268343236508977f, C2 = 0.70710678118654752f;
; #pragma unroll
;     for (int b = 0; b < 4; ++b) { const f32x2 x0 = x[b], x1 = x[4 + b]; const f32x2 j1 = {x1.y, -x1.x};
;         x[b] = x0 + x1; x[4 + b] = x0 + j1; x[8 + b] = x0 - x1; x[12 + b] = x0 - j1; }
;     const f32x2 w1 = {C1, -S1}, w2 = {C2, -C2}, w3 = {S1, -C1}, w4 = {0.f, -1.f}, w6 = {-C2, -C2}, w9 = {-C1, S1};
;     x[5] = cmul(x[5], w1); x[6] = cmul(x[6], w2); x[7] = cmul(x[7], w3);
;     x[9] = cmul(x[9], w2); x[10] = cmul(x[10], w4); x[11] = cmul(x[11], w6);
;     x[13] = cmul(x[13], w3); x[14] = cmul(x[14], w6); x[15] = cmul(x[15], w9);
; #pragma unroll
;     for (int c = 0; c < 4; ++c) dft4<false>(x[4 * c], x[4 * c + 1], x[4 * c + 2], x[4 * c + 3]);
;     f32x2 y[16];
; #pragma unroll
;     for (int k = 0; k < 16; ++k) y[k] = x[4 * (k & 3) + (k >> 2)];
; #pragma unroll
;     for (int k = 0; k < 16; ++k) x[k] = y[k];
; }
; template <bool LO> __device__ __forceinline__ void fft_fwd1(f32x2 (&x)[16], LAS f32x2* B, int n2, const f32x2 (&w)[16]) {
;     asm volatile("" : "+v"(n2));
;     if (LO) dft16_fwd_lo(x); else dft16<false>(x);
;     B[fpad(n2)] = x[0];
; #pragma unroll
;     for (int k = 1; k < 16; ++k) B[fpad(512 * k + n2)] = cmul(x[k], w[k]);
; }
	v_pk_fma_f32 v[114:115], v[114:115], s[88:89], v[180:181] op_sel_hi:[1,0,1] neg_lo:[0,0,1]
	v_pk_mul_f32 v[102:103], v[122:123], s[90:91] op_sel:[1,1] op_sel_hi:[0,1]
	v_pk_fma_f32 v[122:123], v[122:123], s[90:91], v[102:103] op_sel_hi:[1,0,1] neg_lo:[0,0,1]
	v_pk_mul_f32 v[110:111], v[130:131], s[98:99] op_sel:[1,1] op_sel_hi:[0,1]
	v_pk_fma_f32 v[130:131], v[130:131], s[98:99], v[110:111] op_sel_hi:[1,0,1] neg_lo:[0,0,1]
	v_pk_add_f32 v[118:119], v[100:101], v[116:117]
	v_pk_add_f32 v[126:127], v[100:101], v[116:117] neg_lo:[0,1] neg_hi:[0,1]
	v_pk_add_f32 v[188:189], v[108:109], v[124:125]
	v_pk_add_f32 v[186:187], v[108:109], v[124:125] neg_lo:[0,1] neg_hi:[0,1]
	v_pk_add_f32 v[100:101], v[118:119], v[188:189]
	v_pk_add_f32 v[116:117], v[118:119], v[188:189] neg_lo:[0,1] neg_hi:[0,1]
	v_pk_add_f32 v[108:109], v[126:127], v[186:187] op_sel:[0,1] op_sel_hi:[1,0] neg_hi:[0,1]
	v_pk_add_f32 v[124:125], v[126:127], v[186:187] op_sel:[0,1] op_sel_hi:[1,0] neg_lo:[0,1]
	v_pk_add_f32 v[168:169], v[178:179], v[166:167]
	v_pk_add_f32 v[184:185], v[178:179], v[166:167] neg_lo:[0,1] neg_hi:[0,1]
	v_pk_add_f32 v[182:183], v[176:177], v[174:175]
	v_pk_add_f32 v[180:181], v[176:177], v[174:175] neg_lo:[0,1] neg_hi:[0,1]
	v_pk_add_f32 v[178:179], v[168:169], v[182:183]
	v_pk_add_f32 v[166:167], v[168:169], v[182:183] neg_lo:[0,1] neg_hi:[0,1]
	v_pk_add_f32 v[176:177], v[184:185], v[180:181] op_sel:[0,1] op_sel_hi:[1,0] neg_hi:[0,1]
	v_pk_add_f32 v[174:175], v[184:185], v[180:181] op_sel:[0,1] op_sel_hi:[1,0] neg_lo:[0,1]
	v_pk_add_f32 v[102:103], v[104:105], v[120:121] op_sel:[0,1] op_sel_hi:[1,0] neg_hi:[0,1]
	v_pk_add_f32 v[110:111], v[104:105], v[120:121] op_sel:[0,1] op_sel_hi:[1,0] neg_lo:[0,1]
	v_pk_add_f32 v[118:119], v[112:113], v[128:129]
	v_pk_add_f32 v[126:127], v[112:113], v[128:129] neg_lo:[0,1] neg_hi:[0,1]
	v_pk_add_f32 v[104:105], v[102:103], v[118:119]
	v_pk_add_f32 v[120:121], v[102:103], v[118:119] neg_lo:[0,1] neg_hi:[0,1]
	v_pk_add_f32 v[112:113], v[110:111], v[126:127] op_sel:[0,1] op_sel_hi:[1,0] neg_hi:[0,1]
	v_pk_add_f32 v[128:129], v[110:111], v[126:127] op_sel:[0,1] op_sel_hi:[1,0] neg_lo:[0,1]
	v_pk_add_f32 v[188:189], v[106:107], v[122:123]
	v_pk_add_f32 v[186:187], v[106:107], v[122:123] neg_lo:[0,1] neg_hi:[0,1]
	v_pk_add_f32 v[168:169], v[114:115], v[130:131]
	v_pk_add_f32 v[184:185], v[114:115], v[130:131] neg_lo:[0,1] neg_hi:[0,1]
	v_pk_add_f32 v[106:107], v[188:189], v[168:169]
	v_pk_add_f32 v[122:123], v[188:189], v[168:169] neg_lo:[0,1] neg_hi:[0,1]
	v_pk_add_f32 v[114:115], v[186:187], v[184:185] op_sel:[0,1] op_sel_hi:[1,0] neg_hi:[0,1]
	v_pk_add_f32 v[130:131], v[186:187], v[184:185] op_sel:[0,1] op_sel_hi:[1,0] neg_lo:[0,1]
	ds_write_b64 v3, v[100:101]
	v_pk_mul_f32 v[180:181], v[178:179], v[6:7] op_sel:[1,1] op_sel_hi:[0,1]
	v_pk_fma_f32 v[182:183], v[178:179], v[6:7], v[180:181] op_sel_hi:[1,0,1] neg_lo:[0,0,1]
	ds_write_b64 v3, v[182:183] offset:4224
	v_pk_mul_f32 v[110:111], v[104:105], v[8:9] op_sel:[1,1] op_sel_hi:[0,1]
	v_pk_fma_f32 v[102:103], v[104:105], v[8:9], v[110:111] op_sel_hi:[1,0,1] neg_lo:[0,0,1]
	ds_write_b64 v3, v[102:103] offset:8448
	v_pk_mul_f32 v[126:127], v[106:107], v[10:11] op_sel:[1,1] op_sel_hi:[0,1]
	v_pk_fma_f32 v[118:119], v[106:107], v[10:11], v[126:127] op_sel_hi:[1,0,1] neg_lo:[0,0,1]
	ds_write_b64 v3, v[118:119] offset:12672
	v_pk_mul_f32 v[186:187], v[108:109], v[12:13] op_sel:[1,1] op_sel_hi:[0,1]
	v_pk_fma_f32 v[188:189], v[108:109], v[12:13], v[186:187] op_sel_hi:[1,0,1] neg_lo:[0,0,1]
	ds_write_b64 v3, v[188:189] offset:16896
	v_pk_mul_f32 v[184:185], v[176:177], v[14:15] op_sel:[1,1] op_sel_hi:[0,1]
	v_pk_fma_f32 v[168:169], v[176:177], v[14:15], v[184:185] op_sel_hi:[1,0,1] neg_lo:[0,0,1]
	ds_write_b64 v3, v[168:169] offset:21120
	v_pk_mul_f32 v[182:183], v[112:113], v[16:17] op_sel:[1,1] op_sel_hi:[0,1]
	v_pk_fma_f32 v[180:181], v[112:113], v[16:17], v[182:183] op_sel_hi:[1,0,1] neg_lo:[0,0,1]
	ds_write_b64 v3, v[180:181] offset:25344
	v_pk_mul_f32 v[102:103], v[114:115], v[18:19] op_sel:[1,1] op_sel_hi:[0,1]
	v_pk_fma_f32 v[110:111], v[114:115], v[18:19], v[102:103] op_sel_hi:[1,0,1] neg_lo:[0,0,1]
	ds_write_b64 v3, v[110:111] offset:29568
	v_pk_mul_f32 v[118:119], v[116:117], v[20:21] op_sel:[1,1] op_sel_hi:[0,1]
	v_pk_fma_f32 v[126:127], v[116:117], v[20:21], v[118:119] op_sel_hi:[1,0,1] neg_lo:[0,0,1]
	ds_write_b64 v3, v[126:127] offset:33792
	v_pk_mul_f32 v[188:189], v[166:167], v[22:23] op_sel:[1,1] op_sel_hi:[0,1]
	v_pk_fma_f32 v[186:187], v[166:167], v[22:23], v[188:189] op_sel_hi:[1,0,1] neg_lo:[0,0,1]
	ds_write_b64 v3, v[186:187] offset:38016
	v_pk_mul_f32 v[168:169], v[120:121], v[24:25] op_sel:[1,1] op_sel_hi:[0,1]
	v_pk_fma_f32 v[184:185], v[120:121], v[24:25], v[168:169] op_sel_hi:[1,0,1] neg_lo:[0,0,1]
	ds_write_b64 v3, v[184:185] offset:42240
	v_pk_mul_f32 v[180:181], v[122:123], v[26:27] op_sel:[1,1] op_sel_hi:[0,1]
	v_pk_fma_f32 v[182:183], v[122:123], v[26:27], v[180:181] op_sel_hi:[1,0,1] neg_lo:[0,0,1]
	ds_write_b64 v3, v[182:183] offset:46464
	v_pk_mul_f32 v[110:111], v[124:125], v[28:29] op_sel:[1,1] op_sel_hi:[0,1]
	v_pk_fma_f32 v[102:103], v[124:125], v[28:29], v[110:111] op_sel_hi:[1,0,1] neg_lo:[0,0,1]
	ds_write_b64 v3, v[102:103] offset:50688
	v_pk_mul_f32 v[126:127], v[174:175], v[30:31] op_sel:[1,1] op_sel_hi:[0,1]
	v_pk_fma_f32 v[118:119], v[174:175], v[30:31], v[126:127] op_sel_hi:[1,0,1] neg_lo:[0,0,1]
	ds_write_b64 v3, v[118:119] offset:54912
	v_pk_mul_f32 v[186:187], v[128:129], v[32:33] op_sel:[1,1] op_sel_hi:[0,1]
	v_pk_fma_f32 v[188:189], v[128:129], v[32:33], v[186:187] op_sel_hi:[1,0,1] neg_lo:[0,0,1]
	ds_write_b64 v3, v[188:189] offset:59136
	v_pk_mul_f32 v[184:185], v[130:131], v[34:35] op_sel:[1,1] op_sel_hi:[0,1]
	v_pk_fma_f32 v[168:169], v[130:131], v[34:35], v[184:185] op_sel_hi:[1,0,1] neg_lo:[0,0,1]
	ds_write_b64 v3, v[168:169] offset:63360
	s_waitcnt lgkmcnt(0)
	s_barrier
	s_cbranch_vccz .Lhfft_st5
	s_sleep 8
; #define LAS __attribute__((address_space(3)))
; __device__ __forceinline__ f32x2 cmul(f32x2 a, f32x2 b) { return (f32x2){a.x * b.x - a.y * b.y, a.x * b.y + a.y * b.x}; }
; __device__ __forceinline__ void fft_fwd2(LAS f32x2* B, const LAS f32x2* TW2, int tid) {
;     asm volatile("" : "+v"(tid));
;     const int b = tid >> 5, n2 = tid & 31, base = 512 * b + n2; f32x2 x[16];
; #pragma unroll
;     for (int r = 0; r < 16; ++r) x[r] = B[fpad(base + 32 * r)];
;     dft16<false>(x);
;     B[fpad(base)] = x[0];
; #pragma unroll
;     for (int k = 1; k < 16; ++k) B[fpad(base + 32 * k)] = cmul(x[k], TW2[k * 32 + n2]);
; }
.Lhfft_st5:
	ds_read_b64 v[100:101], v5
	ds_read_b64 v[108:109], v5 offset:1056
	ds_read_b64 v[116:117], v5 offset:2112
	ds_read_b64 v[124:125], v5 offset:3168
	ds_read_b64 v[178:179], v5 offset:264
	ds_read_b64 v[176:177], v5 offset:1320
	ds_read_b64 v[166:167], v5 offset:2376
	ds_read_b64 v[174:175], v5 offset:3432
	ds_read_b64 v[104:105], v5 offset:528
	ds_read_b64 v[112:113], v5 offset:1584
	ds_read_b64 v[120:121], v5 offset:2640
	ds_read_b64 v[128:129], v5 offset:3696
	s_waitcnt lgkmcnt(8)
	ds_read_b64 v[106:107], v5 offset:792
	ds_read_b64 v[114:115], v5 offset:1848
	ds_read_b64 v[122:123], v5 offset:2904
	ds_read_b64 v[130:131], v5 offset:3960
	v_pk_add_f32 v[180:181], v[100:101], v[116:117]
	v_pk_add_f32 v[182:183], v[100:101], v[116:117] neg_lo:[0,1] neg_hi:[0,1]
	v_pk_add_f32 v[110:111], v[108:109], v[124:125]
	v_pk_add_f32 v[102:103], v[108:109], v[124:125] neg_lo:[0,1] neg_hi:[0,1]
	v_pk_add_f32 v[100:101], v[180:181], v[110:111]
	v_pk_add_f32 v[116:117], v[180:181], v[110:111] neg_lo:[0,1] neg_hi:[0,1]
	v_pk_add_f32 v[108:109], v[182:183], v[102:103] op_sel:[0,1] op_sel_hi:[1,0] neg_hi:[0,1]
	v_pk_add_f32 v[124:125], v[182:183], v[102:103] op_sel:[0,1] op_sel_hi:[1,0] neg_lo:[0,1]
	s_waitcnt lgkmcnt(9)
	v_pk_add_f32 v[126:127], v[178:179], v[166:167]
	v_pk_add_f32 v[118:119], v[178:179], v[166:167] neg_lo:[0,1] neg_hi:[0,1]
	s_waitcnt lgkmcnt(8)
	v_pk_add_f32 v[186:187], v[176:177], v[174:175]
	v_pk_add_f32 v[188:189], v[176:177], v[174:175] neg_lo:[0,1] neg_hi:[0,1]
	v_pk_add_f32 v[178:179], v[126:127], v[186:187]
	v_pk_add_f32 v[166:167], v[126:127], v[186:187] neg_lo:[0,1] neg_hi:[0,1]
	v_pk_add_f32 v[176:177], v[118:119], v[188:189] op_sel:[0,1] op_sel_hi:[1,0] neg_hi:[0,1]
	v_pk_add_f32 v[174:175], v[118:119], v[188:189] op_sel:[0,1] op_sel_hi:[1,0] neg_lo:[0,1]
	s_waitcnt lgkmcnt(5)
	v_pk_add_f32 v[184:185], v[104:105], v[120:121]
	v_pk_add_f32 v[168:169], v[104:105], v[120:121] neg_lo:[0,1] neg_hi:[0,1]
	s_waitcnt lgkmcnt(4)
	v_pk_add_f32 v[180:181], v[112:113], v[128:129]
	v_pk_add_f32 v[182:183], v[112:113], v[128:129] neg_lo:[0,1] neg_hi:[0,1]
	v_pk_add_f32 v[104:105], v[184:185], v[180:181]
	v_pk_add_f32 v[120:121], v[184:185], v[180:181] neg_lo:[0,1] neg_hi:[0,1]
	v_pk_add_f32 v[112:113], v[168:169], v[182:183] op_sel:[0,1] op_sel_hi:[1,0] neg_hi:[0,1]
	v_pk_add_f32 v[128:129], v[168:169], v[182:183] op_sel:[0,1] op_sel_hi:[1,0] neg_lo:[0,1]
	s_waitcnt lgkmcnt(1)
	v_pk_add_f32 v[110:111], v[106:107], v[122:123]
	v_pk_add_f32 v[102:103], v[106:107], v[122:123] neg_lo:[0,1] neg_hi:[0,1]
	s_waitcnt lgkmcnt(0)
	v_pk_add_f32 v[126:127], v[114:115], v[130:131]
	v_pk_add_f32 v[118:119], v[114:115], v[130:131] neg_lo:[0,1] neg_hi:[0,1]
	v_pk_add_f32 v[106:107], v[110:111], v[126:127]
	v_pk_add_f32 v[122:123], v[110:111], v[126:127] neg_lo:[0,1] neg_hi:[0,1]
	v_pk_add_f32 v[114:115], v[102:103], v[118:119] op_sel:[0,1] op_sel_hi:[1,0] neg_hi:[0,1]
	v_pk_add_f32 v[130:131], v[102:103], v[118:119] op_sel:[0,1] op_sel_hi:[1,0] neg_lo:[0,1]
	v_pk_mul_f32 v[186:187], v[176:177], s[68:69] op_sel:[1,1] op_sel_hi:[0,1]
	v_pk_fma_f32 v[176:177], v[176:177], s[68:69], v[186:187] op_sel_hi:[1,0,1] neg_lo:[0,0,1]
	v_pk_mul_f32 v[188:189], v[112:113], s[84:85] op_sel:[1,1] op_sel_hi:[0,1]
	v_pk_fma_f32 v[112:113], v[112:113], s[84:85], v[188:189] op_sel_hi:[1,0,1] neg_lo:[0,0,1]
	v_pk_mul_f32 v[184:185], v[114:115], s[88:89] op_sel:[1,1] op_sel_hi:[0,1]
	v_pk_fma_f32 v[114:115], v[114:115], s[88:89], v[184:185] op_sel_hi:[1,0,1] neg_lo:[0,0,1]
	v_pk_mul_f32 v[168:169], v[166:167], s[84:85] op_sel:[1,1] op_sel_hi:[0,1]
	v_pk_fma_f32 v[166:167], v[166:167], s[84:85], v[168:169] op_sel_hi:[1,0,1] neg_lo:[0,0,1]
	v_pk_mul_f32 v[180:181], v[122:123], s[90:91] op_sel:[1,1] op_sel_hi:[0,1]
	v_pk_fma_f32 v[122:123], v[122:123], s[90:91], v[180:181] op_sel_hi:[1,0,1] neg_lo:[0,0,1]
	v_pk_mul_f32 v[182:183], v[174:175], s[88:89] op_sel:[1,1] op_sel_hi:[0,1]
	v_pk_fma_f32 v[174:175], v[174:175], s[88:89], v[182:183] op_sel_hi:[1,0,1] neg_lo:[0,0,1]
	v_pk_mul_f32 v[110:111], v[128:129], s[90:91] op_sel:[1,1] op_sel_hi:[0,1]
	v_pk_fma_f32 v[128:129], v[128:129], s[90:91], v[110:111] op_sel_hi:[1,0,1] neg_lo:[0,0,1]
	v_pk_mul_f32 v[102:103], v[130:131], s[98:99] op_sel:[1,1] op_sel_hi:[0,1]
	v_pk_fma_f32 v[130:131], v[130:131], s[98:99], v[102:103] op_sel_hi:[1,0,1] neg_lo:[0,0,1]
	v_pk_add_f32 v[126:127], v[100:101], v[104:105]
	v_pk_add_f32 v[118:119], v[100:101], v[104:105] neg_lo:[0,1] neg_hi:[0,1]
	v_pk_add_f32 v[186:187], v[178:179], v[106:107]
	v_pk_add_f32 v[188:189], v[178:179], v[106:107] neg_lo:[0,1] neg_hi:[0,1]
	v_pk_add_f32 v[100:101], v[126:127], v[186:187]
	v_pk_add_f32 v[104:105], v[126:127], v[186:187] neg_lo:[0,1] neg_hi:[0,1]
	v_pk_add_f32 v[178:179], v[118:119], v[188:189] op_sel:[0,1] op_sel_hi:[1,0] neg_hi:[0,1]
	v_pk_add_f32 v[106:107], v[118:119], v[188:189] op_sel:[0,1] op_sel_hi:[1,0] neg_lo:[0,1]
	v_pk_add_f32 v[184:185], v[108:109], v[112:113]
	v_pk_add_f32 v[168:169], v[108:109], v[112:113] neg_lo:[0,1] neg_hi:[0,1]
	v_pk_add_f32 v[180:181], v[176:177], v[114:115]
	v_pk_add_f32 v[182:183], v[176:177], v[114:115] neg_lo:[0,1] neg_hi:[0,1]
	v_pk_add_f32 v[108:109], v[184:185], v[180:181]
	v_pk_add_f32 v[112:113], v[184:185], v[180:181] neg_lo:[0,1] neg_hi:[0,1]
	v_pk_add_f32 v[176:177], v[168:169], v[182:183] op_sel:[0,1] op_sel_hi:[1,0] neg_hi:[0,1]
	v_pk_add_f32 v[114:115], v[168:169], v[182:183] op_sel:[0,1] op_sel_hi:[1,0] neg_lo:[0,1]
	v_pk_add_f32 v[110:111], v[116:117], v[120:121] op_sel:[0,1] op_sel_hi:[1,0] neg_hi:[0,1]
	v_pk_add_f32 v[102:103], v[116:117], v[120:121] op_sel:[0,1] op_sel_hi:[1,0] neg_lo:[0,1]
	v_pk_add_f32 v[126:127], v[166:167], v[122:123]
	v_pk_add_f32 v[118:119], v[166:167], v[122:123] neg_lo:[0,1] neg_hi:[0,1]
	v_pk_add_f32 v[116:117], v[110:111], v[126:127]
	v_pk_add_f32 v[120:121], v[110:111], v[126:127] neg_lo:[0,1] neg_hi:[0,1]
	v_pk_add_f32 v[166:167], v[102:103], v[118:119] op_sel:[0,1] op_sel_hi:[1,0] neg_hi:[0,1]
	v_pk_add_f32 v[122:123], v[102:103], v[118:119] op_sel:[0,1] op_sel_hi:[1,0] neg_lo:[0,1]
	v_pk_add_f32 v[186:187], v[124:125], v[128:129]
	v_pk_add_f32 v[188:189], v[124:125], v[128:129] neg_lo:[0,1] neg_hi:[0,1]
	v_pk_add_f32 v[184:185], v[174:175], v[130:131]
	v_pk_add_f32 v[168:169], v[174:175], v[130:131] neg_lo:[0,1] neg_hi:[0,1]
	v_pk_add_f32 v[124:125], v[186:187], v[184:185]
	v_pk_add_f32 v[128:129], v[186:187], v[184:185] neg_lo:[0,1] neg_hi:[0,1]
	v_pk_add_f32 v[174:175], v[188:189], v[168:169] op_sel:[0,1] op_sel_hi:[1,0] neg_hi:[0,1]
	v_pk_add_f32 v[130:131], v[188:189], v[168:169] op_sel:[0,1] op_sel_hi:[1,0] neg_lo:[0,1]
	ds_write_b64 v5, v[100:101]
	ds_read_b64 v[180:181], v56 offset:256
	ds_read_b64 v[182:183], v56 offset:512
	ds_read_b64 v[110:111], v56 offset:768
	ds_read_b64 v[102:103], v56 offset:1024
	s_waitcnt lgkmcnt(3)
; #define LAS __attribute__((address_space(3)))
; __device__ __forceinline__ f32x2 cmul(f32x2 a, f32x2 b) { return (f32x2){a.x * b.x - a.y * b.y, a.x * b.y + a.y * b.x}; }
; __device__ __forceinline__ void fft_fwd2(LAS f32x2* B, const LAS f32x2* TW2, int tid) {
;     asm volatile("" : "+v"(tid));
;     const int b = tid >> 5, n2 = tid & 31, base = 512 * b + n2; f32x2 x[16];
; #pragma unroll
;     for (int r = 0; r < 16; ++r) x[r] = B[fpad(base + 32 * r)];
;     dft16<false>(x);
;     B[fpad(base)] = x[0];
; #pragma unroll
;     for (int k = 1; k < 16; ++k) B[fpad(base + 32 * k)] = cmul(x[k], TW2[k * 32 + n2]);
; }
; template <int MODE> __device__ __forceinline__ void fft_pair32(LAS f32x2* B, const LAS f32x2* F, int wave, int lane) {
;     ...
;     const int hi = lane >> 5, blk = 32 * wave + (lane & 31); const float sg = hi ? -1.f : 1.f;
;     LAS f32x2* p = B + 33 * blk; f32x2 v[16];
; #pragma unroll
;     for (int j = 0; j < 16; ++j) { const f32x2 d = p[j] + p[j + 16] * sg;
;         const f32x2 w = {hi ? CS[j] : 1.f, hi ? -SN[j] : 0.f}; v[j] = j == 0 ? d : cmul(d, w); }
	v_pk_mul_f32 v[126:127], v[108:109], v[180:181] op_sel:[1,1] op_sel_hi:[0,1]
	v_pk_fma_f32 v[108:109], v[108:109], v[180:181], v[126:127] op_sel_hi:[1,0,1] neg_lo:[0,0,1]
	ds_write_b64 v5, v[108:109] offset:264
	s_waitcnt lgkmcnt(3)
	v_pk_mul_f32 v[118:119], v[116:117], v[182:183] op_sel:[1,1] op_sel_hi:[0,1]
	v_pk_fma_f32 v[116:117], v[116:117], v[182:183], v[118:119] op_sel_hi:[1,0,1] neg_lo:[0,0,1]
	ds_write_b64 v5, v[116:117] offset:528
	s_waitcnt lgkmcnt(3)
	v_pk_mul_f32 v[186:187], v[124:125], v[110:111] op_sel:[1,1] op_sel_hi:[0,1]
	v_pk_fma_f32 v[124:125], v[124:125], v[110:111], v[186:187] op_sel_hi:[1,0,1] neg_lo:[0,0,1]
	ds_write_b64 v5, v[124:125] offset:792
	s_waitcnt lgkmcnt(3)
	v_pk_mul_f32 v[188:189], v[178:179], v[102:103] op_sel:[1,1] op_sel_hi:[0,1]
	v_pk_fma_f32 v[178:179], v[178:179], v[102:103], v[188:189] op_sel_hi:[1,0,1] neg_lo:[0,0,1]
	ds_write_b64 v5, v[178:179] offset:1056
	ds_read_b64 v[184:185], v56 offset:1280
	ds_read_b64 v[168:169], v56 offset:1536
	ds_read_b64 v[126:127], v56 offset:1792
	ds_read_b64 v[118:119], v56 offset:2048
	s_waitcnt lgkmcnt(3)
	v_pk_mul_f32 v[186:187], v[176:177], v[184:185] op_sel:[1,1] op_sel_hi:[0,1]
	v_pk_fma_f32 v[176:177], v[176:177], v[184:185], v[186:187] op_sel_hi:[1,0,1] neg_lo:[0,0,1]
	ds_write_b64 v5, v[176:177] offset:1320
	s_waitcnt lgkmcnt(3)
	v_pk_mul_f32 v[188:189], v[166:167], v[168:169] op_sel:[1,1] op_sel_hi:[0,1]
	v_pk_fma_f32 v[166:167], v[166:167], v[168:169], v[188:189] op_sel_hi:[1,0,1] neg_lo:[0,0,1]
	ds_write_b64 v5, v[166:167] offset:1584
	s_waitcnt lgkmcnt(3)
	v_pk_mul_f32 v[180:181], v[174:175], v[126:127] op_sel:[1,1] op_sel_hi:[0,1]
	v_pk_fma_f32 v[174:175], v[174:175], v[126:127], v[180:181] op_sel_hi:[1,0,1] neg_lo:[0,0,1]
	ds_write_b64 v5, v[174:175] offset:1848
	s_waitcnt lgkmcnt(3)
	v_pk_mul_f32 v[182:183], v[104:105], v[118:119] op_sel:[1,1] op_sel_hi:[0,1]
	v_pk_fma_f32 v[104:105], v[104:105], v[118:119], v[182:183] op_sel_hi:[1,0,1] neg_lo:[0,0,1]
	ds_write_b64 v5, v[104:105] offset:2112
	ds_read_b64 v[110:111], v56 offset:2304
	ds_read_b64 v[102:103], v56 offset:2560
	ds_read_b64 v[186:187], v56 offset:2816
	ds_read_b64 v[188:189], v56 offset:3072
	s_waitcnt lgkmcnt(3)
	v_pk_mul_f32 v[180:181], v[112:113], v[110:111] op_sel:[1,1] op_sel_hi:[0,1]
	v_pk_fma_f32 v[112:113], v[112:113], v[110:111], v[180:181] op_sel_hi:[1,0,1] neg_lo:[0,0,1]
	ds_write_b64 v5, v[112:113] offset:2376
	s_waitcnt lgkmcnt(3)
	v_pk_mul_f32 v[182:183], v[120:121], v[102:103] op_sel:[1,1] op_sel_hi:[0,1]
	v_pk_fma_f32 v[120:121], v[120:121], v[102:103], v[182:183] op_sel_hi:[1,0,1] neg_lo:[0,0,1]
	ds_write_b64 v5, v[120:121] offset:2640
	s_waitcnt lgkmcnt(3)
	v_pk_mul_f32 v[184:185], v[128:129], v[186:187] op_sel:[1,1] op_sel_hi:[0,1]
	v_pk_fma_f32 v[128:129], v[128:129], v[186:187], v[184:185] op_sel_hi:[1,0,1] neg_lo:[0,0,1]
	ds_write_b64 v5, v[128:129] offset:2904
	s_waitcnt lgkmcnt(3)
	v_pk_mul_f32 v[168:169], v[106:107], v[188:189] op_sel:[1,1] op_sel_hi:[0,1]
	v_pk_fma_f32 v[106:107], v[106:107], v[188:189], v[168:169] op_sel_hi:[1,0,1] neg_lo:[0,0,1]
	ds_write_b64 v5, v[106:107] offset:3168
	ds_read_b64 v[126:127], v56 offset:3328
	ds_read_b64 v[118:119], v56 offset:3584
	ds_read_b64 v[180:181], v56 offset:3840
	s_waitcnt lgkmcnt(2)
	v_pk_mul_f32 v[182:183], v[114:115], v[126:127] op_sel:[1,1] op_sel_hi:[0,1]
	v_pk_fma_f32 v[114:115], v[114:115], v[126:127], v[182:183] op_sel_hi:[1,0,1] neg_lo:[0,0,1]
	ds_write_b64 v5, v[114:115] offset:3432
	s_waitcnt lgkmcnt(2)
	v_pk_mul_f32 v[184:185], v[122:123], v[118:119] op_sel:[1,1] op_sel_hi:[0,1]
	v_pk_fma_f32 v[122:123], v[122:123], v[118:119], v[184:185] op_sel_hi:[1,0,1] neg_lo:[0,0,1]
	ds_write_b64 v5, v[122:123] offset:3696
	s_waitcnt lgkmcnt(2)
	v_pk_mul_f32 v[168:169], v[130:131], v[180:181] op_sel:[1,1] op_sel_hi:[0,1]
	v_pk_fma_f32 v[130:131], v[130:131], v[180:181], v[168:169] op_sel_hi:[1,0,1] neg_lo:[0,0,1]
	ds_write_b64 v5, v[130:131] offset:3960
	s_waitcnt lgkmcnt(0)
	ds_read_b64 v[100:101], v156
	ds_read_b64 v[110:111], v156 offset:128
	ds_read_b64 v[108:109], v156 offset:8
	ds_read_b64 v[102:103], v156 offset:136
	ds_read_b64 v[116:117], v156 offset:16
	ds_read_b64 v[186:187], v156 offset:144
	ds_read_b64 v[124:125], v156 offset:24
	ds_read_b64 v[188:189], v156 offset:152
	s_waitcnt lgkmcnt(6)
	v_pk_fma_f32 v[100:101], v[110:111], v[190:191], v[100:101] op_sel_hi:[1,0,1]
	s_waitcnt lgkmcnt(4)
	v_pk_fma_f32 v[108:109], v[102:103], v[190:191], v[108:109] op_sel_hi:[1,0,1]
	v_pk_mul_f32 v[182:183], v[108:109], v[36:37] op_sel:[1,1] op_sel_hi:[0,1]
	v_pk_fma_f32 v[108:109], v[108:109], v[36:37], v[182:183] op_sel_hi:[1,0,1] neg_lo:[0,0,1]
	s_waitcnt lgkmcnt(2)
	v_pk_fma_f32 v[116:117], v[186:187], v[190:191], v[116:117] op_sel_hi:[1,0,1]
	v_pk_mul_f32 v[184:185], v[116:117], v[38:39] op_sel:[1,1] op_sel_hi:[0,1]
	v_pk_fma_f32 v[116:117], v[116:117], v[38:39], v[184:185] op_sel_hi:[1,0,1] neg_lo:[0,0,1]
	s_waitcnt lgkmcnt(0)
	v_pk_fma_f32 v[124:125], v[188:189], v[190:191], v[124:125] op_sel_hi:[1,0,1]
	v_pk_mul_f32 v[168:169], v[124:125], v[40:41] op_sel:[1,1] op_sel_hi:[0,1]
	v_pk_fma_f32 v[124:125], v[124:125], v[40:41], v[168:169] op_sel_hi:[1,0,1] neg_lo:[0,0,1]
	ds_read_b64 v[178:179], v156 offset:32
	ds_read_b64 v[126:127], v156 offset:160
	ds_read_b64 v[176:177], v156 offset:40
	ds_read_b64 v[118:119], v156 offset:168
	ds_read_b64 v[166:167], v156 offset:48
	ds_read_b64 v[180:181], v156 offset:176
	ds_read_b64 v[174:175], v156 offset:56
	ds_read_b64 v[182:183], v156 offset:184
	s_waitcnt lgkmcnt(6)
; __device__ __forceinline__ f32x2 cmul(f32x2 a, f32x2 b) { return (f32x2){a.x * b.x - a.y * b.y, a.x * b.y + a.y * b.x}; }
; template <bool INV> __device__ __forceinline__ f32x2 cmul_tw(f32x2 a, f32x2 w) { return INV ? cmulc(a, w) : cmul(a, w); }
; template <bool INV> __device__ __forceinline__ void dft16(f32x2 (&x)[16]) {
;     constexpr float C1 = 0.92387953251128674f, S1 = 0.38268343236508977f, C2 = 0.70710678118654752f;
; #pragma unroll
;     for (int b = 0; b < 4; ++b) dft4<INV>(x[b], x[4 + b], x[8 + b], x[12 + b]);
;     const f32x2 w1 = {C1, -S1}, w2 = {C2, -C2}, w3 = {S1, -C1}, w4 = {0.f, -1.f}, w6 = {-C2, -C2}, w9 = {-C1, S1};
;     x[4 * 1 + 1] = cmul_tw<INV>(x[5], w1); x[4 * 1 + 2] = cmul_tw<INV>(x[6], w2); x[4 * 1 + 3] = cmul_tw<INV>(x[7], w3);
;     x[4 * 2 + 1] = cmul_tw<INV>(x[9], w2); x[4 * 2 + 2] = cmul_tw<INV>(x[10], w4); x[4 * 2 + 3] = cmul_tw<INV>(x[11], w6);
;     x[4 * 3 + 1] = cmul_tw<INV>(x[13], w3); x[4 * 3 + 2] = cmul_tw<INV>(x[14], w6); x[4 * 3 + 3] = cmul_tw<INV>(x[15], w9);
; #pragma unroll
;     for (int c = 0; c < 4; ++c) dft4<INV>(x[4 * c], x[4 * c + 1], x[4 * c + 2], x[4 * c + 3]);
;     f32x2 y[16];
; #pragma unroll
;     for (int k = 0; k < 16; ++k) y[k] = x[4 * (k & 3) + (k >> 2)];
; #pragma unroll
;     for (int k = 0; k < 16; ++k) x[k] = y[k];
; template <int MODE> __device__ __forceinline__ void fft_pair32(LAS f32x2* B, const LAS f32x2* F, int wave, int lane) {
;     ...
;     for (int j = 0; j < 16; ++j) { const f32x2 d = p[j] + p[j + 16] * sg;
;         const f32x2 w = {hi ? CS[j] : 1.f, hi ? -SN[j] : 0.f}; v[j] = j == 0 ? d : cmul(d, w); }
;     dft16<false>(v);
	v_pk_fma_f32 v[178:179], v[126:127], v[190:191], v[178:179] op_sel_hi:[1,0,1]
	v_pk_mul_f32 v[184:185], v[178:179], v[42:43] op_sel:[1,1] op_sel_hi:[0,1]
	v_pk_fma_f32 v[178:179], v[178:179], v[42:43], v[184:185] op_sel_hi:[1,0,1] neg_lo:[0,0,1]
	s_waitcnt lgkmcnt(4)
	v_pk_fma_f32 v[176:177], v[118:119], v[190:191], v[176:177] op_sel_hi:[1,0,1]
	v_pk_mul_f32 v[168:169], v[176:177], v[44:45] op_sel:[1,1] op_sel_hi:[0,1]
	v_pk_fma_f32 v[176:177], v[176:177], v[44:45], v[168:169] op_sel_hi:[1,0,1] neg_lo:[0,0,1]
	s_waitcnt lgkmcnt(2)
	v_pk_fma_f32 v[166:167], v[180:181], v[190:191], v[166:167] op_sel_hi:[1,0,1]
	v_pk_mul_f32 v[110:111], v[166:167], v[46:47] op_sel:[1,1] op_sel_hi:[0,1]
	v_pk_fma_f32 v[166:167], v[166:167], v[46:47], v[110:111] op_sel_hi:[1,0,1] neg_lo:[0,0,1]
	s_waitcnt lgkmcnt(0)
	v_pk_fma_f32 v[174:175], v[182:183], v[190:191], v[174:175] op_sel_hi:[1,0,1]
	v_pk_mul_f32 v[102:103], v[174:175], v[48:49] op_sel:[1,1] op_sel_hi:[0,1]
	v_pk_fma_f32 v[174:175], v[174:175], v[48:49], v[102:103] op_sel_hi:[1,0,1] neg_lo:[0,0,1]
	ds_read_b64 v[104:105], v156 offset:64
	ds_read_b64 v[186:187], v156 offset:192
	ds_read_b64 v[112:113], v156 offset:72
	ds_read_b64 v[188:189], v156 offset:200
	ds_read_b64 v[120:121], v156 offset:80
	ds_read_b64 v[184:185], v156 offset:208
	ds_read_b64 v[128:129], v156 offset:88
	ds_read_b64 v[168:169], v156 offset:216
	s_waitcnt lgkmcnt(6)
	v_pk_fma_f32 v[104:105], v[186:187], v[190:191], v[104:105] op_sel_hi:[1,0,1]
	v_pk_mul_f32 v[110:111], v[104:105], v[50:51] op_sel:[1,1] op_sel_hi:[0,1]
	v_pk_fma_f32 v[104:105], v[104:105], v[50:51], v[110:111] op_sel_hi:[1,0,1] neg_lo:[0,0,1]
	s_waitcnt lgkmcnt(4)
	v_pk_fma_f32 v[112:113], v[188:189], v[190:191], v[112:113] op_sel_hi:[1,0,1]
	v_pk_mul_f32 v[102:103], v[112:113], v[52:53] op_sel:[1,1] op_sel_hi:[0,1]
	v_pk_fma_f32 v[112:113], v[112:113], v[52:53], v[102:103] op_sel_hi:[1,0,1] neg_lo:[0,0,1]
	s_waitcnt lgkmcnt(2)
	v_pk_fma_f32 v[120:121], v[184:185], v[190:191], v[120:121] op_sel_hi:[1,0,1]
	v_pk_mul_f32 v[126:127], v[120:121], v[54:55] op_sel:[1,1] op_sel_hi:[0,1]
	v_pk_fma_f32 v[120:121], v[120:121], v[54:55], v[126:127] op_sel_hi:[1,0,1] neg_lo:[0,0,1]
	s_waitcnt lgkmcnt(0)
	v_pk_fma_f32 v[128:129], v[168:169], v[190:191], v[128:129] op_sel_hi:[1,0,1]
	v_pk_mul_f32 v[118:119], v[128:129], v[90:91] op_sel:[1,1] op_sel_hi:[0,1]
	v_pk_fma_f32 v[128:129], v[128:129], v[90:91], v[118:119] op_sel_hi:[1,0,1] neg_lo:[0,0,1]
	ds_read_b64 v[106:107], v156 offset:96
	ds_read_b64 v[180:181], v156 offset:224
	ds_read_b64 v[114:115], v156 offset:104
	ds_read_b64 v[182:183], v156 offset:232
	ds_read_b64 v[122:123], v156 offset:112
	ds_read_b64 v[110:111], v156 offset:240
	ds_read_b64 v[130:131], v156 offset:120
	ds_read_b64 v[102:103], v156 offset:248
	s_waitcnt lgkmcnt(6)
	v_pk_fma_f32 v[106:107], v[180:181], v[190:191], v[106:107] op_sel_hi:[1,0,1]
	v_pk_mul_f32 v[126:127], v[106:107], v[92:93] op_sel:[1,1] op_sel_hi:[0,1]
	v_pk_fma_f32 v[106:107], v[106:107], v[92:93], v[126:127] op_sel_hi:[1,0,1] neg_lo:[0,0,1]
	s_waitcnt lgkmcnt(4)
	v_pk_fma_f32 v[114:115], v[182:183], v[190:191], v[114:115] op_sel_hi:[1,0,1]
	v_pk_mul_f32 v[118:119], v[114:115], v[94:95] op_sel:[1,1] op_sel_hi:[0,1]
	v_pk_fma_f32 v[114:115], v[114:115], v[94:95], v[118:119] op_sel_hi:[1,0,1] neg_lo:[0,0,1]
	s_waitcnt lgkmcnt(2)
	v_pk_fma_f32 v[122:123], v[110:111], v[190:191], v[122:123] op_sel_hi:[1,0,1]
	v_pk_mul_f32 v[186:187], v[122:123], v[96:97] op_sel:[1,1] op_sel_hi:[0,1]
	v_pk_fma_f32 v[122:123], v[122:123], v[96:97], v[186:187] op_sel_hi:[1,0,1] neg_lo:[0,0,1]
	s_waitcnt lgkmcnt(0)
	v_pk_fma_f32 v[130:131], v[102:103], v[190:191], v[130:131] op_sel_hi:[1,0,1]
	v_pk_mul_f32 v[188:189], v[130:131], v[98:99] op_sel:[1,1] op_sel_hi:[0,1]
	v_pk_fma_f32 v[130:131], v[130:131], v[98:99], v[188:189] op_sel_hi:[1,0,1] neg_lo:[0,0,1]
	v_pk_add_f32 v[184:185], v[100:101], v[104:105]
	v_pk_add_f32 v[168:169], v[100:101], v[104:105] neg_lo:[0,1] neg_hi:[0,1]
	v_pk_add_f32 v[126:127], v[178:179], v[106:107]
	v_pk_add_f32 v[118:119], v[178:179], v[106:107] neg_lo:[0,1] neg_hi:[0,1]
	v_pk_add_f32 v[100:101], v[184:185], v[126:127]
	v_pk_add_f32 v[104:105], v[184:185], v[126:127] neg_lo:[0,1] neg_hi:[0,1]
	v_pk_add_f32 v[178:179], v[168:169], v[118:119] op_sel:[0,1] op_sel_hi:[1,0] neg_hi:[0,1]
	v_pk_add_f32 v[106:107], v[168:169], v[118:119] op_sel:[0,1] op_sel_hi:[1,0] neg_lo:[0,1]
	v_pk_add_f32 v[186:187], v[108:109], v[112:113]
	v_pk_add_f32 v[188:189], v[108:109], v[112:113] neg_lo:[0,1] neg_hi:[0,1]
	v_pk_add_f32 v[180:181], v[176:177], v[114:115]
	v_pk_add_f32 v[182:183], v[176:177], v[114:115] neg_lo:[0,1] neg_hi:[0,1]
	v_pk_add_f32 v[108:109], v[186:187], v[180:181]
	v_pk_add_f32 v[112:113], v[186:187], v[180:181] neg_lo:[0,1] neg_hi:[0,1]
	v_pk_add_f32 v[176:177], v[188:189], v[182:183] op_sel:[0,1] op_sel_hi:[1,0] neg_hi:[0,1]
	v_pk_add_f32 v[114:115], v[188:189], v[182:183] op_sel:[0,1] op_sel_hi:[1,0] neg_lo:[0,1]
	v_pk_add_f32 v[110:111], v[116:117], v[120:121]
	v_pk_add_f32 v[102:103], v[116:117], v[120:121] neg_lo:[0,1] neg_hi:[0,1]
	v_pk_add_f32 v[184:185], v[166:167], v[122:123]
	v_pk_add_f32 v[168:169], v[166:167], v[122:123] neg_lo:[0,1] neg_hi:[0,1]
	v_pk_add_f32 v[116:117], v[110:111], v[184:185]
	v_pk_add_f32 v[120:121], v[110:111], v[184:185] neg_lo:[0,1] neg_hi:[0,1]
	v_pk_add_f32 v[166:167], v[102:103], v[168:169] op_sel:[0,1] op_sel_hi:[1,0] neg_hi:[0,1]
	v_pk_add_f32 v[122:123], v[102:103], v[168:169] op_sel:[0,1] op_sel_hi:[1,0] neg_lo:[0,1]
	v_pk_add_f32 v[126:127], v[124:125], v[128:129]
	v_pk_add_f32 v[118:119], v[124:125], v[128:129] neg_lo:[0,1] neg_hi:[0,1]
; #define LAS __attribute__((address_space(3)))
; __device__ __forceinline__ f32x2 cmul(f32x2 a, f32x2 b) { return (f32x2){a.x * b.x - a.y * b.y, a.x * b.y + a.y * b.x}; }
; template <bool INV> __device__ __forceinline__ f32x2 cmul_tw(f32x2 a, f32x2 w) { return INV ? cmulc(a, w) : cmul(a, w); }
; template <bool INV> __device__ __forceinline__ void dft16(f32x2 (&x)[16]) {
;     constexpr float C1 = 0.92387953251128674f, S1 = 0.38268343236508977f, C2 = 0.70710678118654752f;
; #pragma unroll
;     for (int b = 0; b < 4; ++b) dft4<INV>(x[b], x[4 + b], x[8 + b], x[12 + b]);
;     const f32x2 w1 = {C1, -S1}, w2 = {C2, -C2}, w3 = {S1, -C1}, w4 = {0.f, -1.f}, w6 = {-C2, -C2}, w9 = {-C1, S1};
;     x[4 * 1 + 1] = cmul_tw<INV>(x[5], w1); x[4 * 1 + 2] = cmul_tw<INV>(x[6], w2); x[4 * 1 + 3] = cmul_tw<INV>(x[7], w3);
;     x[4 * 2 + 1] = cmul_tw<INV>(x[9], w2); x[4 * 2 + 2] = cmul_tw<INV>(x[10], w4); x[4 * 2 + 3] = cmul_tw<INV>(x[11], w6);
;     x[4 * 3 + 1] = cmul_tw<INV>(x[13], w3); x[4 * 3 + 2] = cmul_tw<INV>(x[14], w6); x[4 * 3 + 3] = cmul_tw<INV>(x[15], w9);
; #pragma unroll
;     for (int c = 0; c < 4; ++c) dft4<INV>(x[4 * c], x[4 * c + 1], x[4 * c + 2], x[4 * c + 3]);
;     f32x2 y[16];
; #pragma unroll
;     for (int k = 0; k < 16; ++k) y[k] = x[4 * (k & 3) + (k >> 2)];
; #pragma unroll
;     for (int k = 0; k < 16; ++k) x[k] = y[k];
; template <int MODE> __device__ __forceinline__ void fft_pair32(LAS f32x2* B, const LAS f32x2* F, int wave, int lane) {
;     ...
;     const int k1 = blk >> 4, k2 = blk & 15, kb1 = (16 - k1) & 15, b1 = k1 != 0 ? 1 : 0, kb2 = (16 - k2 - b1) & 15, b2 = (k2 != 0 || b1) ? 1 : 0;
;     const LAS f32x2* fa = F + 33 * blk; const LAS f32x2* fb = F + 33 * (16 * kb1 + kb2);
;     const LAS f32x2* fah = fa + hi; const LAS f32x2* fbh = fb + (1 - b2) - hi;
;     constexpr float SC = 1.0f / (2.0f * (float)FN);
; #pragma unroll
;     for (int k = 0; k < 16; ++k) { const f32x2 A = fah[2 * k]; f32x2 Bm = fbh[31 - 2 * k];
;         if (k == 0) { const f32x2 m0 = b2 ? fb[31] : fa[0]; Bm = hi ? Bm : m0; }
;         const f32x2 H = MODE == 0 ? (f32x2){(A.x + Bm.x) * SC, (A.y - Bm.y) * SC} : (f32x2){(A.y + Bm.y) * SC, (Bm.x - A.x) * SC};
;         v[k] = cmul(v[k], H); }
	v_pk_add_f32 v[186:187], v[174:175], v[130:131]
	v_pk_add_f32 v[188:189], v[174:175], v[130:131] neg_lo:[0,1] neg_hi:[0,1]
	v_pk_add_f32 v[124:125], v[126:127], v[186:187]
	v_pk_add_f32 v[128:129], v[126:127], v[186:187] neg_lo:[0,1] neg_hi:[0,1]
	v_pk_add_f32 v[174:175], v[118:119], v[188:189] op_sel:[0,1] op_sel_hi:[1,0] neg_hi:[0,1]
	v_pk_add_f32 v[130:131], v[118:119], v[188:189] op_sel:[0,1] op_sel_hi:[1,0] neg_lo:[0,1]
	v_pk_mul_f32 v[180:181], v[176:177], s[68:69] op_sel:[1,1] op_sel_hi:[0,1]
	v_pk_fma_f32 v[176:177], v[176:177], s[68:69], v[180:181] op_sel_hi:[1,0,1] neg_lo:[0,0,1]
	v_pk_mul_f32 v[182:183], v[166:167], s[84:85] op_sel:[1,1] op_sel_hi:[0,1]
	v_pk_fma_f32 v[166:167], v[166:167], s[84:85], v[182:183] op_sel_hi:[1,0,1] neg_lo:[0,0,1]
	v_pk_mul_f32 v[110:111], v[174:175], s[88:89] op_sel:[1,1] op_sel_hi:[0,1]
	v_pk_fma_f32 v[174:175], v[174:175], s[88:89], v[110:111] op_sel_hi:[1,0,1] neg_lo:[0,0,1]
	v_pk_mul_f32 v[102:103], v[112:113], s[84:85] op_sel:[1,1] op_sel_hi:[0,1]
	v_pk_fma_f32 v[112:113], v[112:113], s[84:85], v[102:103] op_sel_hi:[1,0,1] neg_lo:[0,0,1]
	v_pk_mul_f32 v[184:185], v[128:129], s[90:91] op_sel:[1,1] op_sel_hi:[0,1]
	v_pk_fma_f32 v[128:129], v[128:129], s[90:91], v[184:185] op_sel_hi:[1,0,1] neg_lo:[0,0,1]
	v_pk_mul_f32 v[168:169], v[114:115], s[88:89] op_sel:[1,1] op_sel_hi:[0,1]
	v_pk_fma_f32 v[114:115], v[114:115], s[88:89], v[168:169] op_sel_hi:[1,0,1] neg_lo:[0,0,1]
	v_pk_mul_f32 v[126:127], v[122:123], s[90:91] op_sel:[1,1] op_sel_hi:[0,1]
	v_pk_fma_f32 v[122:123], v[122:123], s[90:91], v[126:127] op_sel_hi:[1,0,1] neg_lo:[0,0,1]
	v_pk_mul_f32 v[118:119], v[130:131], s[98:99] op_sel:[1,1] op_sel_hi:[0,1]
	v_pk_fma_f32 v[130:131], v[130:131], s[98:99], v[118:119] op_sel_hi:[1,0,1] neg_lo:[0,0,1]
	v_pk_add_f32 v[186:187], v[100:101], v[116:117]
	v_pk_add_f32 v[188:189], v[100:101], v[116:117] neg_lo:[0,1] neg_hi:[0,1]
	v_pk_add_f32 v[180:181], v[108:109], v[124:125]
	v_pk_add_f32 v[182:183], v[108:109], v[124:125] neg_lo:[0,1] neg_hi:[0,1]
	v_pk_add_f32 v[100:101], v[186:187], v[180:181]
	v_pk_add_f32 v[116:117], v[186:187], v[180:181] neg_lo:[0,1] neg_hi:[0,1]
	v_pk_add_f32 v[108:109], v[188:189], v[182:183] op_sel:[0,1] op_sel_hi:[1,0] neg_hi:[0,1]
	v_pk_add_f32 v[124:125], v[188:189], v[182:183] op_sel:[0,1] op_sel_hi:[1,0] neg_lo:[0,1]
	v_pk_add_f32 v[110:111], v[178:179], v[166:167]
	v_pk_add_f32 v[102:103], v[178:179], v[166:167] neg_lo:[0,1] neg_hi:[0,1]
	v_pk_add_f32 v[184:185], v[176:177], v[174:175]
	v_pk_add_f32 v[168:169], v[176:177], v[174:175] neg_lo:[0,1] neg_hi:[0,1]
	v_pk_add_f32 v[178:179], v[110:111], v[184:185]
	v_pk_add_f32 v[166:167], v[110:111], v[184:185] neg_lo:[0,1] neg_hi:[0,1]
	v_pk_add_f32 v[176:177], v[102:103], v[168:169] op_sel:[0,1] op_sel_hi:[1,0] neg_hi:[0,1]
	v_pk_add_f32 v[174:175], v[102:103], v[168:169] op_sel:[0,1] op_sel_hi:[1,0] neg_lo:[0,1]
	v_pk_add_f32 v[126:127], v[104:105], v[120:121] op_sel:[0,1] op_sel_hi:[1,0] neg_hi:[0,1]
	v_pk_add_f32 v[118:119], v[104:105], v[120:121] op_sel:[0,1] op_sel_hi:[1,0] neg_lo:[0,1]
	v_pk_add_f32 v[186:187], v[112:113], v[128:129]
	v_pk_add_f32 v[188:189], v[112:113], v[128:129] neg_lo:[0,1] neg_hi:[0,1]
	v_pk_add_f32 v[104:105], v[126:127], v[186:187]
	v_pk_add_f32 v[120:121], v[126:127], v[186:187] neg_lo:[0,1] neg_hi:[0,1]
	v_pk_add_f32 v[112:113], v[118:119], v[188:189] op_sel:[0,1] op_sel_hi:[1,0] neg_hi:[0,1]
	v_pk_add_f32 v[128:129], v[118:119], v[188:189] op_sel:[0,1] op_sel_hi:[1,0] neg_lo:[0,1]
	v_pk_add_f32 v[180:181], v[106:107], v[122:123]
	v_pk_add_f32 v[182:183], v[106:107], v[122:123] neg_lo:[0,1] neg_hi:[0,1]
	v_pk_add_f32 v[110:111], v[114:115], v[130:131]
	v_pk_add_f32 v[102:103], v[114:115], v[130:131] neg_lo:[0,1] neg_hi:[0,1]
	v_pk_add_f32 v[106:107], v[180:181], v[110:111]
	v_pk_add_f32 v[122:123], v[180:181], v[110:111] neg_lo:[0,1] neg_hi:[0,1]
	v_pk_add_f32 v[114:115], v[182:183], v[102:103] op_sel:[0,1] op_sel_hi:[1,0] neg_hi:[0,1]
	v_pk_add_f32 v[130:131], v[182:183], v[102:103] op_sel:[0,1] op_sel_hi:[1,0] neg_lo:[0,1]
	ds_read_b64 v[184:185], v200
	ds_read_b64 v[186:187], v204
	ds_read_b64 v[168:169], v200 offset:16
	ds_read_b64 v[188:189], v202 offset:232
	ds_read_b64 v[126:127], v200 offset:32
	ds_read_b64 v[180:181], v202 offset:216
	ds_read_b64 v[118:119], v200 offset:48
	ds_read_b64 v[182:183], v202 offset:200
	s_waitcnt lgkmcnt(6)
	v_pk_add_f32 v[184:185], v[184:185], v[186:187] neg_hi:[0,1]
	v_pk_mul_f32 v[110:111], v[100:101], v[184:185] op_sel:[1,1] op_sel_hi:[0,1]
	v_pk_fma_f32 v[100:101], v[100:101], v[184:185], v[110:111] op_sel_hi:[1,0,1] neg_lo:[0,0,1]
	s_waitcnt lgkmcnt(4)
	v_pk_add_f32 v[168:169], v[168:169], v[188:189] neg_hi:[0,1]
	v_pk_mul_f32 v[102:103], v[178:179], v[168:169] op_sel:[1,1] op_sel_hi:[0,1]
	v_pk_fma_f32 v[178:179], v[178:179], v[168:169], v[102:103] op_sel_hi:[1,0,1] neg_lo:[0,0,1]
	s_waitcnt lgkmcnt(2)
	v_pk_add_f32 v[126:127], v[126:127], v[180:181] neg_hi:[0,1]
	v_pk_mul_f32 v[110:111], v[104:105], v[126:127] op_sel:[1,1] op_sel_hi:[0,1]
	v_pk_fma_f32 v[104:105], v[104:105], v[126:127], v[110:111] op_sel_hi:[1,0,1] neg_lo:[0,0,1]
	s_waitcnt lgkmcnt(0)
	v_pk_add_f32 v[118:119], v[118:119], v[182:183] neg_hi:[0,1]
	v_pk_mul_f32 v[102:103], v[106:107], v[118:119] op_sel:[1,1] op_sel_hi:[0,1]
	v_pk_fma_f32 v[106:107], v[106:107], v[118:119], v[102:103] op_sel_hi:[1,0,1] neg_lo:[0,0,1]
	ds_read_b64 v[110:111], v200 offset:64
	ds_read_b64 v[126:127], v202 offset:184
	ds_read_b64 v[102:103], v200 offset:80
	ds_read_b64 v[118:119], v202 offset:168
	ds_read_b64 v[184:185], v200 offset:96
	ds_read_b64 v[186:187], v202 offset:152
	ds_read_b64 v[168:169], v200 offset:112
	ds_read_b64 v[188:189], v202 offset:136
	s_waitcnt lgkmcnt(6)
; __device__ __forceinline__ f32x2 cmul(f32x2 a, f32x2 b) { return (f32x2){a.x * b.x - a.y * b.y, a.x * b.y + a.y * b.x}; }
; template <bool INV> __device__ __forceinline__ f32x2 cmul_tw(f32x2 a, f32x2 w) { return INV ? cmulc(a, w) : cmul(a, w); }
; template <bool INV> __device__ __forceinline__ void dft16(f32x2 (&x)[16]) {
;     constexpr float C1 = 0.92387953251128674f, S1 = 0.38268343236508977f, C2 = 0.70710678118654752f;
; #pragma unroll
;     for (int b = 0; b < 4; ++b) dft4<INV>(x[b], x[4 + b], x[8 + b], x[12 + b]);
;     const f32x2 w1 = {C1, -S1}, w2 = {C2, -C2}, w3 = {S1, -C1}, w4 = {0.f, -1.f}, w6 = {-C2, -C2}, w9 = {-C1, S1};
;     x[4 * 1 + 1] = cmul_tw<INV>(x[5], w1); x[4 * 1 + 2] = cmul_tw<INV>(x[6], w2); x[4 * 1 + 3] = cmul_tw<INV>(x[7], w3);
;     x[4 * 2 + 1] = cmul_tw<INV>(x[9], w2); x[4 * 2 + 2] = cmul_tw<INV>(x[10], w4); x[4 * 2 + 3] = cmul_tw<INV>(x[11], w6);
;     x[4 * 3 + 1] = cmul_tw<INV>(x[13], w3); x[4 * 3 + 2] = cmul_tw<INV>(x[14], w6); x[4 * 3 + 3] = cmul_tw<INV>(x[15], w9);
; #pragma unroll
;     for (int c = 0; c < 4; ++c) dft4<INV>(x[4 * c], x[4 * c + 1], x[4 * c + 2], x[4 * c + 3]);
; template <int MODE> __device__ __forceinline__ void fft_pair32(LAS f32x2* B, const LAS f32x2* F, int wave, int lane) {
;     ...
;     for (int k = 0; k < 16; ++k) { const f32x2 A = fah[2 * k]; f32x2 Bm = fbh[31 - 2 * k];
;         if (k == 0) { const f32x2 m0 = b2 ? fb[31] : fa[0]; Bm = hi ? Bm : m0; }
;         const f32x2 H = MODE == 0 ? (f32x2){(A.x + Bm.x) * SC, (A.y - Bm.y) * SC} : (f32x2){(A.y + Bm.y) * SC, (Bm.x - A.x) * SC};
;         v[k] = cmul(v[k], H); }
;     dft16<true>(v);
	v_pk_add_f32 v[110:111], v[110:111], v[126:127] neg_hi:[0,1]
	v_pk_mul_f32 v[180:181], v[108:109], v[110:111] op_sel:[1,1] op_sel_hi:[0,1]
	v_pk_fma_f32 v[108:109], v[108:109], v[110:111], v[180:181] op_sel_hi:[1,0,1] neg_lo:[0,0,1]
	s_waitcnt lgkmcnt(4)
	v_pk_add_f32 v[102:103], v[102:103], v[118:119] neg_hi:[0,1]
	v_pk_mul_f32 v[182:183], v[176:177], v[102:103] op_sel:[1,1] op_sel_hi:[0,1]
	v_pk_fma_f32 v[176:177], v[176:177], v[102:103], v[182:183] op_sel_hi:[1,0,1] neg_lo:[0,0,1]
	s_waitcnt lgkmcnt(2)
	v_pk_add_f32 v[184:185], v[184:185], v[186:187] neg_hi:[0,1]
	v_pk_mul_f32 v[180:181], v[112:113], v[184:185] op_sel:[1,1] op_sel_hi:[0,1]
	v_pk_fma_f32 v[112:113], v[112:113], v[184:185], v[180:181] op_sel_hi:[1,0,1] neg_lo:[0,0,1]
	s_waitcnt lgkmcnt(0)
	v_pk_add_f32 v[168:169], v[168:169], v[188:189] neg_hi:[0,1]
	v_pk_mul_f32 v[182:183], v[114:115], v[168:169] op_sel:[1,1] op_sel_hi:[0,1]
	v_pk_fma_f32 v[114:115], v[114:115], v[168:169], v[182:183] op_sel_hi:[1,0,1] neg_lo:[0,0,1]
	ds_read_b64 v[180:181], v200 offset:128
	ds_read_b64 v[184:185], v202 offset:120
	ds_read_b64 v[182:183], v200 offset:144
	ds_read_b64 v[168:169], v202 offset:104
	ds_read_b64 v[110:111], v200 offset:160
	ds_read_b64 v[126:127], v202 offset:88
	ds_read_b64 v[102:103], v200 offset:176
	ds_read_b64 v[118:119], v202 offset:72
	s_waitcnt lgkmcnt(6)
	v_pk_add_f32 v[180:181], v[180:181], v[184:185] neg_hi:[0,1]
	v_pk_mul_f32 v[186:187], v[116:117], v[180:181] op_sel:[1,1] op_sel_hi:[0,1]
	v_pk_fma_f32 v[116:117], v[116:117], v[180:181], v[186:187] op_sel_hi:[1,0,1] neg_lo:[0,0,1]
	s_waitcnt lgkmcnt(4)
	v_pk_add_f32 v[182:183], v[182:183], v[168:169] neg_hi:[0,1]
	v_pk_mul_f32 v[188:189], v[166:167], v[182:183] op_sel:[1,1] op_sel_hi:[0,1]
	v_pk_fma_f32 v[166:167], v[166:167], v[182:183], v[188:189] op_sel_hi:[1,0,1] neg_lo:[0,0,1]
	s_waitcnt lgkmcnt(2)
	v_pk_add_f32 v[110:111], v[110:111], v[126:127] neg_hi:[0,1]
	v_pk_mul_f32 v[186:187], v[120:121], v[110:111] op_sel:[1,1] op_sel_hi:[0,1]
	v_pk_fma_f32 v[120:121], v[120:121], v[110:111], v[186:187] op_sel_hi:[1,0,1] neg_lo:[0,0,1]
	s_waitcnt lgkmcnt(0)
	v_pk_add_f32 v[102:103], v[102:103], v[118:119] neg_hi:[0,1]
	v_pk_mul_f32 v[188:189], v[122:123], v[102:103] op_sel:[1,1] op_sel_hi:[0,1]
	v_pk_fma_f32 v[122:123], v[122:123], v[102:103], v[188:189] op_sel_hi:[1,0,1] neg_lo:[0,0,1]
	ds_read_b64 v[186:187], v200 offset:192
	ds_read_b64 v[110:111], v202 offset:56
	ds_read_b64 v[188:189], v200 offset:208
	ds_read_b64 v[102:103], v202 offset:40
	ds_read_b64 v[180:181], v200 offset:224
	ds_read_b64 v[184:185], v202 offset:24
	ds_read_b64 v[182:183], v200 offset:240
	ds_read_b64 v[168:169], v202 offset:8
	s_waitcnt lgkmcnt(6)
	v_pk_add_f32 v[186:187], v[186:187], v[110:111] neg_hi:[0,1]
	v_pk_mul_f32 v[126:127], v[124:125], v[186:187] op_sel:[1,1] op_sel_hi:[0,1]
	v_pk_fma_f32 v[124:125], v[124:125], v[186:187], v[126:127] op_sel_hi:[1,0,1] neg_lo:[0,0,1]
	s_waitcnt lgkmcnt(4)
	v_pk_add_f32 v[188:189], v[188:189], v[102:103] neg_hi:[0,1]
	v_pk_mul_f32 v[118:119], v[174:175], v[188:189] op_sel:[1,1] op_sel_hi:[0,1]
	v_pk_fma_f32 v[174:175], v[174:175], v[188:189], v[118:119] op_sel_hi:[1,0,1] neg_lo:[0,0,1]
	s_waitcnt lgkmcnt(2)
	v_pk_add_f32 v[180:181], v[180:181], v[184:185] neg_hi:[0,1]
	v_pk_mul_f32 v[126:127], v[128:129], v[180:181] op_sel:[1,1] op_sel_hi:[0,1]
	v_pk_fma_f32 v[128:129], v[128:129], v[180:181], v[126:127] op_sel_hi:[1,0,1] neg_lo:[0,0,1]
	s_waitcnt lgkmcnt(0)
	v_pk_add_f32 v[182:183], v[182:183], v[168:169] neg_hi:[0,1]
	v_pk_mul_f32 v[118:119], v[130:131], v[182:183] op_sel:[1,1] op_sel_hi:[0,1]
	v_pk_fma_f32 v[130:131], v[130:131], v[182:183], v[118:119] op_sel_hi:[1,0,1] neg_lo:[0,0,1]
	v_pk_add_f32 v[126:127], v[100:101], v[116:117]
	v_pk_add_f32 v[118:119], v[100:101], v[116:117] neg_lo:[0,1] neg_hi:[0,1]
	v_pk_add_f32 v[186:187], v[108:109], v[124:125]
	v_pk_add_f32 v[188:189], v[108:109], v[124:125] neg_lo:[0,1] neg_hi:[0,1]
	v_pk_add_f32 v[100:101], v[126:127], v[186:187]
	v_pk_add_f32 v[116:117], v[126:127], v[186:187] neg_lo:[0,1] neg_hi:[0,1]
	v_pk_add_f32 v[108:109], v[118:119], v[188:189] op_sel:[0,1] op_sel_hi:[1,0] neg_lo:[0,1]
	v_pk_add_f32 v[124:125], v[118:119], v[188:189] op_sel:[0,1] op_sel_hi:[1,0] neg_hi:[0,1]
	v_pk_add_f32 v[180:181], v[178:179], v[166:167]
	v_pk_add_f32 v[182:183], v[178:179], v[166:167] neg_lo:[0,1] neg_hi:[0,1]
	v_pk_add_f32 v[110:111], v[176:177], v[174:175]
	v_pk_add_f32 v[102:103], v[176:177], v[174:175] neg_lo:[0,1] neg_hi:[0,1]
	v_pk_add_f32 v[178:179], v[180:181], v[110:111]
	v_pk_add_f32 v[166:167], v[180:181], v[110:111] neg_lo:[0,1] neg_hi:[0,1]
	v_pk_add_f32 v[176:177], v[182:183], v[102:103] op_sel:[0,1] op_sel_hi:[1,0] neg_lo:[0,1]
	v_pk_add_f32 v[174:175], v[182:183], v[102:103] op_sel:[0,1] op_sel_hi:[1,0] neg_hi:[0,1]
	v_pk_add_f32 v[184:185], v[104:105], v[120:121]
	v_pk_add_f32 v[168:169], v[104:105], v[120:121] neg_lo:[0,1] neg_hi:[0,1]
	v_pk_add_f32 v[126:127], v[112:113], v[128:129]
	v_pk_add_f32 v[118:119], v[112:113], v[128:129] neg_lo:[0,1] neg_hi:[0,1]
	v_pk_add_f32 v[104:105], v[184:185], v[126:127]
	v_pk_add_f32 v[120:121], v[184:185], v[126:127] neg_lo:[0,1] neg_hi:[0,1]
	v_pk_add_f32 v[112:113], v[168:169], v[118:119] op_sel:[0,1] op_sel_hi:[1,0] neg_lo:[0,1]
	v_pk_add_f32 v[128:129], v[168:169], v[118:119] op_sel:[0,1] op_sel_hi:[1,0] neg_hi:[0,1]
	v_pk_add_f32 v[186:187], v[106:107], v[122:123]
	v_pk_add_f32 v[188:189], v[106:107], v[122:123] neg_lo:[0,1] neg_hi:[0,1]
	v_pk_add_f32 v[180:181], v[114:115], v[130:131]
	v_pk_add_f32 v[182:183], v[114:115], v[130:131] neg_lo:[0,1] neg_hi:[0,1]
	v_pk_add_f32 v[106:107], v[186:187], v[180:181]
; __device__ __forceinline__ f32x2 cmulc(f32x2 a, f32x2 b) { return (f32x2){a.x * b.x + a.y * b.y, a.y * b.x - a.x * b.y}; }
; template <bool INV> __device__ __forceinline__ f32x2 cmul_tw(f32x2 a, f32x2 w) { return INV ? cmulc(a, w) : cmul(a, w); }
; template <bool INV> __device__ __forceinline__ void dft16(f32x2 (&x)[16]) {
;     constexpr float C1 = 0.92387953251128674f, S1 = 0.38268343236508977f, C2 = 0.70710678118654752f;
; #pragma unroll
;     for (int b = 0; b < 4; ++b) dft4<INV>(x[b], x[4 + b], x[8 + b], x[12 + b]);
;     const f32x2 w1 = {C1, -S1}, w2 = {C2, -C2}, w3 = {S1, -C1}, w4 = {0.f, -1.f}, w6 = {-C2, -C2}, w9 = {-C1, S1};
;     x[4 * 1 + 1] = cmul_tw<INV>(x[5], w1); x[4 * 1 + 2] = cmul_tw<INV>(x[6], w2); x[4 * 1 + 3] = cmul_tw<INV>(x[7], w3);
;     x[4 * 2 + 1] = cmul_tw<INV>(x[9], w2); x[4 * 2 + 2] = cmul_tw<INV>(x[10], w4); x[4 * 2 + 3] = cmul_tw<INV>(x[11], w6);
;     x[4 * 3 + 1] = cmul_tw<INV>(x[13], w3); x[4 * 3 + 2] = cmul_tw<INV>(x[14], w6); x[4 * 3 + 3] = cmul_tw<INV>(x[15], w9);
; #pragma unroll
;     for (int c = 0; c < 4; ++c) dft4<INV>(x[4 * c], x[4 * c + 1], x[4 * c + 2], x[4 * c + 3]);
;     f32x2 y[16];
; #pragma unroll
;     for (int k = 0; k < 16; ++k) y[k] = x[4 * (k & 3) + (k >> 2)];
; #pragma unroll
;     for (int k = 0; k < 16; ++k) x[k] = y[k];
; template <int MODE> __device__ __forceinline__ void fft_pair32(LAS f32x2* B, const LAS f32x2* F, int wave, int lane) {
;     ...
;     for (int j = 0; j < 16; ++j) { const f32x2 w = {hi ? CS[j] : 1.f, hi ? -SN[j] : 0.f}; const f32x2 u = j == 0 ? v[j] : cmulc(v[j], w);
;         const auto rx = __builtin_amdgcn_permlane32_swap(__float_as_uint(u.x), __float_as_uint(u.x), false, false);
;         const auto ry = __builtin_amdgcn_permlane32_swap(__float_as_uint(u.y), __float_as_uint(u.y), false, false);
;         const f32x2 a = {__uint_as_float(rx[0]), __uint_as_float(ry[0])}, b = {__uint_as_float(rx[1]), __uint_as_float(ry[1])};
;         p[16 * hi + j] = a + b * sg; }
	v_pk_add_f32 v[122:123], v[186:187], v[180:181] neg_lo:[0,1] neg_hi:[0,1]
	v_pk_add_f32 v[114:115], v[188:189], v[182:183] op_sel:[0,1] op_sel_hi:[1,0] neg_lo:[0,1]
	v_pk_add_f32 v[130:131], v[188:189], v[182:183] op_sel:[0,1] op_sel_hi:[1,0] neg_hi:[0,1]
	v_pk_mul_f32 v[110:111], v[176:177], s[68:69] op_sel:[1,1] op_sel_hi:[0,1]
	v_pk_fma_f32 v[176:177], v[176:177], s[68:69], v[110:111] op_sel_hi:[1,0,1] neg_hi:[0,0,1]
	v_pk_mul_f32 v[102:103], v[112:113], s[84:85] op_sel:[1,1] op_sel_hi:[0,1]
	v_pk_fma_f32 v[112:113], v[112:113], s[84:85], v[102:103] op_sel_hi:[1,0,1] neg_hi:[0,0,1]
	v_pk_mul_f32 v[184:185], v[114:115], s[88:89] op_sel:[1,1] op_sel_hi:[0,1]
	v_pk_fma_f32 v[114:115], v[114:115], s[88:89], v[184:185] op_sel_hi:[1,0,1] neg_hi:[0,0,1]
	v_pk_mul_f32 v[168:169], v[166:167], s[84:85] op_sel:[1,1] op_sel_hi:[0,1]
	v_pk_fma_f32 v[166:167], v[166:167], s[84:85], v[168:169] op_sel_hi:[1,0,1] neg_hi:[0,0,1]
	v_pk_mul_f32 v[126:127], v[122:123], s[90:91] op_sel:[1,1] op_sel_hi:[0,1]
	v_pk_fma_f32 v[122:123], v[122:123], s[90:91], v[126:127] op_sel_hi:[1,0,1] neg_hi:[0,0,1]
	v_pk_mul_f32 v[118:119], v[174:175], s[88:89] op_sel:[1,1] op_sel_hi:[0,1]
	v_pk_fma_f32 v[174:175], v[174:175], s[88:89], v[118:119] op_sel_hi:[1,0,1] neg_hi:[0,0,1]
	v_pk_mul_f32 v[186:187], v[128:129], s[90:91] op_sel:[1,1] op_sel_hi:[0,1]
	v_pk_fma_f32 v[128:129], v[128:129], s[90:91], v[186:187] op_sel_hi:[1,0,1] neg_hi:[0,0,1]
	v_pk_mul_f32 v[188:189], v[130:131], s[98:99] op_sel:[1,1] op_sel_hi:[0,1]
	v_pk_fma_f32 v[130:131], v[130:131], s[98:99], v[188:189] op_sel_hi:[1,0,1] neg_hi:[0,0,1]
	v_pk_add_f32 v[180:181], v[100:101], v[104:105]
	v_pk_add_f32 v[182:183], v[100:101], v[104:105] neg_lo:[0,1] neg_hi:[0,1]
	v_pk_add_f32 v[110:111], v[178:179], v[106:107]
	v_pk_add_f32 v[102:103], v[178:179], v[106:107] neg_lo:[0,1] neg_hi:[0,1]
	v_pk_add_f32 v[100:101], v[180:181], v[110:111]
	v_pk_add_f32 v[104:105], v[180:181], v[110:111] neg_lo:[0,1] neg_hi:[0,1]
	v_pk_add_f32 v[178:179], v[182:183], v[102:103] op_sel:[0,1] op_sel_hi:[1,0] neg_lo:[0,1]
	v_pk_add_f32 v[106:107], v[182:183], v[102:103] op_sel:[0,1] op_sel_hi:[1,0] neg_hi:[0,1]
	v_pk_add_f32 v[184:185], v[108:109], v[112:113]
	v_pk_add_f32 v[168:169], v[108:109], v[112:113] neg_lo:[0,1] neg_hi:[0,1]
	v_pk_add_f32 v[126:127], v[176:177], v[114:115]
	v_pk_add_f32 v[118:119], v[176:177], v[114:115] neg_lo:[0,1] neg_hi:[0,1]
	v_pk_add_f32 v[108:109], v[184:185], v[126:127]
	v_pk_add_f32 v[112:113], v[184:185], v[126:127] neg_lo:[0,1] neg_hi:[0,1]
	v_pk_add_f32 v[176:177], v[168:169], v[118:119] op_sel:[0,1] op_sel_hi:[1,0] neg_lo:[0,1]
	v_pk_add_f32 v[114:115], v[168:169], v[118:119] op_sel:[0,1] op_sel_hi:[1,0] neg_hi:[0,1]
	v_pk_add_f32 v[186:187], v[116:117], v[120:121] op_sel:[0,1] op_sel_hi:[1,0] neg_lo:[0,1]
	v_pk_add_f32 v[188:189], v[116:117], v[120:121] op_sel:[0,1] op_sel_hi:[1,0] neg_hi:[0,1]
	v_pk_add_f32 v[180:181], v[166:167], v[122:123]
	v_pk_add_f32 v[182:183], v[166:167], v[122:123] neg_lo:[0,1] neg_hi:[0,1]
	v_pk_add_f32 v[116:117], v[186:187], v[180:181]
	v_pk_add_f32 v[120:121], v[186:187], v[180:181] neg_lo:[0,1] neg_hi:[0,1]
	v_pk_add_f32 v[166:167], v[188:189], v[182:183] op_sel:[0,1] op_sel_hi:[1,0] neg_lo:[0,1]
	v_pk_add_f32 v[122:123], v[188:189], v[182:183] op_sel:[0,1] op_sel_hi:[1,0] neg_hi:[0,1]
	v_pk_add_f32 v[110:111], v[124:125], v[128:129]
	v_pk_add_f32 v[102:103], v[124:125], v[128:129] neg_lo:[0,1] neg_hi:[0,1]
	v_pk_add_f32 v[184:185], v[174:175], v[130:131]
	v_pk_add_f32 v[168:169], v[174:175], v[130:131] neg_lo:[0,1] neg_hi:[0,1]
	v_pk_add_f32 v[124:125], v[110:111], v[184:185]
	v_pk_add_f32 v[128:129], v[110:111], v[184:185] neg_lo:[0,1] neg_hi:[0,1]
	v_pk_add_f32 v[174:175], v[102:103], v[168:169] op_sel:[0,1] op_sel_hi:[1,0] neg_lo:[0,1]
	v_pk_add_f32 v[130:131], v[102:103], v[168:169] op_sel:[0,1] op_sel_hi:[1,0] neg_hi:[0,1]
	v_mov_b32_e32 v126, v100
	v_mov_b32_e32 v127, v101
	v_pk_mul_f32 v[180:181], v[108:109], v[36:37] op_sel:[1,1] op_sel_hi:[0,1]
	v_pk_fma_f32 v[118:119], v[108:109], v[36:37], v[180:181] op_sel_hi:[1,0,1] neg_hi:[0,0,1]
	v_pk_fma_f32 v[108:109], v[108:109], v[36:37], v[180:181] op_sel_hi:[1,0,1] neg_hi:[0,0,1]
	v_pk_mul_f32 v[182:183], v[116:117], v[38:39] op_sel:[1,1] op_sel_hi:[0,1]
	v_pk_fma_f32 v[186:187], v[116:117], v[38:39], v[182:183] op_sel_hi:[1,0,1] neg_hi:[0,0,1]
	v_pk_fma_f32 v[116:117], v[116:117], v[38:39], v[182:183] op_sel_hi:[1,0,1] neg_hi:[0,0,1]
	v_pk_mul_f32 v[110:111], v[124:125], v[40:41] op_sel:[1,1] op_sel_hi:[0,1]
	v_pk_fma_f32 v[188:189], v[124:125], v[40:41], v[110:111] op_sel_hi:[1,0,1] neg_hi:[0,0,1]
	v_pk_fma_f32 v[124:125], v[124:125], v[40:41], v[110:111] op_sel_hi:[1,0,1] neg_hi:[0,0,1]
	s_nop 1
	v_permlane32_swap_b32_e32 v100, v126
	v_permlane32_swap_b32_e32 v101, v127
	v_permlane32_swap_b32_e32 v108, v118
	v_permlane32_swap_b32_e32 v109, v119
	v_permlane32_swap_b32_e32 v116, v186
	v_permlane32_swap_b32_e32 v117, v187
	v_permlane32_swap_b32_e32 v124, v188
	v_permlane32_swap_b32_e32 v125, v189
	v_pk_fma_f32 v[100:101], v[126:127], v[190:191], v[100:101] op_sel_hi:[1,0,1]
	ds_write_b64 v198, v[100:101]
	v_pk_fma_f32 v[108:109], v[118:119], v[190:191], v[108:109] op_sel_hi:[1,0,1]
	ds_write_b64 v198, v[108:109] offset:8
	v_pk_fma_f32 v[116:117], v[186:187], v[190:191], v[116:117] op_sel_hi:[1,0,1]
	ds_write_b64 v198, v[116:117] offset:16
	v_pk_fma_f32 v[124:125], v[188:189], v[190:191], v[124:125] op_sel_hi:[1,0,1]
	ds_write_b64 v198, v[124:125] offset:24
	v_pk_mul_f32 v[182:183], v[178:179], v[42:43] op_sel:[1,1] op_sel_hi:[0,1]
	v_pk_fma_f32 v[102:103], v[178:179], v[42:43], v[182:183] op_sel_hi:[1,0,1] neg_hi:[0,0,1]
; #define LAS __attribute__((address_space(3)))
; __device__ __forceinline__ f32x2 cmulc(f32x2 a, f32x2 b) { return (f32x2){a.x * b.x + a.y * b.y, a.y * b.x - a.x * b.y}; }
; __device__ __forceinline__ void fft_inv2(LAS f32x2* B, const LAS f32x2* TW2, int tid) {
;     asm volatile("" : "+v"(tid));
;     const int b = tid >> 5, n2 = tid & 31, base = 512 * b + n2; f32x2 x[16];
;     x[0] = B[fpad(base)];
; #pragma unroll
;     for (int k = 1; k < 16; ++k) x[k] = cmulc(B[fpad(base + 32 * k)], TW2[k * 32 + n2]);
; template <int MODE> __device__ __forceinline__ void fft_pair32(LAS f32x2* B, const LAS f32x2* F, int wave, int lane) {
;     ...
;     for (int j = 0; j < 16; ++j) { const f32x2 w = {hi ? CS[j] : 1.f, hi ? -SN[j] : 0.f}; const f32x2 u = j == 0 ? v[j] : cmulc(v[j], w);
;         const auto rx = __builtin_amdgcn_permlane32_swap(__float_as_uint(u.x), __float_as_uint(u.x), false, false);
;         const auto ry = __builtin_amdgcn_permlane32_swap(__float_as_uint(u.y), __float_as_uint(u.y), false, false);
;         const f32x2 a = {__uint_as_float(rx[0]), __uint_as_float(ry[0])}, b = {__uint_as_float(rx[1]), __uint_as_float(ry[1])};
;         p[16 * hi + j] = a + b * sg; }
	v_pk_fma_f32 v[178:179], v[178:179], v[42:43], v[182:183] op_sel_hi:[1,0,1] neg_hi:[0,0,1]
	v_pk_mul_f32 v[110:111], v[176:177], v[44:45] op_sel:[1,1] op_sel_hi:[0,1]
	v_pk_fma_f32 v[184:185], v[176:177], v[44:45], v[110:111] op_sel_hi:[1,0,1] neg_hi:[0,0,1]
	v_pk_fma_f32 v[176:177], v[176:177], v[44:45], v[110:111] op_sel_hi:[1,0,1] neg_hi:[0,0,1]
	v_pk_mul_f32 v[126:127], v[166:167], v[46:47] op_sel:[1,1] op_sel_hi:[0,1]
	v_pk_fma_f32 v[168:169], v[166:167], v[46:47], v[126:127] op_sel_hi:[1,0,1] neg_hi:[0,0,1]
	v_pk_fma_f32 v[166:167], v[166:167], v[46:47], v[126:127] op_sel_hi:[1,0,1] neg_hi:[0,0,1]
	v_pk_mul_f32 v[118:119], v[174:175], v[48:49] op_sel:[1,1] op_sel_hi:[0,1]
	v_pk_fma_f32 v[180:181], v[174:175], v[48:49], v[118:119] op_sel_hi:[1,0,1] neg_hi:[0,0,1]
	v_pk_fma_f32 v[174:175], v[174:175], v[48:49], v[118:119] op_sel_hi:[1,0,1] neg_hi:[0,0,1]
	s_nop 1
	v_permlane32_swap_b32_e32 v178, v102
	v_permlane32_swap_b32_e32 v179, v103
	v_permlane32_swap_b32_e32 v176, v184
	v_permlane32_swap_b32_e32 v177, v185
	v_permlane32_swap_b32_e32 v166, v168
	v_permlane32_swap_b32_e32 v167, v169
	v_permlane32_swap_b32_e32 v174, v180
	v_permlane32_swap_b32_e32 v175, v181
	v_pk_fma_f32 v[178:179], v[102:103], v[190:191], v[178:179] op_sel_hi:[1,0,1]
	ds_write_b64 v198, v[178:179] offset:32
	v_pk_fma_f32 v[176:177], v[184:185], v[190:191], v[176:177] op_sel_hi:[1,0,1]
	ds_write_b64 v198, v[176:177] offset:40
	v_pk_fma_f32 v[166:167], v[168:169], v[190:191], v[166:167] op_sel_hi:[1,0,1]
	ds_write_b64 v198, v[166:167] offset:48
	v_pk_fma_f32 v[174:175], v[180:181], v[190:191], v[174:175] op_sel_hi:[1,0,1]
	ds_write_b64 v198, v[174:175] offset:56
	v_pk_mul_f32 v[126:127], v[104:105], v[50:51] op_sel:[1,1] op_sel_hi:[0,1]
	v_pk_fma_f32 v[186:187], v[104:105], v[50:51], v[126:127] op_sel_hi:[1,0,1] neg_hi:[0,0,1]
	v_pk_fma_f32 v[104:105], v[104:105], v[50:51], v[126:127] op_sel_hi:[1,0,1] neg_hi:[0,0,1]
	v_pk_mul_f32 v[118:119], v[112:113], v[52:53] op_sel:[1,1] op_sel_hi:[0,1]
	v_pk_fma_f32 v[188:189], v[112:113], v[52:53], v[118:119] op_sel_hi:[1,0,1] neg_hi:[0,0,1]
	v_pk_fma_f32 v[112:113], v[112:113], v[52:53], v[118:119] op_sel_hi:[1,0,1] neg_hi:[0,0,1]
	v_pk_mul_f32 v[102:103], v[120:121], v[54:55] op_sel:[1,1] op_sel_hi:[0,1]
	v_pk_fma_f32 v[182:183], v[120:121], v[54:55], v[102:103] op_sel_hi:[1,0,1] neg_hi:[0,0,1]
	v_pk_fma_f32 v[120:121], v[120:121], v[54:55], v[102:103] op_sel_hi:[1,0,1] neg_hi:[0,0,1]
	v_pk_mul_f32 v[184:185], v[128:129], v[90:91] op_sel:[1,1] op_sel_hi:[0,1]
	v_pk_fma_f32 v[110:111], v[128:129], v[90:91], v[184:185] op_sel_hi:[1,0,1] neg_hi:[0,0,1]
	v_pk_fma_f32 v[128:129], v[128:129], v[90:91], v[184:185] op_sel_hi:[1,0,1] neg_hi:[0,0,1]
	s_nop 1
	v_permlane32_swap_b32_e32 v104, v186
	v_permlane32_swap_b32_e32 v105, v187
	v_permlane32_swap_b32_e32 v112, v188
	v_permlane32_swap_b32_e32 v113, v189
	v_permlane32_swap_b32_e32 v120, v182
	v_permlane32_swap_b32_e32 v121, v183
	v_permlane32_swap_b32_e32 v128, v110
	v_permlane32_swap_b32_e32 v129, v111
	v_pk_fma_f32 v[104:105], v[186:187], v[190:191], v[104:105] op_sel_hi:[1,0,1]
	ds_write_b64 v198, v[104:105] offset:64
	v_pk_fma_f32 v[112:113], v[188:189], v[190:191], v[112:113] op_sel_hi:[1,0,1]
	ds_write_b64 v198, v[112:113] offset:72
	v_pk_fma_f32 v[120:121], v[182:183], v[190:191], v[120:121] op_sel_hi:[1,0,1]
	ds_write_b64 v198, v[120:121] offset:80
	v_pk_fma_f32 v[128:129], v[110:111], v[190:191], v[128:129] op_sel_hi:[1,0,1]
	ds_write_b64 v198, v[128:129] offset:88
	v_pk_mul_f32 v[102:103], v[106:107], v[92:93] op_sel:[1,1] op_sel_hi:[0,1]
	v_pk_fma_f32 v[168:169], v[106:107], v[92:93], v[102:103] op_sel_hi:[1,0,1] neg_hi:[0,0,1]
	v_pk_fma_f32 v[106:107], v[106:107], v[92:93], v[102:103] op_sel_hi:[1,0,1] neg_hi:[0,0,1]
	v_pk_mul_f32 v[184:185], v[114:115], v[94:95] op_sel:[1,1] op_sel_hi:[0,1]
	v_pk_fma_f32 v[180:181], v[114:115], v[94:95], v[184:185] op_sel_hi:[1,0,1] neg_hi:[0,0,1]
	v_pk_fma_f32 v[114:115], v[114:115], v[94:95], v[184:185] op_sel_hi:[1,0,1] neg_hi:[0,0,1]
	v_pk_mul_f32 v[186:187], v[122:123], v[96:97] op_sel:[1,1] op_sel_hi:[0,1]
	v_pk_fma_f32 v[126:127], v[122:123], v[96:97], v[186:187] op_sel_hi:[1,0,1] neg_hi:[0,0,1]
	v_pk_fma_f32 v[122:123], v[122:123], v[96:97], v[186:187] op_sel_hi:[1,0,1] neg_hi:[0,0,1]
	v_pk_mul_f32 v[188:189], v[130:131], v[98:99] op_sel:[1,1] op_sel_hi:[0,1]
	v_pk_fma_f32 v[118:119], v[130:131], v[98:99], v[188:189] op_sel_hi:[1,0,1] neg_hi:[0,0,1]
	v_pk_fma_f32 v[130:131], v[130:131], v[98:99], v[188:189] op_sel_hi:[1,0,1] neg_hi:[0,0,1]
	s_nop 1
	v_permlane32_swap_b32_e32 v106, v168
	v_permlane32_swap_b32_e32 v107, v169
	v_permlane32_swap_b32_e32 v114, v180
	v_permlane32_swap_b32_e32 v115, v181
	v_permlane32_swap_b32_e32 v122, v126
	v_permlane32_swap_b32_e32 v123, v127
	v_permlane32_swap_b32_e32 v130, v118
	v_permlane32_swap_b32_e32 v131, v119
	v_pk_fma_f32 v[106:107], v[168:169], v[190:191], v[106:107] op_sel_hi:[1,0,1]
	ds_write_b64 v198, v[106:107] offset:96
	v_pk_fma_f32 v[114:115], v[180:181], v[190:191], v[114:115] op_sel_hi:[1,0,1]
	ds_write_b64 v198, v[114:115] offset:104
	v_pk_fma_f32 v[122:123], v[126:127], v[190:191], v[122:123] op_sel_hi:[1,0,1]
	ds_write_b64 v198, v[122:123] offset:112
	v_pk_fma_f32 v[130:131], v[118:119], v[190:191], v[130:131] op_sel_hi:[1,0,1]
	ds_write_b64 v198, v[130:131] offset:120
	s_waitcnt lgkmcnt(0)
	ds_read_b64 v[100:101], v5
	ds_read_b64 v[108:109], v5 offset:264
	ds_read_b64 v[182:183], v56 offset:256
	ds_read_b64 v[116:117], v5 offset:528
	ds_read_b64 v[110:111], v56 offset:512
	ds_read_b64 v[124:125], v5 offset:792
	ds_read_b64 v[102:103], v56 offset:768
	ds_read_b64 v[178:179], v5 offset:1056
	ds_read_b64 v[184:185], v56 offset:1024
	ds_read_b64 v[176:177], v5 offset:1320
	ds_read_b64 v[186:187], v56 offset:1280
	s_waitcnt lgkmcnt(8)
; #define LAS __attribute__((address_space(3)))
; __device__ __forceinline__ f32x2 cmulc(f32x2 a, f32x2 b) { return (f32x2){a.x * b.x + a.y * b.y, a.y * b.x - a.x * b.y}; }
; __device__ __forceinline__ void fft_inv2(LAS f32x2* B, const LAS f32x2* TW2, int tid) {
;     asm volatile("" : "+v"(tid));
;     const int b = tid >> 5, n2 = tid & 31, base = 512 * b + n2; f32x2 x[16];
;     x[0] = B[fpad(base)];
; #pragma unroll
;     for (int k = 1; k < 16; ++k) x[k] = cmulc(B[fpad(base + 32 * k)], TW2[k * 32 + n2]);
;     dft16<true>(x);
	v_pk_mul_f32 v[188:189], v[108:109], v[182:183] op_sel:[1,1] op_sel_hi:[0,1]
	v_pk_fma_f32 v[108:109], v[108:109], v[182:183], v[188:189] op_sel_hi:[1,0,1] neg_hi:[0,0,1]
	s_waitcnt lgkmcnt(6)
	v_pk_mul_f32 v[168:169], v[116:117], v[110:111] op_sel:[1,1] op_sel_hi:[0,1]
	v_pk_fma_f32 v[116:117], v[116:117], v[110:111], v[168:169] op_sel_hi:[1,0,1] neg_hi:[0,0,1]
	s_waitcnt lgkmcnt(4)
	v_pk_mul_f32 v[180:181], v[124:125], v[102:103] op_sel:[1,1] op_sel_hi:[0,1]
	v_pk_fma_f32 v[124:125], v[124:125], v[102:103], v[180:181] op_sel_hi:[1,0,1] neg_hi:[0,0,1]
	s_waitcnt lgkmcnt(2)
	v_pk_mul_f32 v[126:127], v[178:179], v[184:185] op_sel:[1,1] op_sel_hi:[0,1]
	v_pk_fma_f32 v[178:179], v[178:179], v[184:185], v[126:127] op_sel_hi:[1,0,1] neg_hi:[0,0,1]
	s_waitcnt lgkmcnt(0)
	v_pk_mul_f32 v[118:119], v[176:177], v[186:187] op_sel:[1,1] op_sel_hi:[0,1]
	v_pk_fma_f32 v[176:177], v[176:177], v[186:187], v[118:119] op_sel_hi:[1,0,1] neg_hi:[0,0,1]
	ds_read_b64 v[166:167], v5 offset:1584
	ds_read_b64 v[188:189], v56 offset:1536
	ds_read_b64 v[174:175], v5 offset:1848
	ds_read_b64 v[168:169], v56 offset:1792
	ds_read_b64 v[104:105], v5 offset:2112
	ds_read_b64 v[180:181], v56 offset:2048
	ds_read_b64 v[112:113], v5 offset:2376
	ds_read_b64 v[126:127], v56 offset:2304
	ds_read_b64 v[120:121], v5 offset:2640
	ds_read_b64 v[118:119], v56 offset:2560
	s_waitcnt lgkmcnt(8)
	v_pk_mul_f32 v[182:183], v[166:167], v[188:189] op_sel:[1,1] op_sel_hi:[0,1]
	v_pk_fma_f32 v[166:167], v[166:167], v[188:189], v[182:183] op_sel_hi:[1,0,1] neg_hi:[0,0,1]
	s_waitcnt lgkmcnt(6)
	v_pk_mul_f32 v[110:111], v[174:175], v[168:169] op_sel:[1,1] op_sel_hi:[0,1]
	v_pk_fma_f32 v[174:175], v[174:175], v[168:169], v[110:111] op_sel_hi:[1,0,1] neg_hi:[0,0,1]
	s_waitcnt lgkmcnt(4)
	v_pk_mul_f32 v[102:103], v[104:105], v[180:181] op_sel:[1,1] op_sel_hi:[0,1]
	v_pk_fma_f32 v[104:105], v[104:105], v[180:181], v[102:103] op_sel_hi:[1,0,1] neg_hi:[0,0,1]
	s_waitcnt lgkmcnt(2)
	v_pk_mul_f32 v[184:185], v[112:113], v[126:127] op_sel:[1,1] op_sel_hi:[0,1]
	v_pk_fma_f32 v[112:113], v[112:113], v[126:127], v[184:185] op_sel_hi:[1,0,1] neg_hi:[0,0,1]
	s_waitcnt lgkmcnt(0)
	v_pk_mul_f32 v[186:187], v[120:121], v[118:119] op_sel:[1,1] op_sel_hi:[0,1]
	v_pk_fma_f32 v[120:121], v[120:121], v[118:119], v[186:187] op_sel_hi:[1,0,1] neg_hi:[0,0,1]
	ds_read_b64 v[128:129], v5 offset:2904
	ds_read_b64 v[182:183], v56 offset:2816
	ds_read_b64 v[106:107], v5 offset:3168
	ds_read_b64 v[110:111], v56 offset:3072
	ds_read_b64 v[114:115], v5 offset:3432
	ds_read_b64 v[102:103], v56 offset:3328
	ds_read_b64 v[122:123], v5 offset:3696
	ds_read_b64 v[184:185], v56 offset:3584
	ds_read_b64 v[130:131], v5 offset:3960
	ds_read_b64 v[186:187], v56 offset:3840
	s_waitcnt lgkmcnt(8)
	v_pk_mul_f32 v[188:189], v[128:129], v[182:183] op_sel:[1,1] op_sel_hi:[0,1]
	v_pk_fma_f32 v[128:129], v[128:129], v[182:183], v[188:189] op_sel_hi:[1,0,1] neg_hi:[0,0,1]
	s_waitcnt lgkmcnt(6)
	v_pk_mul_f32 v[168:169], v[106:107], v[110:111] op_sel:[1,1] op_sel_hi:[0,1]
	v_pk_fma_f32 v[106:107], v[106:107], v[110:111], v[168:169] op_sel_hi:[1,0,1] neg_hi:[0,0,1]
	s_waitcnt lgkmcnt(4)
	v_pk_mul_f32 v[180:181], v[114:115], v[102:103] op_sel:[1,1] op_sel_hi:[0,1]
	v_pk_fma_f32 v[114:115], v[114:115], v[102:103], v[180:181] op_sel_hi:[1,0,1] neg_hi:[0,0,1]
	s_waitcnt lgkmcnt(2)
	v_pk_mul_f32 v[126:127], v[122:123], v[184:185] op_sel:[1,1] op_sel_hi:[0,1]
	v_pk_fma_f32 v[122:123], v[122:123], v[184:185], v[126:127] op_sel_hi:[1,0,1] neg_hi:[0,0,1]
	s_waitcnt lgkmcnt(0)
	v_pk_mul_f32 v[118:119], v[130:131], v[186:187] op_sel:[1,1] op_sel_hi:[0,1]
	v_pk_fma_f32 v[130:131], v[130:131], v[186:187], v[118:119] op_sel_hi:[1,0,1] neg_hi:[0,0,1]
	v_pk_add_f32 v[188:189], v[100:101], v[104:105]
	v_pk_add_f32 v[168:169], v[100:101], v[104:105] neg_lo:[0,1] neg_hi:[0,1]
	v_pk_add_f32 v[180:181], v[178:179], v[106:107]
	v_pk_add_f32 v[126:127], v[178:179], v[106:107] neg_lo:[0,1] neg_hi:[0,1]
	v_pk_add_f32 v[100:101], v[188:189], v[180:181]
	v_pk_add_f32 v[104:105], v[188:189], v[180:181] neg_lo:[0,1] neg_hi:[0,1]
	v_pk_add_f32 v[178:179], v[168:169], v[126:127] op_sel:[0,1] op_sel_hi:[1,0] neg_lo:[0,1]
	v_pk_add_f32 v[106:107], v[168:169], v[126:127] op_sel:[0,1] op_sel_hi:[1,0] neg_hi:[0,1]
	v_pk_add_f32 v[118:119], v[108:109], v[112:113]
	v_pk_add_f32 v[182:183], v[108:109], v[112:113] neg_lo:[0,1] neg_hi:[0,1]
	v_pk_add_f32 v[110:111], v[176:177], v[114:115]
	v_pk_add_f32 v[102:103], v[176:177], v[114:115] neg_lo:[0,1] neg_hi:[0,1]
	v_pk_add_f32 v[108:109], v[118:119], v[110:111]
	v_pk_add_f32 v[112:113], v[118:119], v[110:111] neg_lo:[0,1] neg_hi:[0,1]
	v_pk_add_f32 v[176:177], v[182:183], v[102:103] op_sel:[0,1] op_sel_hi:[1,0] neg_lo:[0,1]
	v_pk_add_f32 v[114:115], v[182:183], v[102:103] op_sel:[0,1] op_sel_hi:[1,0] neg_hi:[0,1]
	v_pk_add_f32 v[184:185], v[116:117], v[120:121]
	v_pk_add_f32 v[186:187], v[116:117], v[120:121] neg_lo:[0,1] neg_hi:[0,1]
	v_pk_add_f32 v[188:189], v[166:167], v[122:123]
	v_pk_add_f32 v[168:169], v[166:167], v[122:123] neg_lo:[0,1] neg_hi:[0,1]
	v_pk_add_f32 v[116:117], v[184:185], v[188:189]
	v_pk_add_f32 v[120:121], v[184:185], v[188:189] neg_lo:[0,1] neg_hi:[0,1]
	v_pk_add_f32 v[166:167], v[186:187], v[168:169] op_sel:[0,1] op_sel_hi:[1,0] neg_lo:[0,1]
	v_pk_add_f32 v[122:123], v[186:187], v[168:169] op_sel:[0,1] op_sel_hi:[1,0] neg_hi:[0,1]
	v_pk_add_f32 v[180:181], v[124:125], v[128:129]
	v_pk_add_f32 v[126:127], v[124:125], v[128:129] neg_lo:[0,1] neg_hi:[0,1]
	v_pk_add_f32 v[118:119], v[174:175], v[130:131]
	v_pk_add_f32 v[182:183], v[174:175], v[130:131] neg_lo:[0,1] neg_hi:[0,1]
	v_pk_add_f32 v[124:125], v[180:181], v[118:119]
; template <bool INV> __device__ __forceinline__ f32x2 cmul_tw(f32x2 a, f32x2 w) { return INV ? cmulc(a, w) : cmul(a, w); }
; #define WG_SYNC() do { asm volatile("s_waitcnt lgkmcnt(0)" ::: "memory"); __builtin_amdgcn_s_barrier(); asm volatile("" ::: "memory"); } while (0)
; template <bool INV> __device__ __forceinline__ void dft16(f32x2 (&x)[16]) {
;     constexpr float C1 = 0.92387953251128674f, S1 = 0.38268343236508977f, C2 = 0.70710678118654752f;
; #pragma unroll
;     for (int b = 0; b < 4; ++b) dft4<INV>(x[b], x[4 + b], x[8 + b], x[12 + b]);
;     const f32x2 w1 = {C1, -S1}, w2 = {C2, -C2}, w3 = {S1, -C1}, w4 = {0.f, -1.f}, w6 = {-C2, -C2}, w9 = {-C1, S1};
;     x[4 * 1 + 1] = cmul_tw<INV>(x[5], w1); x[4 * 1 + 2] = cmul_tw<INV>(x[6], w2); x[4 * 1 + 3] = cmul_tw<INV>(x[7], w3);
;     x[4 * 2 + 1] = cmul_tw<INV>(x[9], w2); x[4 * 2 + 2] = cmul_tw<INV>(x[10], w4); x[4 * 2 + 3] = cmul_tw<INV>(x[11], w6);
;     x[4 * 3 + 1] = cmul_tw<INV>(x[13], w3); x[4 * 3 + 2] = cmul_tw<INV>(x[14], w6); x[4 * 3 + 3] = cmul_tw<INV>(x[15], w9);
; #pragma unroll
;     for (int c = 0; c < 4; ++c) dft4<INV>(x[4 * c], x[4 * c + 1], x[4 * c + 2], x[4 * c + 3]);
;     f32x2 y[16];
; #pragma unroll
;     for (int k = 0; k < 16; ++k) y[k] = x[4 * (k & 3) + (k >> 2)];
; #pragma unroll
;     for (int k = 0; k < 16; ++k) x[k] = y[k];
; }
; __device__ __forceinline__ void fft_inv2(LAS f32x2* B, const LAS f32x2* TW2, int tid) {
;     ...
;     for (int r = 0; r < 16; ++r) B[fpad(base + 32 * r)] = x[r];
; __device__ __forceinline__ void hyena_fft(LAS unsigned char* lds, int layer, int G, const int wave_s) {
;     ...
;             WG_SYNC(); fft_inv1(x, Db, n2, w1p);
	v_pk_add_f32 v[128:129], v[180:181], v[118:119] neg_lo:[0,1] neg_hi:[0,1]
	v_pk_add_f32 v[174:175], v[126:127], v[182:183] op_sel:[0,1] op_sel_hi:[1,0] neg_lo:[0,1]
	v_pk_add_f32 v[130:131], v[126:127], v[182:183] op_sel:[0,1] op_sel_hi:[1,0] neg_hi:[0,1]
	v_pk_mul_f32 v[110:111], v[176:177], s[68:69] op_sel:[1,1] op_sel_hi:[0,1]
	v_pk_fma_f32 v[176:177], v[176:177], s[68:69], v[110:111] op_sel_hi:[1,0,1] neg_hi:[0,0,1]
	v_pk_mul_f32 v[102:103], v[166:167], s[84:85] op_sel:[1,1] op_sel_hi:[0,1]
	v_pk_fma_f32 v[166:167], v[166:167], s[84:85], v[102:103] op_sel_hi:[1,0,1] neg_hi:[0,0,1]
	v_pk_mul_f32 v[184:185], v[174:175], s[88:89] op_sel:[1,1] op_sel_hi:[0,1]
	v_pk_fma_f32 v[174:175], v[174:175], s[88:89], v[184:185] op_sel_hi:[1,0,1] neg_hi:[0,0,1]
	v_pk_mul_f32 v[186:187], v[112:113], s[84:85] op_sel:[1,1] op_sel_hi:[0,1]
	v_pk_fma_f32 v[112:113], v[112:113], s[84:85], v[186:187] op_sel_hi:[1,0,1] neg_hi:[0,0,1]
	v_pk_mul_f32 v[188:189], v[128:129], s[90:91] op_sel:[1,1] op_sel_hi:[0,1]
	v_pk_fma_f32 v[128:129], v[128:129], s[90:91], v[188:189] op_sel_hi:[1,0,1] neg_hi:[0,0,1]
	v_pk_mul_f32 v[168:169], v[114:115], s[88:89] op_sel:[1,1] op_sel_hi:[0,1]
	v_pk_fma_f32 v[114:115], v[114:115], s[88:89], v[168:169] op_sel_hi:[1,0,1] neg_hi:[0,0,1]
	v_pk_mul_f32 v[180:181], v[122:123], s[90:91] op_sel:[1,1] op_sel_hi:[0,1]
	v_pk_fma_f32 v[122:123], v[122:123], s[90:91], v[180:181] op_sel_hi:[1,0,1] neg_hi:[0,0,1]
	v_pk_mul_f32 v[126:127], v[130:131], s[98:99] op_sel:[1,1] op_sel_hi:[0,1]
	v_pk_fma_f32 v[130:131], v[130:131], s[98:99], v[126:127] op_sel_hi:[1,0,1] neg_hi:[0,0,1]
	v_pk_add_f32 v[118:119], v[100:101], v[116:117]
	v_pk_add_f32 v[182:183], v[100:101], v[116:117] neg_lo:[0,1] neg_hi:[0,1]
	v_pk_add_f32 v[110:111], v[108:109], v[124:125]
	v_pk_add_f32 v[102:103], v[108:109], v[124:125] neg_lo:[0,1] neg_hi:[0,1]
	v_pk_add_f32 v[100:101], v[118:119], v[110:111]
	v_pk_add_f32 v[116:117], v[118:119], v[110:111] neg_lo:[0,1] neg_hi:[0,1]
	v_pk_add_f32 v[108:109], v[182:183], v[102:103] op_sel:[0,1] op_sel_hi:[1,0] neg_lo:[0,1]
	v_pk_add_f32 v[124:125], v[182:183], v[102:103] op_sel:[0,1] op_sel_hi:[1,0] neg_hi:[0,1]
	v_pk_add_f32 v[184:185], v[178:179], v[166:167]
	v_pk_add_f32 v[186:187], v[178:179], v[166:167] neg_lo:[0,1] neg_hi:[0,1]
	v_pk_add_f32 v[188:189], v[176:177], v[174:175]
	v_pk_add_f32 v[168:169], v[176:177], v[174:175] neg_lo:[0,1] neg_hi:[0,1]
	v_pk_add_f32 v[178:179], v[184:185], v[188:189]
	v_pk_add_f32 v[166:167], v[184:185], v[188:189] neg_lo:[0,1] neg_hi:[0,1]
	v_pk_add_f32 v[176:177], v[186:187], v[168:169] op_sel:[0,1] op_sel_hi:[1,0] neg_lo:[0,1]
	v_pk_add_f32 v[174:175], v[186:187], v[168:169] op_sel:[0,1] op_sel_hi:[1,0] neg_hi:[0,1]
	v_pk_add_f32 v[180:181], v[104:105], v[120:121] op_sel:[0,1] op_sel_hi:[1,0] neg_lo:[0,1]
	v_pk_add_f32 v[126:127], v[104:105], v[120:121] op_sel:[0,1] op_sel_hi:[1,0] neg_hi:[0,1]
	v_pk_add_f32 v[118:119], v[112:113], v[128:129]
	v_pk_add_f32 v[182:183], v[112:113], v[128:129] neg_lo:[0,1] neg_hi:[0,1]
	v_pk_add_f32 v[104:105], v[180:181], v[118:119]
	v_pk_add_f32 v[120:121], v[180:181], v[118:119] neg_lo:[0,1] neg_hi:[0,1]
	v_pk_add_f32 v[112:113], v[126:127], v[182:183] op_sel:[0,1] op_sel_hi:[1,0] neg_lo:[0,1]
	v_pk_add_f32 v[128:129], v[126:127], v[182:183] op_sel:[0,1] op_sel_hi:[1,0] neg_hi:[0,1]
	v_pk_add_f32 v[110:111], v[106:107], v[122:123]
	v_pk_add_f32 v[102:103], v[106:107], v[122:123] neg_lo:[0,1] neg_hi:[0,1]
	v_pk_add_f32 v[184:185], v[114:115], v[130:131]
	v_pk_add_f32 v[186:187], v[114:115], v[130:131] neg_lo:[0,1] neg_hi:[0,1]
	v_pk_add_f32 v[106:107], v[110:111], v[184:185]
	v_pk_add_f32 v[122:123], v[110:111], v[184:185] neg_lo:[0,1] neg_hi:[0,1]
	v_pk_add_f32 v[114:115], v[102:103], v[186:187] op_sel:[0,1] op_sel_hi:[1,0] neg_lo:[0,1]
	v_pk_add_f32 v[130:131], v[102:103], v[186:187] op_sel:[0,1] op_sel_hi:[1,0] neg_hi:[0,1]
	ds_write_b64 v5, v[100:101]
	ds_write_b64 v5, v[178:179] offset:264
	ds_write_b64 v5, v[104:105] offset:528
	ds_write_b64 v5, v[106:107] offset:792
	ds_write_b64 v5, v[108:109] offset:1056
	ds_write_b64 v5, v[176:177] offset:1320
	ds_write_b64 v5, v[112:113] offset:1584
	ds_write_b64 v5, v[114:115] offset:1848
	ds_write_b64 v5, v[116:117] offset:2112
	ds_write_b64 v5, v[166:167] offset:2376
	ds_write_b64 v5, v[120:121] offset:2640
	ds_write_b64 v5, v[122:123] offset:2904
	ds_write_b64 v5, v[124:125] offset:3168
	ds_write_b64 v5, v[174:175] offset:3432
	ds_write_b64 v5, v[128:129] offset:3696
	ds_write_b64 v5, v[130:131] offset:3960
	s_waitcnt lgkmcnt(0)
	s_barrier
; #define LAS __attribute__((address_space(3)))
; __device__ __forceinline__ f32x2 cmulc(f32x2 a, f32x2 b) { return (f32x2){a.x * b.x + a.y * b.y, a.y * b.x - a.x * b.y}; }
; __device__ __forceinline__ void dft16_inv_lo(f32x2 (&x)[16]) {
;     constexpr float C1 = 0.92387953251128674f, S1 = 0.38268343236508977f, C2 = 0.70710678118654752f;
; #pragma unroll
;     for (int b = 0; b < 4; ++b) dft4<true>(x[b], x[4 + b], x[8 + b], x[12 + b]);
;     const f32x2 w1 = {C1, -S1}, w2 = {C2, -C2}, w3 = {S1, -C1}, w4 = {0.f, -1.f}, w6 = {-C2, -C2}, w9 = {-C1, S1};
;     x[5] = cmulc(x[5], w1); x[6] = cmulc(x[6], w2); x[7] = cmulc(x[7], w3);
;     x[9] = cmulc(x[9], w2); x[10] = cmulc(x[10], w4); x[11] = cmulc(x[11], w6);
;     x[13] = cmulc(x[13], w3); x[14] = cmulc(x[14], w6); x[15] = cmulc(x[15], w9);
; __device__ __forceinline__ void fft_inv1(f32x2 (&x)[16], const LAS f32x2* B, int n2, const f32x2 (&w)[16]) {
;     asm volatile("" : "+v"(n2));
;     x[0] = B[fpad(n2)];
; #pragma unroll
;     for (int k = 1; k < 16; ++k) x[k] = cmulc(B[fpad(512 * k + n2)], w[k]);
;     dft16_inv_lo(x);
	ds_read_b64 v[100:101], v3
	ds_read_b64 v[108:109], v3 offset:16896
	ds_read_b64 v[116:117], v3 offset:33792
	ds_read_b64 v[124:125], v3 offset:50688
	ds_read_b64 v[178:179], v3 offset:4224
	ds_read_b64 v[176:177], v3 offset:21120
	ds_read_b64 v[166:167], v3 offset:38016
	ds_read_b64 v[174:175], v3 offset:54912
	ds_read_b64 v[104:105], v3 offset:8448
	ds_read_b64 v[112:113], v3 offset:25344
	ds_read_b64 v[120:121], v3 offset:42240
	ds_read_b64 v[128:129], v3 offset:59136
	ds_read_b64 v[106:107], v3 offset:12672
	ds_read_b64 v[114:115], v3 offset:29568
	ds_read_b64 v[122:123], v3 offset:46464
	ds_read_b64 v[130:131], v3 offset:63360
	s_waitcnt lgkmcnt(14)
	v_pk_mul_f32 v[188:189], v[108:109], v[12:13] op_sel:[1,1] op_sel_hi:[0,1]
	v_pk_fma_f32 v[108:109], v[108:109], v[12:13], v[188:189] op_sel_hi:[1,0,1] neg_hi:[0,0,1]
	s_waitcnt lgkmcnt(13)
	v_pk_mul_f32 v[168:169], v[116:117], v[20:21] op_sel:[1,1] op_sel_hi:[0,1]
	v_pk_fma_f32 v[116:117], v[116:117], v[20:21], v[168:169] op_sel_hi:[1,0,1] neg_hi:[0,0,1]
	s_waitcnt lgkmcnt(12)
	v_pk_mul_f32 v[180:181], v[124:125], v[28:29] op_sel:[1,1] op_sel_hi:[0,1]
	v_pk_fma_f32 v[124:125], v[124:125], v[28:29], v[180:181] op_sel_hi:[1,0,1] neg_hi:[0,0,1]
	s_waitcnt lgkmcnt(11)
	v_pk_mul_f32 v[126:127], v[178:179], v[6:7] op_sel:[1,1] op_sel_hi:[0,1]
	v_pk_fma_f32 v[178:179], v[178:179], v[6:7], v[126:127] op_sel_hi:[1,0,1] neg_hi:[0,0,1]
	s_waitcnt lgkmcnt(10)
	v_pk_mul_f32 v[118:119], v[176:177], v[14:15] op_sel:[1,1] op_sel_hi:[0,1]
	v_pk_fma_f32 v[176:177], v[176:177], v[14:15], v[118:119] op_sel_hi:[1,0,1] neg_hi:[0,0,1]
	s_waitcnt lgkmcnt(9)
	v_pk_mul_f32 v[182:183], v[166:167], v[22:23] op_sel:[1,1] op_sel_hi:[0,1]
	v_pk_fma_f32 v[166:167], v[166:167], v[22:23], v[182:183] op_sel_hi:[1,0,1] neg_hi:[0,0,1]
	s_waitcnt lgkmcnt(8)
	v_pk_mul_f32 v[110:111], v[174:175], v[30:31] op_sel:[1,1] op_sel_hi:[0,1]
	v_pk_fma_f32 v[174:175], v[174:175], v[30:31], v[110:111] op_sel_hi:[1,0,1] neg_hi:[0,0,1]
	s_waitcnt lgkmcnt(7)
	v_pk_mul_f32 v[102:103], v[104:105], v[8:9] op_sel:[1,1] op_sel_hi:[0,1]
	v_pk_fma_f32 v[104:105], v[104:105], v[8:9], v[102:103] op_sel_hi:[1,0,1] neg_hi:[0,0,1]
	s_waitcnt lgkmcnt(6)
	v_pk_mul_f32 v[184:185], v[112:113], v[16:17] op_sel:[1,1] op_sel_hi:[0,1]
	v_pk_fma_f32 v[112:113], v[112:113], v[16:17], v[184:185] op_sel_hi:[1,0,1] neg_hi:[0,0,1]
	s_waitcnt lgkmcnt(5)
	v_pk_mul_f32 v[186:187], v[120:121], v[24:25] op_sel:[1,1] op_sel_hi:[0,1]
	v_pk_fma_f32 v[120:121], v[120:121], v[24:25], v[186:187] op_sel_hi:[1,0,1] neg_hi:[0,0,1]
	s_waitcnt lgkmcnt(4)
	v_pk_mul_f32 v[188:189], v[128:129], v[32:33] op_sel:[1,1] op_sel_hi:[0,1]
	v_pk_fma_f32 v[128:129], v[128:129], v[32:33], v[188:189] op_sel_hi:[1,0,1] neg_hi:[0,0,1]
	s_waitcnt lgkmcnt(3)
	v_pk_mul_f32 v[168:169], v[106:107], v[10:11] op_sel:[1,1] op_sel_hi:[0,1]
	v_pk_fma_f32 v[106:107], v[106:107], v[10:11], v[168:169] op_sel_hi:[1,0,1] neg_hi:[0,0,1]
	s_waitcnt lgkmcnt(2)
	v_pk_mul_f32 v[180:181], v[114:115], v[18:19] op_sel:[1,1] op_sel_hi:[0,1]
	v_pk_fma_f32 v[114:115], v[114:115], v[18:19], v[180:181] op_sel_hi:[1,0,1] neg_hi:[0,0,1]
	s_waitcnt lgkmcnt(1)
	v_pk_mul_f32 v[126:127], v[122:123], v[26:27] op_sel:[1,1] op_sel_hi:[0,1]
	v_pk_fma_f32 v[122:123], v[122:123], v[26:27], v[126:127] op_sel_hi:[1,0,1] neg_hi:[0,0,1]
	s_waitcnt lgkmcnt(0)
	v_pk_mul_f32 v[118:119], v[130:131], v[34:35] op_sel:[1,1] op_sel_hi:[0,1]
	v_pk_fma_f32 v[130:131], v[130:131], v[34:35], v[118:119] op_sel_hi:[1,0,1] neg_hi:[0,0,1]
	v_pk_add_f32 v[182:183], v[100:101], v[116:117]
	v_pk_add_f32 v[110:111], v[100:101], v[116:117] neg_lo:[0,1] neg_hi:[0,1]
	v_pk_add_f32 v[102:103], v[108:109], v[124:125]
	v_pk_add_f32 v[184:185], v[108:109], v[124:125] neg_lo:[0,1] neg_hi:[0,1]
	v_pk_add_f32 v[100:101], v[182:183], v[102:103]
	v_pk_add_f32 v[116:117], v[182:183], v[102:103] neg_lo:[0,1] neg_hi:[0,1]
	v_pk_add_f32 v[108:109], v[110:111], v[184:185] op_sel:[0,1] op_sel_hi:[1,0] neg_lo:[0,1]
	v_pk_add_f32 v[124:125], v[110:111], v[184:185] op_sel:[0,1] op_sel_hi:[1,0] neg_hi:[0,1]
	v_pk_add_f32 v[186:187], v[178:179], v[166:167]
	v_pk_add_f32 v[188:189], v[178:179], v[166:167] neg_lo:[0,1] neg_hi:[0,1]
	v_pk_add_f32 v[168:169], v[176:177], v[174:175]
	v_pk_add_f32 v[180:181], v[176:177], v[174:175] neg_lo:[0,1] neg_hi:[0,1]
	v_pk_add_f32 v[178:179], v[186:187], v[168:169]
	v_pk_add_f32 v[166:167], v[186:187], v[168:169] neg_lo:[0,1] neg_hi:[0,1]
	v_pk_add_f32 v[176:177], v[188:189], v[180:181] op_sel:[0,1] op_sel_hi:[1,0] neg_lo:[0,1]
	v_pk_add_f32 v[174:175], v[188:189], v[180:181] op_sel:[0,1] op_sel_hi:[1,0] neg_hi:[0,1]
	v_pk_add_f32 v[126:127], v[104:105], v[120:121]
	v_pk_add_f32 v[118:119], v[104:105], v[120:121] neg_lo:[0,1] neg_hi:[0,1]
	v_pk_add_f32 v[182:183], v[112:113], v[128:129]
	v_pk_add_f32 v[110:111], v[112:113], v[128:129] neg_lo:[0,1] neg_hi:[0,1]
	v_pk_add_f32 v[104:105], v[126:127], v[182:183]
	v_pk_add_f32 v[120:121], v[126:127], v[182:183] neg_lo:[0,1] neg_hi:[0,1]
	v_pk_add_f32 v[112:113], v[118:119], v[110:111] op_sel:[0,1] op_sel_hi:[1,0] neg_lo:[0,1]
	v_pk_add_f32 v[128:129], v[118:119], v[110:111] op_sel:[0,1] op_sel_hi:[1,0] neg_hi:[0,1]
	v_pk_add_f32 v[102:103], v[106:107], v[122:123]
	v_pk_add_f32 v[184:185], v[106:107], v[122:123] neg_lo:[0,1] neg_hi:[0,1]
	v_pk_add_f32 v[186:187], v[114:115], v[130:131]
	v_pk_add_f32 v[188:189], v[114:115], v[130:131] neg_lo:[0,1] neg_hi:[0,1]
	v_pk_add_f32 v[106:107], v[102:103], v[186:187]
	v_pk_add_f32 v[122:123], v[102:103], v[186:187] neg_lo:[0,1] neg_hi:[0,1]
	v_pk_add_f32 v[114:115], v[184:185], v[188:189] op_sel:[0,1] op_sel_hi:[1,0] neg_lo:[0,1]
; #define LAS __attribute__((address_space(3)))
; #define WG_SYNC() do { asm volatile("s_waitcnt lgkmcnt(0)" ::: "memory"); __builtin_amdgcn_s_barrier(); asm volatile("" ::: "memory"); } while (0)
; __device__ __forceinline__ void dft16_inv_lo(f32x2 (&x)[16]) {
;     ...
;     f32x2 y[8];
; #pragma unroll
;     for (int c = 0; c < 4; ++c) { const f32x2 t0 = x[4 * c] + x[4 * c + 2], t1 = x[4 * c] - x[4 * c + 2], t2 = x[4 * c + 1] + x[4 * c + 3], t3 = x[4 * c + 1] - x[4 * c + 3];
;         y[c] = t0 + t2; y[4 + c] = t1 + (f32x2){-t3.y, t3.x}; }
; #pragma unroll
;     for (int k = 0; k < 8; ++k) x[k] = y[k];
; __device__ __forceinline__ void hy_stage(LAS float* plane, const bf16_t* PHY, int cg, int jc, int tid) {
;     ...
;     for (int k = 0; k < 8; ++k) { const int i = tid + 512 * k; const u32x4 v = src[i];
;         const unsigned w0 = (jc & 2) ? v.y : v.x, w1 = (jc & 2) ? v.w : v.z;
;         f32x2 o; o.x = (jc & 1) ? bf_hi(w0) : bf_lo(w0); o.y = (jc & 1) ? bf_hi(w1) : bf_lo(w1);
;         *(LAS f32x2*)(plane + 2 * i) = o; }
; __device__ __forceinline__ void hyena_fft(LAS unsigned char* lds, int layer, int G, const int wave_s) {
;     ...
;             { const float fb0 = fbias[c];
; #pragma unroll
;               for (int r = 0; r < 8; ++r) { uz[r][0] = ux[r][0] * (x[r].x + fb0 * uz[r][0]); uz[r][1] = ux[r][1] * (x[r].y + fb0 * uz[r][1]); } }
;             WG_SYNC();
;             hy_stage(pl0, PHY, (HY / 4) + unit, jc, tid);
;             WG_SYNC();
	v_pk_add_f32 v[130:131], v[184:185], v[188:189] op_sel:[0,1] op_sel_hi:[1,0] neg_hi:[0,1]
	v_pk_mul_f32 v[168:169], v[176:177], s[68:69] op_sel:[1,1] op_sel_hi:[0,1]
	v_pk_fma_f32 v[176:177], v[176:177], s[68:69], v[168:169] op_sel_hi:[1,0,1] neg_hi:[0,0,1]
	v_pk_mul_f32 v[180:181], v[112:113], s[84:85] op_sel:[1,1] op_sel_hi:[0,1]
	v_pk_fma_f32 v[112:113], v[112:113], s[84:85], v[180:181] op_sel_hi:[1,0,1] neg_hi:[0,0,1]
	v_pk_mul_f32 v[126:127], v[114:115], s[88:89] op_sel:[1,1] op_sel_hi:[0,1]
	v_pk_fma_f32 v[114:115], v[114:115], s[88:89], v[126:127] op_sel_hi:[1,0,1] neg_hi:[0,0,1]
	v_pk_mul_f32 v[118:119], v[166:167], s[84:85] op_sel:[1,1] op_sel_hi:[0,1]
	v_pk_fma_f32 v[166:167], v[166:167], s[84:85], v[118:119] op_sel_hi:[1,0,1] neg_hi:[0,0,1]
	v_pk_mul_f32 v[182:183], v[122:123], s[90:91] op_sel:[1,1] op_sel_hi:[0,1]
	v_pk_fma_f32 v[122:123], v[122:123], s[90:91], v[182:183] op_sel_hi:[1,0,1] neg_hi:[0,0,1]
	v_pk_mul_f32 v[110:111], v[174:175], s[88:89] op_sel:[1,1] op_sel_hi:[0,1]
	v_pk_fma_f32 v[174:175], v[174:175], s[88:89], v[110:111] op_sel_hi:[1,0,1] neg_hi:[0,0,1]
	v_pk_mul_f32 v[102:103], v[128:129], s[90:91] op_sel:[1,1] op_sel_hi:[0,1]
	v_pk_fma_f32 v[128:129], v[128:129], s[90:91], v[102:103] op_sel_hi:[1,0,1] neg_hi:[0,0,1]
	v_pk_mul_f32 v[184:185], v[130:131], s[98:99] op_sel:[1,1] op_sel_hi:[0,1]
	v_pk_fma_f32 v[130:131], v[130:131], s[98:99], v[184:185] op_sel_hi:[1,0,1] neg_hi:[0,0,1]
	v_pk_add_f32 v[186:187], v[100:101], v[104:105]
	v_pk_add_f32 v[188:189], v[100:101], v[104:105] neg_lo:[0,1] neg_hi:[0,1]
	v_pk_add_f32 v[168:169], v[178:179], v[106:107]
	v_pk_add_f32 v[180:181], v[178:179], v[106:107] neg_lo:[0,1] neg_hi:[0,1]
	v_pk_add_f32 v[100:101], v[186:187], v[168:169]
	v_pk_add_f32 v[178:179], v[188:189], v[180:181] op_sel:[0,1] op_sel_hi:[1,0] neg_lo:[0,1]
	v_pk_add_f32 v[126:127], v[108:109], v[112:113]
	v_pk_add_f32 v[118:119], v[108:109], v[112:113] neg_lo:[0,1] neg_hi:[0,1]
	v_pk_add_f32 v[182:183], v[176:177], v[114:115]
	v_pk_add_f32 v[110:111], v[176:177], v[114:115] neg_lo:[0,1] neg_hi:[0,1]
	v_pk_add_f32 v[108:109], v[126:127], v[182:183]
	v_pk_add_f32 v[176:177], v[118:119], v[110:111] op_sel:[0,1] op_sel_hi:[1,0] neg_lo:[0,1]
	v_pk_add_f32 v[102:103], v[116:117], v[120:121] op_sel:[0,1] op_sel_hi:[1,0] neg_lo:[0,1]
	v_pk_add_f32 v[184:185], v[116:117], v[120:121] op_sel:[0,1] op_sel_hi:[1,0] neg_hi:[0,1]
	v_pk_add_f32 v[186:187], v[166:167], v[122:123]
	v_pk_add_f32 v[188:189], v[166:167], v[122:123] neg_lo:[0,1] neg_hi:[0,1]
	v_pk_add_f32 v[116:117], v[102:103], v[186:187]
	v_pk_add_f32 v[166:167], v[184:185], v[188:189] op_sel:[0,1] op_sel_hi:[1,0] neg_lo:[0,1]
	v_pk_add_f32 v[168:169], v[124:125], v[128:129]
	v_pk_add_f32 v[180:181], v[124:125], v[128:129] neg_lo:[0,1] neg_hi:[0,1]
	v_pk_add_f32 v[126:127], v[174:175], v[130:131]
	v_pk_add_f32 v[118:119], v[174:175], v[130:131] neg_lo:[0,1] neg_hi:[0,1]
	v_pk_add_f32 v[124:125], v[168:169], v[126:127]
	v_pk_add_f32 v[174:175], v[180:181], v[118:119] op_sel:[0,1] op_sel_hi:[1,0] neg_lo:[0,1]
	s_load_dword s35, s[50:51], 0x0
	s_waitcnt lgkmcnt(0)
	v_mov_b32_e32 v194, s35
	v_pk_fma_f32 v[182:183], v[132:133], v[194:195], v[100:101] op_sel_hi:[1,0,1]
	v_pk_mul_f32 v[132:133], v[148:149], v[182:183]
	v_pk_fma_f32 v[110:111], v[134:135], v[194:195], v[108:109] op_sel_hi:[1,0,1]
	v_pk_mul_f32 v[134:135], v[150:151], v[110:111]
	v_pk_fma_f32 v[102:103], v[136:137], v[194:195], v[116:117] op_sel_hi:[1,0,1]
	v_pk_mul_f32 v[136:137], v[152:153], v[102:103]
	v_pk_fma_f32 v[184:185], v[138:139], v[194:195], v[124:125] op_sel_hi:[1,0,1]
	v_pk_mul_f32 v[138:139], v[154:155], v[184:185]
	v_pk_fma_f32 v[186:187], v[140:141], v[194:195], v[178:179] op_sel_hi:[1,0,1]
	v_pk_mul_f32 v[140:141], v[158:159], v[186:187]
	v_pk_fma_f32 v[188:189], v[142:143], v[194:195], v[176:177] op_sel_hi:[1,0,1]
	v_pk_mul_f32 v[142:143], v[160:161], v[188:189]
	v_pk_fma_f32 v[168:169], v[144:145], v[194:195], v[166:167] op_sel_hi:[1,0,1]
	v_pk_mul_f32 v[144:145], v[162:163], v[168:169]
	v_pk_fma_f32 v[180:181], v[146:147], v[194:195], v[174:175] op_sel_hi:[1,0,1]
	v_pk_mul_f32 v[146:147], v[164:165], v[180:181]
	s_waitcnt lgkmcnt(0)
	s_barrier
	s_waitcnt vmcnt(7)
	v_perm_b32 v126, 0, v58, s15
	v_perm_b32 v127, 0, v60, s15
	ds_write_b64 v206, v[126:127]
	s_waitcnt vmcnt(6)
	v_perm_b32 v118, 0, v62, s15
	v_perm_b32 v119, 0, v64, s15
	ds_write_b64 v206, v[118:119] offset:4096
	s_waitcnt vmcnt(5)
	v_perm_b32 v182, 0, v66, s15
	v_perm_b32 v183, 0, v68, s15
	ds_write_b64 v206, v[182:183] offset:8192
	s_waitcnt vmcnt(4)
	v_perm_b32 v110, 0, v70, s15
	v_perm_b32 v111, 0, v72, s15
	ds_write_b64 v206, v[110:111] offset:12288
	s_waitcnt vmcnt(3)
	v_perm_b32 v102, 0, v74, s15
	v_perm_b32 v103, 0, v76, s15
	ds_write_b64 v206, v[102:103] offset:16384
	s_waitcnt vmcnt(2)
	v_perm_b32 v184, 0, v78, s15
	v_perm_b32 v185, 0, v80, s15
	ds_write_b64 v206, v[184:185] offset:20480
	s_waitcnt vmcnt(1)
	v_perm_b32 v186, 0, v82, s15
	v_perm_b32 v187, 0, v84, s15
	ds_write_b64 v206, v[186:187] offset:24576
	s_waitcnt vmcnt(0)
	v_perm_b32 v188, 0, v86, s15
	v_perm_b32 v189, 0, v88, s15
	ds_write_b64 v206, v[188:189] offset:28672
	s_waitcnt lgkmcnt(0)
	s_barrier
; #define LAS __attribute__((address_space(3)))
; #define WG_SYNC() do { asm volatile("s_waitcnt lgkmcnt(0)" ::: "memory"); __builtin_amdgcn_s_barrier(); asm volatile("" ::: "memory"); } while (0)
; __device__ __forceinline__ void hy_sconv(const LAS float* plane, float w0, float w1, float w2, float cb, int n2, float (&u)[8][2]) {
;     asm volatile("" : "+v"(n2));
; #pragma unroll
;     for (int r = 0; r < 8; ++r)
; #pragma unroll
;         for (int b = 0; b < 2; ++b) { const int t = n2 + 512 * r, row = b * SEQ + t;
;             float a = cb + w1 * plane[row];
;             if (t > 0) a += w0 * plane[row - 1];
;             if (t < SEQ - 1) a += w2 * plane[row + 1];
;             u[r][b] = a; }
; }
; __device__ __forceinline__ void hyena_fft(LAS unsigned char* lds, int layer, int G, const int wave_s) {
;     ...
;             hy_sconv(pl0, cw[HY + c], cw[3 * HY + HY + c], cw[6 * HY + HY + c], cb[HY + c], n2, ux);
;             WG_SYNC();
	v_mov_b32_e32 v168, s17
	v_mov_b32_e32 v169, s23
	v_mov_b32_e32 v180, s25
	v_mov_b32_e32 v181, s26
	ds_read_b32 v126, v208
	ds_read_b32 v118, v210
	ds_read_b32 v182, v208 offset:4
	ds_read_b32 v127, v208 offset:16384
	ds_read_b32 v119, v210 offset:16384
	ds_read_b32 v183, v208 offset:16388
	ds_read_b32 v110, v208 offset:2048
	ds_read_b32 v102, v208 offset:2044
	ds_read_b32 v184, v208 offset:2052
	ds_read_b32 v111, v208 offset:18432
	ds_read_b32 v103, v208 offset:18428
	ds_read_b32 v185, v208 offset:18436
	s_waitcnt lgkmcnt(10)
	v_cndmask_b32_e64 v118, v118, 0, s[10:11]
	s_waitcnt lgkmcnt(7)
	v_cndmask_b32_e64 v119, v119, 0, s[10:11]
	v_pk_fma_f32 v[148:149], v[168:169], v[126:127], v[180:181] op_sel:[1,0,1]
	v_pk_fma_f32 v[148:149], v[168:169], v[118:119], v[148:149] op_sel_hi:[0,1,1]
	s_waitcnt lgkmcnt(6)
	v_pk_fma_f32 v[148:149], v[180:181], v[182:183], v[148:149] op_sel_hi:[0,1,1]
	s_waitcnt lgkmcnt(2)
	v_pk_fma_f32 v[150:151], v[168:169], v[110:111], v[180:181] op_sel:[1,0,1]
	s_waitcnt lgkmcnt(1)
	v_pk_fma_f32 v[150:151], v[168:169], v[102:103], v[150:151] op_sel_hi:[0,1,1]
	s_waitcnt lgkmcnt(0)
	v_pk_fma_f32 v[150:151], v[180:181], v[184:185], v[150:151] op_sel_hi:[0,1,1]
	ds_read_b32 v186, v208 offset:4096
	ds_read_b32 v188, v208 offset:4092
	ds_read_b32 v126, v208 offset:4100
	ds_read_b32 v187, v208 offset:20480
	ds_read_b32 v189, v208 offset:20476
	ds_read_b32 v127, v208 offset:20484
	ds_read_b32 v118, v208 offset:6144
	ds_read_b32 v182, v208 offset:6140
	ds_read_b32 v110, v208 offset:6148
	ds_read_b32 v119, v208 offset:22528
	ds_read_b32 v183, v208 offset:22524
	ds_read_b32 v111, v208 offset:22532
	s_waitcnt lgkmcnt(8)
	v_pk_fma_f32 v[152:153], v[168:169], v[186:187], v[180:181] op_sel:[1,0,1]
	s_waitcnt lgkmcnt(7)
	v_pk_fma_f32 v[152:153], v[168:169], v[188:189], v[152:153] op_sel_hi:[0,1,1]
	s_waitcnt lgkmcnt(6)
	v_pk_fma_f32 v[152:153], v[180:181], v[126:127], v[152:153] op_sel_hi:[0,1,1]
	s_waitcnt lgkmcnt(2)
	v_pk_fma_f32 v[154:155], v[168:169], v[118:119], v[180:181] op_sel:[1,0,1]
	s_waitcnt lgkmcnt(1)
	v_pk_fma_f32 v[154:155], v[168:169], v[182:183], v[154:155] op_sel_hi:[0,1,1]
	s_waitcnt lgkmcnt(0)
	v_pk_fma_f32 v[154:155], v[180:181], v[110:111], v[154:155] op_sel_hi:[0,1,1]
	ds_read_b32 v102, v208 offset:8192
	ds_read_b32 v184, v208 offset:8188
	ds_read_b32 v186, v208 offset:8196
	ds_read_b32 v103, v208 offset:24576
	ds_read_b32 v185, v208 offset:24572
	ds_read_b32 v187, v208 offset:24580
	ds_read_b32 v188, v208 offset:10240
	ds_read_b32 v126, v208 offset:10236
	ds_read_b32 v118, v208 offset:10244
	ds_read_b32 v189, v208 offset:26624
	ds_read_b32 v127, v208 offset:26620
	ds_read_b32 v119, v208 offset:26628
	s_waitcnt lgkmcnt(8)
	v_pk_fma_f32 v[158:159], v[168:169], v[102:103], v[180:181] op_sel:[1,0,1]
	s_waitcnt lgkmcnt(7)
	v_pk_fma_f32 v[158:159], v[168:169], v[184:185], v[158:159] op_sel_hi:[0,1,1]
	s_waitcnt lgkmcnt(6)
	v_pk_fma_f32 v[158:159], v[180:181], v[186:187], v[158:159] op_sel_hi:[0,1,1]
	s_waitcnt lgkmcnt(2)
	v_pk_fma_f32 v[160:161], v[168:169], v[188:189], v[180:181] op_sel:[1,0,1]
	s_waitcnt lgkmcnt(1)
	v_pk_fma_f32 v[160:161], v[168:169], v[126:127], v[160:161] op_sel_hi:[0,1,1]
	s_waitcnt lgkmcnt(0)
	v_pk_fma_f32 v[160:161], v[180:181], v[118:119], v[160:161] op_sel_hi:[0,1,1]
	ds_read_b32 v182, v208 offset:12288
	ds_read_b32 v110, v208 offset:12284
	ds_read_b32 v102, v208 offset:12292
	ds_read_b32 v183, v208 offset:28672
	ds_read_b32 v111, v208 offset:28668
	ds_read_b32 v103, v208 offset:28676
	ds_read_b32 v184, v208 offset:14336
	ds_read_b32 v186, v208 offset:14332
	ds_read_b32 v188, v208 offset:14340
	ds_read_b32 v185, v208 offset:30720
	ds_read_b32 v187, v208 offset:30716
	ds_read_b32 v189, v208 offset:30724
	s_waitcnt lgkmcnt(8)
	v_pk_fma_f32 v[162:163], v[168:169], v[182:183], v[180:181] op_sel:[1,0,1]
	s_waitcnt lgkmcnt(7)
	v_pk_fma_f32 v[162:163], v[168:169], v[110:111], v[162:163] op_sel_hi:[0,1,1]
	s_waitcnt lgkmcnt(6)
	v_pk_fma_f32 v[162:163], v[180:181], v[102:103], v[162:163] op_sel_hi:[0,1,1]
	s_waitcnt lgkmcnt(3)
	v_cndmask_b32_e64 v188, v188, 0, s[28:29]
	s_waitcnt lgkmcnt(0)
	v_cndmask_b32_e64 v189, v189, 0, s[28:29]
	v_pk_fma_f32 v[164:165], v[168:169], v[184:185], v[180:181] op_sel:[1,0,1]
	v_pk_fma_f32 v[164:165], v[168:169], v[186:187], v[164:165] op_sel_hi:[0,1,1]
	v_pk_fma_f32 v[164:165], v[180:181], v[188:189], v[164:165] op_sel_hi:[0,1,1]
	s_waitcnt lgkmcnt(0)
	s_barrier
; #define LAS __attribute__((address_space(3)))
; __device__ __forceinline__ f32x2 cmul(f32x2 a, f32x2 b) { return (f32x2){a.x * b.x - a.y * b.y, a.x * b.y + a.y * b.x}; }
; #define WG_SYNC() do { asm volatile("s_waitcnt lgkmcnt(0)" ::: "memory"); __builtin_amdgcn_s_barrier(); asm volatile("" ::: "memory"); } while (0)
; __device__ __forceinline__ void dft16_fwd_lo(f32x2 (&x)[16]) {
;     constexpr float C1 = 0.92387953251128674f, S1 = 0.38268343236508977f, C2 = 0.70710678118654752f;
; #pragma unroll
;     for (int b = 0; b < 4; ++b) { const f32x2 x0 = x[b], x1 = x[4 + b]; const f32x2 j1 = {x1.y, -x1.x};
;         x[b] = x0 + x1; x[4 + b] = x0 + j1; x[8 + b] = x0 - x1; x[12 + b] = x0 - j1; }
;     const f32x2 w1 = {C1, -S1}, w2 = {C2, -C2}, w3 = {S1, -C1}, w4 = {0.f, -1.f}, w6 = {-C2, -C2}, w9 = {-C1, S1};
;     x[5] = cmul(x[5], w1); x[6] = cmul(x[6], w2); x[7] = cmul(x[7], w3);
;     x[9] = cmul(x[9], w2); x[10] = cmul(x[10], w4); x[11] = cmul(x[11], w6);
;     x[13] = cmul(x[13], w3); x[14] = cmul(x[14], w6); x[15] = cmul(x[15], w9);
; #pragma unroll
;     for (int c = 0; c < 4; ++c) dft4<false>(x[4 * c], x[4 * c + 1], x[4 * c + 2], x[4 * c + 3]);
; template <bool LO> __device__ __forceinline__ void fft_fwd1(f32x2 (&x)[16], LAS f32x2* B, int n2, const f32x2 (&w)[16]) {
;     asm volatile("" : "+v"(n2));
;     if (LO) dft16_fwd_lo(x); else dft16<false>(x);
;     B[fpad(n2)] = x[0];
; #pragma unroll
;     for (int k = 1; k < 16; ++k) B[fpad(512 * k + n2)] = cmul(x[k], w[k]);
; __device__ __forceinline__ void hyena_fft(LAS unsigned char* lds, int layer, int G, const int wave_s) {
;     ...
;             for (int r = 0; r < 8; ++r) { x[r] = (f32x2){uz[r][0], uz[r][1]}; x[r + 8] = (f32x2){0.f, 0.f}; }
;             fft_fwd1<true>(x, Db, n2, w1p); WG_SYNC();
	v_pk_add_f32 v[104:105], v[132:133], v[140:141] neg_lo:[0,1] neg_hi:[0,1]
	v_pk_add_f32 v[106:107], v[132:133], v[140:141] op_sel:[0,1] op_sel_hi:[1,0] neg_lo:[0,1]
	v_pk_add_f32 v[126:127], v[132:133], v[140:141] op_sel:[0,1] op_sel_hi:[1,0] neg_hi:[0,1]
	v_pk_add_f32 v[100:101], v[132:133], v[140:141]
	v_pk_add_f32 v[112:113], v[134:135], v[142:143] neg_lo:[0,1] neg_hi:[0,1]
	v_pk_add_f32 v[114:115], v[134:135], v[142:143] op_sel:[0,1] op_sel_hi:[1,0] neg_lo:[0,1]
	v_pk_add_f32 v[118:119], v[134:135], v[142:143] op_sel:[0,1] op_sel_hi:[1,0] neg_hi:[0,1]
	v_pk_add_f32 v[108:109], v[134:135], v[142:143]
	v_pk_add_f32 v[120:121], v[136:137], v[144:145] neg_lo:[0,1] neg_hi:[0,1]
	v_pk_add_f32 v[122:123], v[136:137], v[144:145] op_sel:[0,1] op_sel_hi:[1,0] neg_lo:[0,1]
	v_pk_add_f32 v[182:183], v[136:137], v[144:145] op_sel:[0,1] op_sel_hi:[1,0] neg_hi:[0,1]
	v_pk_add_f32 v[116:117], v[136:137], v[144:145]
	v_pk_add_f32 v[128:129], v[138:139], v[146:147] neg_lo:[0,1] neg_hi:[0,1]
	v_pk_add_f32 v[130:131], v[138:139], v[146:147] op_sel:[0,1] op_sel_hi:[1,0] neg_lo:[0,1]
	v_pk_add_f32 v[110:111], v[138:139], v[146:147] op_sel:[0,1] op_sel_hi:[1,0] neg_hi:[0,1]
	v_pk_add_f32 v[124:125], v[138:139], v[146:147]
	v_pk_mul_f32 v[102:103], v[118:119], s[68:69] op_sel:[1,1] op_sel_hi:[0,1]
	v_pk_fma_f32 v[118:119], v[118:119], s[68:69], v[102:103] op_sel_hi:[1,0,1] neg_lo:[0,0,1]
	v_pk_mul_f32 v[184:185], v[182:183], s[84:85] op_sel:[1,1] op_sel_hi:[0,1]
	v_pk_fma_f32 v[182:183], v[182:183], s[84:85], v[184:185] op_sel_hi:[1,0,1] neg_lo:[0,0,1]
	v_pk_mul_f32 v[186:187], v[110:111], s[88:89] op_sel:[1,1] op_sel_hi:[0,1]
	v_pk_fma_f32 v[110:111], v[110:111], s[88:89], v[186:187] op_sel_hi:[1,0,1] neg_lo:[0,0,1]
	v_pk_mul_f32 v[188:189], v[112:113], s[84:85] op_sel:[1,1] op_sel_hi:[0,1]
	v_pk_fma_f32 v[112:113], v[112:113], s[84:85], v[188:189] op_sel_hi:[1,0,1] neg_lo:[0,0,1]
	v_pk_mul_f32 v[168:169], v[128:129], s[90:91] op_sel:[1,1] op_sel_hi:[0,1]
	v_pk_fma_f32 v[128:129], v[128:129], s[90:91], v[168:169] op_sel_hi:[1,0,1] neg_lo:[0,0,1]
	v_pk_mul_f32 v[180:181], v[114:115], s[88:89] op_sel:[1,1] op_sel_hi:[0,1]
	v_pk_fma_f32 v[114:115], v[114:115], s[88:89], v[180:181] op_sel_hi:[1,0,1] neg_lo:[0,0,1]
	v_pk_mul_f32 v[178:179], v[122:123], s[90:91] op_sel:[1,1] op_sel_hi:[0,1]
	v_pk_fma_f32 v[122:123], v[122:123], s[90:91], v[178:179] op_sel_hi:[1,0,1] neg_lo:[0,0,1]
	v_pk_mul_f32 v[176:177], v[130:131], s[98:99] op_sel:[1,1] op_sel_hi:[0,1]
	v_pk_fma_f32 v[130:131], v[130:131], s[98:99], v[176:177] op_sel_hi:[1,0,1] neg_lo:[0,0,1]
	v_pk_add_f32 v[166:167], v[100:101], v[116:117]
	v_pk_add_f32 v[174:175], v[100:101], v[116:117] neg_lo:[0,1] neg_hi:[0,1]
	v_pk_add_f32 v[102:103], v[108:109], v[124:125]
	v_pk_add_f32 v[184:185], v[108:109], v[124:125] neg_lo:[0,1] neg_hi:[0,1]
	v_pk_add_f32 v[100:101], v[166:167], v[102:103]
	v_pk_add_f32 v[116:117], v[166:167], v[102:103] neg_lo:[0,1] neg_hi:[0,1]
	v_pk_add_f32 v[108:109], v[174:175], v[184:185] op_sel:[0,1] op_sel_hi:[1,0] neg_hi:[0,1]
	v_pk_add_f32 v[124:125], v[174:175], v[184:185] op_sel:[0,1] op_sel_hi:[1,0] neg_lo:[0,1]
	v_pk_add_f32 v[186:187], v[126:127], v[182:183]
	v_pk_add_f32 v[188:189], v[126:127], v[182:183] neg_lo:[0,1] neg_hi:[0,1]
	v_pk_add_f32 v[168:169], v[118:119], v[110:111]
	v_pk_add_f32 v[180:181], v[118:119], v[110:111] neg_lo:[0,1] neg_hi:[0,1]
	v_pk_add_f32 v[126:127], v[186:187], v[168:169]
	v_pk_add_f32 v[182:183], v[186:187], v[168:169] neg_lo:[0,1] neg_hi:[0,1]
	v_pk_add_f32 v[118:119], v[188:189], v[180:181] op_sel:[0,1] op_sel_hi:[1,0] neg_hi:[0,1]
	v_pk_add_f32 v[110:111], v[188:189], v[180:181] op_sel:[0,1] op_sel_hi:[1,0] neg_lo:[0,1]
	v_pk_add_f32 v[178:179], v[104:105], v[120:121] op_sel:[0,1] op_sel_hi:[1,0] neg_hi:[0,1]
	v_pk_add_f32 v[176:177], v[104:105], v[120:121] op_sel:[0,1] op_sel_hi:[1,0] neg_lo:[0,1]
	v_pk_add_f32 v[166:167], v[112:113], v[128:129]
	v_pk_add_f32 v[174:175], v[112:113], v[128:129] neg_lo:[0,1] neg_hi:[0,1]
	v_pk_add_f32 v[104:105], v[178:179], v[166:167]
	v_pk_add_f32 v[120:121], v[178:179], v[166:167] neg_lo:[0,1] neg_hi:[0,1]
	v_pk_add_f32 v[112:113], v[176:177], v[174:175] op_sel:[0,1] op_sel_hi:[1,0] neg_hi:[0,1]
	v_pk_add_f32 v[128:129], v[176:177], v[174:175] op_sel:[0,1] op_sel_hi:[1,0] neg_lo:[0,1]
	v_pk_add_f32 v[102:103], v[106:107], v[122:123]
	v_pk_add_f32 v[184:185], v[106:107], v[122:123] neg_lo:[0,1] neg_hi:[0,1]
	v_pk_add_f32 v[186:187], v[114:115], v[130:131]
	v_pk_add_f32 v[188:189], v[114:115], v[130:131] neg_lo:[0,1] neg_hi:[0,1]
	v_pk_add_f32 v[106:107], v[102:103], v[186:187]
	v_pk_add_f32 v[122:123], v[102:103], v[186:187] neg_lo:[0,1] neg_hi:[0,1]
	v_pk_add_f32 v[114:115], v[184:185], v[188:189] op_sel:[0,1] op_sel_hi:[1,0] neg_hi:[0,1]
	v_pk_add_f32 v[130:131], v[184:185], v[188:189] op_sel:[0,1] op_sel_hi:[1,0] neg_lo:[0,1]
	ds_write_b64 v3, v[100:101]
	v_pk_mul_f32 v[180:181], v[126:127], v[6:7] op_sel:[1,1] op_sel_hi:[0,1]
	v_pk_fma_f32 v[168:169], v[126:127], v[6:7], v[180:181] op_sel_hi:[1,0,1] neg_lo:[0,0,1]
	ds_write_b64 v3, v[168:169] offset:4224
	v_pk_mul_f32 v[176:177], v[104:105], v[8:9] op_sel:[1,1] op_sel_hi:[0,1]
	v_pk_fma_f32 v[178:179], v[104:105], v[8:9], v[176:177] op_sel_hi:[1,0,1] neg_lo:[0,0,1]
	ds_write_b64 v3, v[178:179] offset:8448
	v_pk_mul_f32 v[174:175], v[106:107], v[10:11] op_sel:[1,1] op_sel_hi:[0,1]
	v_pk_fma_f32 v[166:167], v[106:107], v[10:11], v[174:175] op_sel_hi:[1,0,1] neg_lo:[0,0,1]
	ds_write_b64 v3, v[166:167] offset:12672
	v_pk_mul_f32 v[184:185], v[108:109], v[12:13] op_sel:[1,1] op_sel_hi:[0,1]
	v_pk_fma_f32 v[102:103], v[108:109], v[12:13], v[184:185] op_sel_hi:[1,0,1] neg_lo:[0,0,1]
; #define LAS __attribute__((address_space(3)))
; __device__ __forceinline__ f32x2 cmul(f32x2 a, f32x2 b) { return (f32x2){a.x * b.x - a.y * b.y, a.x * b.y + a.y * b.x}; }
; #define WG_SYNC() do { asm volatile("s_waitcnt lgkmcnt(0)" ::: "memory"); __builtin_amdgcn_s_barrier(); asm volatile("" ::: "memory"); } while (0)
; #define WAVE_FENCE() do { asm volatile("s_waitcnt lgkmcnt(0)" ::: "memory"); __builtin_amdgcn_sched_barrier(0); } while (0)
; template <bool INV> __device__ __forceinline__ void dft16(f32x2 (&x)[16]) {
;     constexpr float C1 = 0.92387953251128674f, S1 = 0.38268343236508977f, C2 = 0.70710678118654752f;
; #pragma unroll
;     for (int b = 0; b < 4; ++b) dft4<INV>(x[b], x[4 + b], x[8 + b], x[12 + b]);
; template <bool LO> __device__ __forceinline__ void fft_fwd1(f32x2 (&x)[16], LAS f32x2* B, int n2, const f32x2 (&w)[16]) {
;     ...
;     for (int k = 1; k < 16; ++k) B[fpad(512 * k + n2)] = cmul(x[k], w[k]);
; __device__ __forceinline__ void fft_fwd2(LAS f32x2* B, const LAS f32x2* TW2, int tid) {
;     asm volatile("" : "+v"(tid));
;     const int b = tid >> 5, n2 = tid & 31, base = 512 * b + n2; f32x2 x[16];
; #pragma unroll
;     for (int r = 0; r < 16; ++r) x[r] = B[fpad(base + 32 * r)];
;     dft16<false>(x);
; __device__ __forceinline__ void hyena_fft(LAS unsigned char* lds, int layer, int G, const int wave_s) {
;     ...
;             fft_fwd1<true>(x, Db, n2, w1p); WG_SYNC();
;             fft_fwd2(Db, TW2, tid); WAVE_FENCE(); fft_pair32<1>(Db, Fb, wave, lane); WAVE_FENCE(); fft_inv2(Db, TW2, tid);
	ds_write_b64 v3, v[102:103] offset:16896
	v_pk_mul_f32 v[188:189], v[118:119], v[14:15] op_sel:[1,1] op_sel_hi:[0,1]
	v_pk_fma_f32 v[186:187], v[118:119], v[14:15], v[188:189] op_sel_hi:[1,0,1] neg_lo:[0,0,1]
	ds_write_b64 v3, v[186:187] offset:21120
	v_pk_mul_f32 v[168:169], v[112:113], v[16:17] op_sel:[1,1] op_sel_hi:[0,1]
	v_pk_fma_f32 v[180:181], v[112:113], v[16:17], v[168:169] op_sel_hi:[1,0,1] neg_lo:[0,0,1]
	ds_write_b64 v3, v[180:181] offset:25344
	v_pk_mul_f32 v[178:179], v[114:115], v[18:19] op_sel:[1,1] op_sel_hi:[0,1]
	v_pk_fma_f32 v[176:177], v[114:115], v[18:19], v[178:179] op_sel_hi:[1,0,1] neg_lo:[0,0,1]
	ds_write_b64 v3, v[176:177] offset:29568
	v_pk_mul_f32 v[166:167], v[116:117], v[20:21] op_sel:[1,1] op_sel_hi:[0,1]
	v_pk_fma_f32 v[174:175], v[116:117], v[20:21], v[166:167] op_sel_hi:[1,0,1] neg_lo:[0,0,1]
	ds_write_b64 v3, v[174:175] offset:33792
	v_pk_mul_f32 v[102:103], v[182:183], v[22:23] op_sel:[1,1] op_sel_hi:[0,1]
	v_pk_fma_f32 v[184:185], v[182:183], v[22:23], v[102:103] op_sel_hi:[1,0,1] neg_lo:[0,0,1]
	ds_write_b64 v3, v[184:185] offset:38016
	v_pk_mul_f32 v[186:187], v[120:121], v[24:25] op_sel:[1,1] op_sel_hi:[0,1]
	v_pk_fma_f32 v[188:189], v[120:121], v[24:25], v[186:187] op_sel_hi:[1,0,1] neg_lo:[0,0,1]
	ds_write_b64 v3, v[188:189] offset:42240
	v_pk_mul_f32 v[180:181], v[122:123], v[26:27] op_sel:[1,1] op_sel_hi:[0,1]
	v_pk_fma_f32 v[168:169], v[122:123], v[26:27], v[180:181] op_sel_hi:[1,0,1] neg_lo:[0,0,1]
	ds_write_b64 v3, v[168:169] offset:46464
	v_pk_mul_f32 v[176:177], v[124:125], v[28:29] op_sel:[1,1] op_sel_hi:[0,1]
	v_pk_fma_f32 v[178:179], v[124:125], v[28:29], v[176:177] op_sel_hi:[1,0,1] neg_lo:[0,0,1]
	ds_write_b64 v3, v[178:179] offset:50688
	v_pk_mul_f32 v[174:175], v[110:111], v[30:31] op_sel:[1,1] op_sel_hi:[0,1]
	v_pk_fma_f32 v[166:167], v[110:111], v[30:31], v[174:175] op_sel_hi:[1,0,1] neg_lo:[0,0,1]
	ds_write_b64 v3, v[166:167] offset:54912
	v_pk_mul_f32 v[184:185], v[128:129], v[32:33] op_sel:[1,1] op_sel_hi:[0,1]
	v_pk_fma_f32 v[102:103], v[128:129], v[32:33], v[184:185] op_sel_hi:[1,0,1] neg_lo:[0,0,1]
	ds_write_b64 v3, v[102:103] offset:59136
	v_pk_mul_f32 v[188:189], v[130:131], v[34:35] op_sel:[1,1] op_sel_hi:[0,1]
	v_pk_fma_f32 v[186:187], v[130:131], v[34:35], v[188:189] op_sel_hi:[1,0,1] neg_lo:[0,0,1]
	ds_write_b64 v3, v[186:187] offset:63360
	s_waitcnt lgkmcnt(0)
	s_barrier
	s_cbranch_vccz .Lhfft_st10
	s_sleep 8
.Lhfft_st10:
	ds_read_b64 v[100:101], v5
	ds_read_b64 v[108:109], v5 offset:1056
	ds_read_b64 v[116:117], v5 offset:2112
	ds_read_b64 v[124:125], v5 offset:3168
	ds_read_b64 v[126:127], v5 offset:264
	ds_read_b64 v[118:119], v5 offset:1320
	ds_read_b64 v[182:183], v5 offset:2376
	ds_read_b64 v[110:111], v5 offset:3432
	ds_read_b64 v[104:105], v5 offset:528
	ds_read_b64 v[112:113], v5 offset:1584
	ds_read_b64 v[120:121], v5 offset:2640
	ds_read_b64 v[128:129], v5 offset:3696
	s_waitcnt lgkmcnt(8)
	ds_read_b64 v[106:107], v5 offset:792
	ds_read_b64 v[114:115], v5 offset:1848
	ds_read_b64 v[122:123], v5 offset:2904
	ds_read_b64 v[130:131], v5 offset:3960
	v_pk_add_f32 v[180:181], v[100:101], v[116:117]
	v_pk_add_f32 v[168:169], v[100:101], v[116:117] neg_lo:[0,1] neg_hi:[0,1]
	v_pk_add_f32 v[176:177], v[108:109], v[124:125]
	v_pk_add_f32 v[178:179], v[108:109], v[124:125] neg_lo:[0,1] neg_hi:[0,1]
	v_pk_add_f32 v[100:101], v[180:181], v[176:177]
	v_pk_add_f32 v[116:117], v[180:181], v[176:177] neg_lo:[0,1] neg_hi:[0,1]
	v_pk_add_f32 v[108:109], v[168:169], v[178:179] op_sel:[0,1] op_sel_hi:[1,0] neg_hi:[0,1]
	v_pk_add_f32 v[124:125], v[168:169], v[178:179] op_sel:[0,1] op_sel_hi:[1,0] neg_lo:[0,1]
	s_waitcnt lgkmcnt(9)
	v_pk_add_f32 v[174:175], v[126:127], v[182:183]
	v_pk_add_f32 v[166:167], v[126:127], v[182:183] neg_lo:[0,1] neg_hi:[0,1]
	s_waitcnt lgkmcnt(8)
	v_pk_add_f32 v[184:185], v[118:119], v[110:111]
	v_pk_add_f32 v[102:103], v[118:119], v[110:111] neg_lo:[0,1] neg_hi:[0,1]
	v_pk_add_f32 v[126:127], v[174:175], v[184:185]
	v_pk_add_f32 v[182:183], v[174:175], v[184:185] neg_lo:[0,1] neg_hi:[0,1]
	v_pk_add_f32 v[118:119], v[166:167], v[102:103] op_sel:[0,1] op_sel_hi:[1,0] neg_hi:[0,1]
	v_pk_add_f32 v[110:111], v[166:167], v[102:103] op_sel:[0,1] op_sel_hi:[1,0] neg_lo:[0,1]
	s_waitcnt lgkmcnt(5)
	v_pk_add_f32 v[188:189], v[104:105], v[120:121]
	v_pk_add_f32 v[186:187], v[104:105], v[120:121] neg_lo:[0,1] neg_hi:[0,1]
	s_waitcnt lgkmcnt(4)
	v_pk_add_f32 v[180:181], v[112:113], v[128:129]
	v_pk_add_f32 v[168:169], v[112:113], v[128:129] neg_lo:[0,1] neg_hi:[0,1]
	v_pk_add_f32 v[104:105], v[188:189], v[180:181]
	v_pk_add_f32 v[120:121], v[188:189], v[180:181] neg_lo:[0,1] neg_hi:[0,1]
	v_pk_add_f32 v[112:113], v[186:187], v[168:169] op_sel:[0,1] op_sel_hi:[1,0] neg_hi:[0,1]
	v_pk_add_f32 v[128:129], v[186:187], v[168:169] op_sel:[0,1] op_sel_hi:[1,0] neg_lo:[0,1]
	s_waitcnt lgkmcnt(1)
	v_pk_add_f32 v[176:177], v[106:107], v[122:123]
	v_pk_add_f32 v[178:179], v[106:107], v[122:123] neg_lo:[0,1] neg_hi:[0,1]
	s_waitcnt lgkmcnt(0)
; __device__ __forceinline__ f32x2 cmul(f32x2 a, f32x2 b) { return (f32x2){a.x * b.x - a.y * b.y, a.x * b.y + a.y * b.x}; }
; template <bool INV> __device__ __forceinline__ f32x2 cmul_tw(f32x2 a, f32x2 w) { return INV ? cmulc(a, w) : cmul(a, w); }
; template <bool INV> __device__ __forceinline__ void dft16(f32x2 (&x)[16]) {
;     ...
;     const f32x2 w1 = {C1, -S1}, w2 = {C2, -C2}, w3 = {S1, -C1}, w4 = {0.f, -1.f}, w6 = {-C2, -C2}, w9 = {-C1, S1};
;     x[4 * 1 + 1] = cmul_tw<INV>(x[5], w1); x[4 * 1 + 2] = cmul_tw<INV>(x[6], w2); x[4 * 1 + 3] = cmul_tw<INV>(x[7], w3);
;     x[4 * 2 + 1] = cmul_tw<INV>(x[9], w2); x[4 * 2 + 2] = cmul_tw<INV>(x[10], w4); x[4 * 2 + 3] = cmul_tw<INV>(x[11], w6);
;     x[4 * 3 + 1] = cmul_tw<INV>(x[13], w3); x[4 * 3 + 2] = cmul_tw<INV>(x[14], w6); x[4 * 3 + 3] = cmul_tw<INV>(x[15], w9);
; #pragma unroll
;     for (int c = 0; c < 4; ++c) dft4<INV>(x[4 * c], x[4 * c + 1], x[4 * c + 2], x[4 * c + 3]);
;     f32x2 y[16];
; #pragma unroll
;     for (int k = 0; k < 16; ++k) y[k] = x[4 * (k & 3) + (k >> 2)];
; #pragma unroll
;     for (int k = 0; k < 16; ++k) x[k] = y[k];
; __device__ __forceinline__ void fft_fwd2(LAS f32x2* B, const LAS f32x2* TW2, int tid) {
;     ...
;     B[fpad(base)] = x[0];
; #pragma unroll
;     for (int k = 1; k < 16; ++k) B[fpad(base + 32 * k)] = cmul(x[k], TW2[k * 32 + n2]);
	v_pk_add_f32 v[174:175], v[114:115], v[130:131]
	v_pk_add_f32 v[166:167], v[114:115], v[130:131] neg_lo:[0,1] neg_hi:[0,1]
	v_pk_add_f32 v[106:107], v[176:177], v[174:175]
	v_pk_add_f32 v[122:123], v[176:177], v[174:175] neg_lo:[0,1] neg_hi:[0,1]
	v_pk_add_f32 v[114:115], v[178:179], v[166:167] op_sel:[0,1] op_sel_hi:[1,0] neg_hi:[0,1]
	v_pk_add_f32 v[130:131], v[178:179], v[166:167] op_sel:[0,1] op_sel_hi:[1,0] neg_lo:[0,1]
	v_pk_mul_f32 v[184:185], v[118:119], s[68:69] op_sel:[1,1] op_sel_hi:[0,1]
	v_pk_fma_f32 v[118:119], v[118:119], s[68:69], v[184:185] op_sel_hi:[1,0,1] neg_lo:[0,0,1]
	v_pk_mul_f32 v[102:103], v[112:113], s[84:85] op_sel:[1,1] op_sel_hi:[0,1]
	v_pk_fma_f32 v[112:113], v[112:113], s[84:85], v[102:103] op_sel_hi:[1,0,1] neg_lo:[0,0,1]
	v_pk_mul_f32 v[188:189], v[114:115], s[88:89] op_sel:[1,1] op_sel_hi:[0,1]
	v_pk_fma_f32 v[114:115], v[114:115], s[88:89], v[188:189] op_sel_hi:[1,0,1] neg_lo:[0,0,1]
	v_pk_mul_f32 v[186:187], v[182:183], s[84:85] op_sel:[1,1] op_sel_hi:[0,1]
	v_pk_fma_f32 v[182:183], v[182:183], s[84:85], v[186:187] op_sel_hi:[1,0,1] neg_lo:[0,0,1]
	v_pk_mul_f32 v[180:181], v[122:123], s[90:91] op_sel:[1,1] op_sel_hi:[0,1]
	v_pk_fma_f32 v[122:123], v[122:123], s[90:91], v[180:181] op_sel_hi:[1,0,1] neg_lo:[0,0,1]
	v_pk_mul_f32 v[168:169], v[110:111], s[88:89] op_sel:[1,1] op_sel_hi:[0,1]
	v_pk_fma_f32 v[110:111], v[110:111], s[88:89], v[168:169] op_sel_hi:[1,0,1] neg_lo:[0,0,1]
	v_pk_mul_f32 v[176:177], v[128:129], s[90:91] op_sel:[1,1] op_sel_hi:[0,1]
	v_pk_fma_f32 v[128:129], v[128:129], s[90:91], v[176:177] op_sel_hi:[1,0,1] neg_lo:[0,0,1]
	v_pk_mul_f32 v[178:179], v[130:131], s[98:99] op_sel:[1,1] op_sel_hi:[0,1]
	v_pk_fma_f32 v[130:131], v[130:131], s[98:99], v[178:179] op_sel_hi:[1,0,1] neg_lo:[0,0,1]
	v_pk_add_f32 v[174:175], v[100:101], v[104:105]
	v_pk_add_f32 v[166:167], v[100:101], v[104:105] neg_lo:[0,1] neg_hi:[0,1]
	v_pk_add_f32 v[184:185], v[126:127], v[106:107]
	v_pk_add_f32 v[102:103], v[126:127], v[106:107] neg_lo:[0,1] neg_hi:[0,1]
	v_pk_add_f32 v[100:101], v[174:175], v[184:185]
	v_pk_add_f32 v[104:105], v[174:175], v[184:185] neg_lo:[0,1] neg_hi:[0,1]
	v_pk_add_f32 v[126:127], v[166:167], v[102:103] op_sel:[0,1] op_sel_hi:[1,0] neg_hi:[0,1]
	v_pk_add_f32 v[106:107], v[166:167], v[102:103] op_sel:[0,1] op_sel_hi:[1,0] neg_lo:[0,1]
	v_pk_add_f32 v[188:189], v[108:109], v[112:113]
	v_pk_add_f32 v[186:187], v[108:109], v[112:113] neg_lo:[0,1] neg_hi:[0,1]
	v_pk_add_f32 v[180:181], v[118:119], v[114:115]
	v_pk_add_f32 v[168:169], v[118:119], v[114:115] neg_lo:[0,1] neg_hi:[0,1]
	v_pk_add_f32 v[108:109], v[188:189], v[180:181]
	v_pk_add_f32 v[112:113], v[188:189], v[180:181] neg_lo:[0,1] neg_hi:[0,1]
	v_pk_add_f32 v[118:119], v[186:187], v[168:169] op_sel:[0,1] op_sel_hi:[1,0] neg_hi:[0,1]
	v_pk_add_f32 v[114:115], v[186:187], v[168:169] op_sel:[0,1] op_sel_hi:[1,0] neg_lo:[0,1]
	v_pk_add_f32 v[176:177], v[116:117], v[120:121] op_sel:[0,1] op_sel_hi:[1,0] neg_hi:[0,1]
	v_pk_add_f32 v[178:179], v[116:117], v[120:121] op_sel:[0,1] op_sel_hi:[1,0] neg_lo:[0,1]
	v_pk_add_f32 v[174:175], v[182:183], v[122:123]
	v_pk_add_f32 v[166:167], v[182:183], v[122:123] neg_lo:[0,1] neg_hi:[0,1]
	v_pk_add_f32 v[116:117], v[176:177], v[174:175]
	v_pk_add_f32 v[120:121], v[176:177], v[174:175] neg_lo:[0,1] neg_hi:[0,1]
	v_pk_add_f32 v[182:183], v[178:179], v[166:167] op_sel:[0,1] op_sel_hi:[1,0] neg_hi:[0,1]
	v_pk_add_f32 v[122:123], v[178:179], v[166:167] op_sel:[0,1] op_sel_hi:[1,0] neg_lo:[0,1]
	v_pk_add_f32 v[184:185], v[124:125], v[128:129]
	v_pk_add_f32 v[102:103], v[124:125], v[128:129] neg_lo:[0,1] neg_hi:[0,1]
	v_pk_add_f32 v[188:189], v[110:111], v[130:131]
	v_pk_add_f32 v[186:187], v[110:111], v[130:131] neg_lo:[0,1] neg_hi:[0,1]
	v_pk_add_f32 v[124:125], v[184:185], v[188:189]
	v_pk_add_f32 v[128:129], v[184:185], v[188:189] neg_lo:[0,1] neg_hi:[0,1]
	v_pk_add_f32 v[110:111], v[102:103], v[186:187] op_sel:[0,1] op_sel_hi:[1,0] neg_hi:[0,1]
	v_pk_add_f32 v[130:131], v[102:103], v[186:187] op_sel:[0,1] op_sel_hi:[1,0] neg_lo:[0,1]
	ds_write_b64 v5, v[100:101]
	ds_read_b64 v[180:181], v56 offset:256
	ds_read_b64 v[168:169], v56 offset:512
	ds_read_b64 v[176:177], v56 offset:768
	ds_read_b64 v[178:179], v56 offset:1024
	s_waitcnt lgkmcnt(3)
	v_pk_mul_f32 v[174:175], v[108:109], v[180:181] op_sel:[1,1] op_sel_hi:[0,1]
	v_pk_fma_f32 v[108:109], v[108:109], v[180:181], v[174:175] op_sel_hi:[1,0,1] neg_lo:[0,0,1]
	ds_write_b64 v5, v[108:109] offset:264
	s_waitcnt lgkmcnt(3)
	v_pk_mul_f32 v[166:167], v[116:117], v[168:169] op_sel:[1,1] op_sel_hi:[0,1]
	v_pk_fma_f32 v[116:117], v[116:117], v[168:169], v[166:167] op_sel_hi:[1,0,1] neg_lo:[0,0,1]
	ds_write_b64 v5, v[116:117] offset:528
	s_waitcnt lgkmcnt(3)
	v_pk_mul_f32 v[184:185], v[124:125], v[176:177] op_sel:[1,1] op_sel_hi:[0,1]
	v_pk_fma_f32 v[124:125], v[124:125], v[176:177], v[184:185] op_sel_hi:[1,0,1] neg_lo:[0,0,1]
	ds_write_b64 v5, v[124:125] offset:792
	s_waitcnt lgkmcnt(3)
	v_pk_mul_f32 v[102:103], v[126:127], v[178:179] op_sel:[1,1] op_sel_hi:[0,1]
	v_pk_fma_f32 v[126:127], v[126:127], v[178:179], v[102:103] op_sel_hi:[1,0,1] neg_lo:[0,0,1]
	ds_write_b64 v5, v[126:127] offset:1056
	ds_read_b64 v[188:189], v56 offset:1280
	ds_read_b64 v[186:187], v56 offset:1536
	ds_read_b64 v[174:175], v56 offset:1792
	ds_read_b64 v[166:167], v56 offset:2048
	s_waitcnt lgkmcnt(3)
	v_pk_mul_f32 v[184:185], v[118:119], v[188:189] op_sel:[1,1] op_sel_hi:[0,1]
	v_pk_fma_f32 v[118:119], v[118:119], v[188:189], v[184:185] op_sel_hi:[1,0,1] neg_lo:[0,0,1]
	ds_write_b64 v5, v[118:119] offset:1320
	s_waitcnt lgkmcnt(3)
; #define LAS __attribute__((address_space(3)))
; __device__ __forceinline__ f32x2 cmul(f32x2 a, f32x2 b) { return (f32x2){a.x * b.x - a.y * b.y, a.x * b.y + a.y * b.x}; }
; __device__ __forceinline__ void fft_fwd2(LAS f32x2* B, const LAS f32x2* TW2, int tid) {
;     ...
;     for (int k = 1; k < 16; ++k) B[fpad(base + 32 * k)] = cmul(x[k], TW2[k * 32 + n2]);
; template <int MODE> __device__ __forceinline__ void fft_pair32(LAS f32x2* B, const LAS f32x2* F, int wave, int lane) {
;     ...
;     const int hi = lane >> 5, blk = 32 * wave + (lane & 31); const float sg = hi ? -1.f : 1.f;
;     LAS f32x2* p = B + 33 * blk; f32x2 v[16];
; #pragma unroll
;     for (int j = 0; j < 16; ++j) { const f32x2 d = p[j] + p[j + 16] * sg;
;         const f32x2 w = {hi ? CS[j] : 1.f, hi ? -SN[j] : 0.f}; v[j] = j == 0 ? d : cmul(d, w); }
	v_pk_mul_f32 v[102:103], v[182:183], v[186:187] op_sel:[1,1] op_sel_hi:[0,1]
	v_pk_fma_f32 v[182:183], v[182:183], v[186:187], v[102:103] op_sel_hi:[1,0,1] neg_lo:[0,0,1]
	ds_write_b64 v5, v[182:183] offset:1584
	s_waitcnt lgkmcnt(3)
	v_pk_mul_f32 v[180:181], v[110:111], v[174:175] op_sel:[1,1] op_sel_hi:[0,1]
	v_pk_fma_f32 v[110:111], v[110:111], v[174:175], v[180:181] op_sel_hi:[1,0,1] neg_lo:[0,0,1]
	ds_write_b64 v5, v[110:111] offset:1848
	s_waitcnt lgkmcnt(3)
	v_pk_mul_f32 v[168:169], v[104:105], v[166:167] op_sel:[1,1] op_sel_hi:[0,1]
	v_pk_fma_f32 v[104:105], v[104:105], v[166:167], v[168:169] op_sel_hi:[1,0,1] neg_lo:[0,0,1]
	ds_write_b64 v5, v[104:105] offset:2112
	ds_read_b64 v[176:177], v56 offset:2304
	ds_read_b64 v[178:179], v56 offset:2560
	ds_read_b64 v[184:185], v56 offset:2816
	ds_read_b64 v[102:103], v56 offset:3072
	s_waitcnt lgkmcnt(3)
	v_pk_mul_f32 v[180:181], v[112:113], v[176:177] op_sel:[1,1] op_sel_hi:[0,1]
	v_pk_fma_f32 v[112:113], v[112:113], v[176:177], v[180:181] op_sel_hi:[1,0,1] neg_lo:[0,0,1]
	ds_write_b64 v5, v[112:113] offset:2376
	s_waitcnt lgkmcnt(3)
	v_pk_mul_f32 v[168:169], v[120:121], v[178:179] op_sel:[1,1] op_sel_hi:[0,1]
	v_pk_fma_f32 v[120:121], v[120:121], v[178:179], v[168:169] op_sel_hi:[1,0,1] neg_lo:[0,0,1]
	ds_write_b64 v5, v[120:121] offset:2640
	s_waitcnt lgkmcnt(3)
	v_pk_mul_f32 v[188:189], v[128:129], v[184:185] op_sel:[1,1] op_sel_hi:[0,1]
	v_pk_fma_f32 v[128:129], v[128:129], v[184:185], v[188:189] op_sel_hi:[1,0,1] neg_lo:[0,0,1]
	ds_write_b64 v5, v[128:129] offset:2904
	s_waitcnt lgkmcnt(3)
	v_pk_mul_f32 v[186:187], v[106:107], v[102:103] op_sel:[1,1] op_sel_hi:[0,1]
	v_pk_fma_f32 v[106:107], v[106:107], v[102:103], v[186:187] op_sel_hi:[1,0,1] neg_lo:[0,0,1]
	ds_write_b64 v5, v[106:107] offset:3168
	ds_read_b64 v[174:175], v56 offset:3328
	ds_read_b64 v[166:167], v56 offset:3584
	ds_read_b64 v[180:181], v56 offset:3840
	s_waitcnt lgkmcnt(2)
	v_pk_mul_f32 v[168:169], v[114:115], v[174:175] op_sel:[1,1] op_sel_hi:[0,1]
	v_pk_fma_f32 v[114:115], v[114:115], v[174:175], v[168:169] op_sel_hi:[1,0,1] neg_lo:[0,0,1]
	ds_write_b64 v5, v[114:115] offset:3432
	s_waitcnt lgkmcnt(2)
	v_pk_mul_f32 v[188:189], v[122:123], v[166:167] op_sel:[1,1] op_sel_hi:[0,1]
	v_pk_fma_f32 v[122:123], v[122:123], v[166:167], v[188:189] op_sel_hi:[1,0,1] neg_lo:[0,0,1]
	ds_write_b64 v5, v[122:123] offset:3696
	s_waitcnt lgkmcnt(2)
	v_pk_mul_f32 v[186:187], v[130:131], v[180:181] op_sel:[1,1] op_sel_hi:[0,1]
	v_pk_fma_f32 v[130:131], v[130:131], v[180:181], v[186:187] op_sel_hi:[1,0,1] neg_lo:[0,0,1]
	ds_write_b64 v5, v[130:131] offset:3960
	s_waitcnt lgkmcnt(0)
	ds_read_b64 v[100:101], v156
	ds_read_b64 v[176:177], v156 offset:128
	ds_read_b64 v[108:109], v156 offset:8
	ds_read_b64 v[178:179], v156 offset:136
	ds_read_b64 v[116:117], v156 offset:16
	ds_read_b64 v[184:185], v156 offset:144
	ds_read_b64 v[124:125], v156 offset:24
	ds_read_b64 v[102:103], v156 offset:152
	s_waitcnt lgkmcnt(6)
	v_pk_fma_f32 v[100:101], v[176:177], v[190:191], v[100:101] op_sel_hi:[1,0,1]
	s_waitcnt lgkmcnt(4)
	v_pk_fma_f32 v[108:109], v[178:179], v[190:191], v[108:109] op_sel_hi:[1,0,1]
	v_pk_mul_f32 v[168:169], v[108:109], v[36:37] op_sel:[1,1] op_sel_hi:[0,1]
	v_pk_fma_f32 v[108:109], v[108:109], v[36:37], v[168:169] op_sel_hi:[1,0,1] neg_lo:[0,0,1]
	s_waitcnt lgkmcnt(2)
	v_pk_fma_f32 v[116:117], v[184:185], v[190:191], v[116:117] op_sel_hi:[1,0,1]
	v_pk_mul_f32 v[188:189], v[116:117], v[38:39] op_sel:[1,1] op_sel_hi:[0,1]
	v_pk_fma_f32 v[116:117], v[116:117], v[38:39], v[188:189] op_sel_hi:[1,0,1] neg_lo:[0,0,1]
	s_waitcnt lgkmcnt(0)
	v_pk_fma_f32 v[124:125], v[102:103], v[190:191], v[124:125] op_sel_hi:[1,0,1]
	v_pk_mul_f32 v[186:187], v[124:125], v[40:41] op_sel:[1,1] op_sel_hi:[0,1]
	v_pk_fma_f32 v[124:125], v[124:125], v[40:41], v[186:187] op_sel_hi:[1,0,1] neg_lo:[0,0,1]
	ds_read_b64 v[126:127], v156 offset:32
	ds_read_b64 v[174:175], v156 offset:160
	ds_read_b64 v[118:119], v156 offset:40
	ds_read_b64 v[166:167], v156 offset:168
	ds_read_b64 v[182:183], v156 offset:48
	ds_read_b64 v[180:181], v156 offset:176
	ds_read_b64 v[110:111], v156 offset:56
	ds_read_b64 v[168:169], v156 offset:184
	s_waitcnt lgkmcnt(6)
	v_pk_fma_f32 v[126:127], v[174:175], v[190:191], v[126:127] op_sel_hi:[1,0,1]
	v_pk_mul_f32 v[188:189], v[126:127], v[42:43] op_sel:[1,1] op_sel_hi:[0,1]
	v_pk_fma_f32 v[126:127], v[126:127], v[42:43], v[188:189] op_sel_hi:[1,0,1] neg_lo:[0,0,1]
	s_waitcnt lgkmcnt(4)
	v_pk_fma_f32 v[118:119], v[166:167], v[190:191], v[118:119] op_sel_hi:[1,0,1]
	v_pk_mul_f32 v[186:187], v[118:119], v[44:45] op_sel:[1,1] op_sel_hi:[0,1]
	v_pk_fma_f32 v[118:119], v[118:119], v[44:45], v[186:187] op_sel_hi:[1,0,1] neg_lo:[0,0,1]
	s_waitcnt lgkmcnt(2)
	v_pk_fma_f32 v[182:183], v[180:181], v[190:191], v[182:183] op_sel_hi:[1,0,1]
	v_pk_mul_f32 v[176:177], v[182:183], v[46:47] op_sel:[1,1] op_sel_hi:[0,1]
	v_pk_fma_f32 v[182:183], v[182:183], v[46:47], v[176:177] op_sel_hi:[1,0,1] neg_lo:[0,0,1]
	s_waitcnt lgkmcnt(0)
	v_pk_fma_f32 v[110:111], v[168:169], v[190:191], v[110:111] op_sel_hi:[1,0,1]
	v_pk_mul_f32 v[178:179], v[110:111], v[48:49] op_sel:[1,1] op_sel_hi:[0,1]
	v_pk_fma_f32 v[110:111], v[110:111], v[48:49], v[178:179] op_sel_hi:[1,0,1] neg_lo:[0,0,1]
	ds_read_b64 v[104:105], v156 offset:64
	ds_read_b64 v[184:185], v156 offset:192
	ds_read_b64 v[112:113], v156 offset:72
	ds_read_b64 v[102:103], v156 offset:200
	ds_read_b64 v[120:121], v156 offset:80
	ds_read_b64 v[188:189], v156 offset:208
	ds_read_b64 v[128:129], v156 offset:88
	ds_read_b64 v[186:187], v156 offset:216
	s_waitcnt lgkmcnt(6)
; __device__ __forceinline__ f32x2 cmul(f32x2 a, f32x2 b) { return (f32x2){a.x * b.x - a.y * b.y, a.x * b.y + a.y * b.x}; }
; template <bool INV> __device__ __forceinline__ f32x2 cmul_tw(f32x2 a, f32x2 w) { return INV ? cmulc(a, w) : cmul(a, w); }
; template <bool INV> __device__ __forceinline__ void dft16(f32x2 (&x)[16]) {
;     constexpr float C1 = 0.92387953251128674f, S1 = 0.38268343236508977f, C2 = 0.70710678118654752f;
; #pragma unroll
;     for (int b = 0; b < 4; ++b) dft4<INV>(x[b], x[4 + b], x[8 + b], x[12 + b]);
;     const f32x2 w1 = {C1, -S1}, w2 = {C2, -C2}, w3 = {S1, -C1}, w4 = {0.f, -1.f}, w6 = {-C2, -C2}, w9 = {-C1, S1};
;     x[4 * 1 + 1] = cmul_tw<INV>(x[5], w1); x[4 * 1 + 2] = cmul_tw<INV>(x[6], w2); x[4 * 1 + 3] = cmul_tw<INV>(x[7], w3);
;     x[4 * 2 + 1] = cmul_tw<INV>(x[9], w2); x[4 * 2 + 2] = cmul_tw<INV>(x[10], w4); x[4 * 2 + 3] = cmul_tw<INV>(x[11], w6);
;     x[4 * 3 + 1] = cmul_tw<INV>(x[13], w3); x[4 * 3 + 2] = cmul_tw<INV>(x[14], w6); x[4 * 3 + 3] = cmul_tw<INV>(x[15], w9);
; template <int MODE> __device__ __forceinline__ void fft_pair32(LAS f32x2* B, const LAS f32x2* F, int wave, int lane) {
;     ...
;     for (int j = 0; j < 16; ++j) { const f32x2 d = p[j] + p[j + 16] * sg;
;         const f32x2 w = {hi ? CS[j] : 1.f, hi ? -SN[j] : 0.f}; v[j] = j == 0 ? d : cmul(d, w); }
;     dft16<false>(v);
	v_pk_fma_f32 v[104:105], v[184:185], v[190:191], v[104:105] op_sel_hi:[1,0,1]
	v_pk_mul_f32 v[176:177], v[104:105], v[50:51] op_sel:[1,1] op_sel_hi:[0,1]
	v_pk_fma_f32 v[104:105], v[104:105], v[50:51], v[176:177] op_sel_hi:[1,0,1] neg_lo:[0,0,1]
	s_waitcnt lgkmcnt(4)
	v_pk_fma_f32 v[112:113], v[102:103], v[190:191], v[112:113] op_sel_hi:[1,0,1]
	v_pk_mul_f32 v[178:179], v[112:113], v[52:53] op_sel:[1,1] op_sel_hi:[0,1]
	v_pk_fma_f32 v[112:113], v[112:113], v[52:53], v[178:179] op_sel_hi:[1,0,1] neg_lo:[0,0,1]
	s_waitcnt lgkmcnt(2)
	v_pk_fma_f32 v[120:121], v[188:189], v[190:191], v[120:121] op_sel_hi:[1,0,1]
	v_pk_mul_f32 v[174:175], v[120:121], v[54:55] op_sel:[1,1] op_sel_hi:[0,1]
	v_pk_fma_f32 v[120:121], v[120:121], v[54:55], v[174:175] op_sel_hi:[1,0,1] neg_lo:[0,0,1]
	s_waitcnt lgkmcnt(0)
	v_pk_fma_f32 v[128:129], v[186:187], v[190:191], v[128:129] op_sel_hi:[1,0,1]
	v_pk_mul_f32 v[166:167], v[128:129], v[90:91] op_sel:[1,1] op_sel_hi:[0,1]
	v_pk_fma_f32 v[128:129], v[128:129], v[90:91], v[166:167] op_sel_hi:[1,0,1] neg_lo:[0,0,1]
	ds_read_b64 v[106:107], v156 offset:96
	ds_read_b64 v[180:181], v156 offset:224
	ds_read_b64 v[114:115], v156 offset:104
	ds_read_b64 v[168:169], v156 offset:232
	ds_read_b64 v[122:123], v156 offset:112
	ds_read_b64 v[176:177], v156 offset:240
	ds_read_b64 v[130:131], v156 offset:120
	ds_read_b64 v[178:179], v156 offset:248
	s_waitcnt lgkmcnt(6)
	v_pk_fma_f32 v[106:107], v[180:181], v[190:191], v[106:107] op_sel_hi:[1,0,1]
	v_pk_mul_f32 v[174:175], v[106:107], v[92:93] op_sel:[1,1] op_sel_hi:[0,1]
	v_pk_fma_f32 v[106:107], v[106:107], v[92:93], v[174:175] op_sel_hi:[1,0,1] neg_lo:[0,0,1]
	s_waitcnt lgkmcnt(4)
	v_pk_fma_f32 v[114:115], v[168:169], v[190:191], v[114:115] op_sel_hi:[1,0,1]
	v_pk_mul_f32 v[166:167], v[114:115], v[94:95] op_sel:[1,1] op_sel_hi:[0,1]
	v_pk_fma_f32 v[114:115], v[114:115], v[94:95], v[166:167] op_sel_hi:[1,0,1] neg_lo:[0,0,1]
	s_waitcnt lgkmcnt(2)
	v_pk_fma_f32 v[122:123], v[176:177], v[190:191], v[122:123] op_sel_hi:[1,0,1]
	v_pk_mul_f32 v[184:185], v[122:123], v[96:97] op_sel:[1,1] op_sel_hi:[0,1]
	v_pk_fma_f32 v[122:123], v[122:123], v[96:97], v[184:185] op_sel_hi:[1,0,1] neg_lo:[0,0,1]
	s_waitcnt lgkmcnt(0)
	v_pk_fma_f32 v[130:131], v[178:179], v[190:191], v[130:131] op_sel_hi:[1,0,1]
	v_pk_mul_f32 v[102:103], v[130:131], v[98:99] op_sel:[1,1] op_sel_hi:[0,1]
	v_pk_fma_f32 v[130:131], v[130:131], v[98:99], v[102:103] op_sel_hi:[1,0,1] neg_lo:[0,0,1]
	v_pk_add_f32 v[188:189], v[100:101], v[104:105]
	v_pk_add_f32 v[186:187], v[100:101], v[104:105] neg_lo:[0,1] neg_hi:[0,1]
	v_pk_add_f32 v[174:175], v[126:127], v[106:107]
	v_pk_add_f32 v[166:167], v[126:127], v[106:107] neg_lo:[0,1] neg_hi:[0,1]
	v_pk_add_f32 v[100:101], v[188:189], v[174:175]
	v_pk_add_f32 v[104:105], v[188:189], v[174:175] neg_lo:[0,1] neg_hi:[0,1]
	v_pk_add_f32 v[126:127], v[186:187], v[166:167] op_sel:[0,1] op_sel_hi:[1,0] neg_hi:[0,1]
	v_pk_add_f32 v[106:107], v[186:187], v[166:167] op_sel:[0,1] op_sel_hi:[1,0] neg_lo:[0,1]
	v_pk_add_f32 v[184:185], v[108:109], v[112:113]
	v_pk_add_f32 v[102:103], v[108:109], v[112:113] neg_lo:[0,1] neg_hi:[0,1]
	v_pk_add_f32 v[180:181], v[118:119], v[114:115]
	v_pk_add_f32 v[168:169], v[118:119], v[114:115] neg_lo:[0,1] neg_hi:[0,1]
	v_pk_add_f32 v[108:109], v[184:185], v[180:181]
	v_pk_add_f32 v[112:113], v[184:185], v[180:181] neg_lo:[0,1] neg_hi:[0,1]
	v_pk_add_f32 v[118:119], v[102:103], v[168:169] op_sel:[0,1] op_sel_hi:[1,0] neg_hi:[0,1]
	v_pk_add_f32 v[114:115], v[102:103], v[168:169] op_sel:[0,1] op_sel_hi:[1,0] neg_lo:[0,1]
	v_pk_add_f32 v[176:177], v[116:117], v[120:121]
	v_pk_add_f32 v[178:179], v[116:117], v[120:121] neg_lo:[0,1] neg_hi:[0,1]
	v_pk_add_f32 v[188:189], v[182:183], v[122:123]
	v_pk_add_f32 v[186:187], v[182:183], v[122:123] neg_lo:[0,1] neg_hi:[0,1]
	v_pk_add_f32 v[116:117], v[176:177], v[188:189]
	v_pk_add_f32 v[120:121], v[176:177], v[188:189] neg_lo:[0,1] neg_hi:[0,1]
	v_pk_add_f32 v[182:183], v[178:179], v[186:187] op_sel:[0,1] op_sel_hi:[1,0] neg_hi:[0,1]
	v_pk_add_f32 v[122:123], v[178:179], v[186:187] op_sel:[0,1] op_sel_hi:[1,0] neg_lo:[0,1]
	v_pk_add_f32 v[174:175], v[124:125], v[128:129]
	v_pk_add_f32 v[166:167], v[124:125], v[128:129] neg_lo:[0,1] neg_hi:[0,1]
	v_pk_add_f32 v[184:185], v[110:111], v[130:131]
	v_pk_add_f32 v[102:103], v[110:111], v[130:131] neg_lo:[0,1] neg_hi:[0,1]
	v_pk_add_f32 v[124:125], v[174:175], v[184:185]
	v_pk_add_f32 v[128:129], v[174:175], v[184:185] neg_lo:[0,1] neg_hi:[0,1]
	v_pk_add_f32 v[110:111], v[166:167], v[102:103] op_sel:[0,1] op_sel_hi:[1,0] neg_hi:[0,1]
	v_pk_add_f32 v[130:131], v[166:167], v[102:103] op_sel:[0,1] op_sel_hi:[1,0] neg_lo:[0,1]
	v_pk_mul_f32 v[180:181], v[118:119], s[68:69] op_sel:[1,1] op_sel_hi:[0,1]
	v_pk_fma_f32 v[118:119], v[118:119], s[68:69], v[180:181] op_sel_hi:[1,0,1] neg_lo:[0,0,1]
	v_pk_mul_f32 v[168:169], v[182:183], s[84:85] op_sel:[1,1] op_sel_hi:[0,1]
	v_pk_fma_f32 v[182:183], v[182:183], s[84:85], v[168:169] op_sel_hi:[1,0,1] neg_lo:[0,0,1]
	v_pk_mul_f32 v[176:177], v[110:111], s[88:89] op_sel:[1,1] op_sel_hi:[0,1]
	v_pk_fma_f32 v[110:111], v[110:111], s[88:89], v[176:177] op_sel_hi:[1,0,1] neg_lo:[0,0,1]
	v_pk_mul_f32 v[178:179], v[112:113], s[84:85] op_sel:[1,1] op_sel_hi:[0,1]
	v_pk_fma_f32 v[112:113], v[112:113], s[84:85], v[178:179] op_sel_hi:[1,0,1] neg_lo:[0,0,1]
	v_pk_mul_f32 v[188:189], v[128:129], s[90:91] op_sel:[1,1] op_sel_hi:[0,1]
	v_pk_fma_f32 v[128:129], v[128:129], s[90:91], v[188:189] op_sel_hi:[1,0,1] neg_lo:[0,0,1]
	v_pk_mul_f32 v[186:187], v[114:115], s[88:89] op_sel:[1,1] op_sel_hi:[0,1]
	v_pk_fma_f32 v[114:115], v[114:115], s[88:89], v[186:187] op_sel_hi:[1,0,1] neg_lo:[0,0,1]
; #define LAS __attribute__((address_space(3)))
; __device__ __forceinline__ f32x2 cmul(f32x2 a, f32x2 b) { return (f32x2){a.x * b.x - a.y * b.y, a.x * b.y + a.y * b.x}; }
; template <bool INV> __device__ __forceinline__ void dft16(f32x2 (&x)[16]) {
;     ...
;     for (int c = 0; c < 4; ++c) dft4<INV>(x[4 * c], x[4 * c + 1], x[4 * c + 2], x[4 * c + 3]);
;     f32x2 y[16];
; #pragma unroll
;     for (int k = 0; k < 16; ++k) y[k] = x[4 * (k & 3) + (k >> 2)];
; #pragma unroll
;     for (int k = 0; k < 16; ++k) x[k] = y[k];
; template <int MODE> __device__ __forceinline__ void fft_pair32(LAS f32x2* B, const LAS f32x2* F, int wave, int lane) {
;     ...
;     const int k1 = blk >> 4, k2 = blk & 15, kb1 = (16 - k1) & 15, b1 = k1 != 0 ? 1 : 0, kb2 = (16 - k2 - b1) & 15, b2 = (k2 != 0 || b1) ? 1 : 0;
;     const LAS f32x2* fa = F + 33 * blk; const LAS f32x2* fb = F + 33 * (16 * kb1 + kb2);
;     const LAS f32x2* fah = fa + hi; const LAS f32x2* fbh = fb + (1 - b2) - hi;
;     constexpr float SC = 1.0f / (2.0f * (float)FN);
; #pragma unroll
;     for (int k = 0; k < 16; ++k) { const f32x2 A = fah[2 * k]; f32x2 Bm = fbh[31 - 2 * k];
;         if (k == 0) { const f32x2 m0 = b2 ? fb[31] : fa[0]; Bm = hi ? Bm : m0; }
;         const f32x2 H = MODE == 0 ? (f32x2){(A.x + Bm.x) * SC, (A.y - Bm.y) * SC} : (f32x2){(A.y + Bm.y) * SC, (Bm.x - A.x) * SC};
;         v[k] = cmul(v[k], H); }
	v_pk_mul_f32 v[174:175], v[122:123], s[90:91] op_sel:[1,1] op_sel_hi:[0,1]
	v_pk_fma_f32 v[122:123], v[122:123], s[90:91], v[174:175] op_sel_hi:[1,0,1] neg_lo:[0,0,1]
	v_pk_mul_f32 v[166:167], v[130:131], s[98:99] op_sel:[1,1] op_sel_hi:[0,1]
	v_pk_fma_f32 v[130:131], v[130:131], s[98:99], v[166:167] op_sel_hi:[1,0,1] neg_lo:[0,0,1]
	v_pk_add_f32 v[184:185], v[100:101], v[116:117]
	v_pk_add_f32 v[102:103], v[100:101], v[116:117] neg_lo:[0,1] neg_hi:[0,1]
	v_pk_add_f32 v[180:181], v[108:109], v[124:125]
	v_pk_add_f32 v[168:169], v[108:109], v[124:125] neg_lo:[0,1] neg_hi:[0,1]
	v_pk_add_f32 v[100:101], v[184:185], v[180:181]
	v_pk_add_f32 v[116:117], v[184:185], v[180:181] neg_lo:[0,1] neg_hi:[0,1]
	v_pk_add_f32 v[108:109], v[102:103], v[168:169] op_sel:[0,1] op_sel_hi:[1,0] neg_hi:[0,1]
	v_pk_add_f32 v[124:125], v[102:103], v[168:169] op_sel:[0,1] op_sel_hi:[1,0] neg_lo:[0,1]
	v_pk_add_f32 v[176:177], v[126:127], v[182:183]
	v_pk_add_f32 v[178:179], v[126:127], v[182:183] neg_lo:[0,1] neg_hi:[0,1]
	v_pk_add_f32 v[188:189], v[118:119], v[110:111]
	v_pk_add_f32 v[186:187], v[118:119], v[110:111] neg_lo:[0,1] neg_hi:[0,1]
	v_pk_add_f32 v[126:127], v[176:177], v[188:189]
	v_pk_add_f32 v[182:183], v[176:177], v[188:189] neg_lo:[0,1] neg_hi:[0,1]
	v_pk_add_f32 v[118:119], v[178:179], v[186:187] op_sel:[0,1] op_sel_hi:[1,0] neg_hi:[0,1]
	v_pk_add_f32 v[110:111], v[178:179], v[186:187] op_sel:[0,1] op_sel_hi:[1,0] neg_lo:[0,1]
	v_pk_add_f32 v[174:175], v[104:105], v[120:121] op_sel:[0,1] op_sel_hi:[1,0] neg_hi:[0,1]
	v_pk_add_f32 v[166:167], v[104:105], v[120:121] op_sel:[0,1] op_sel_hi:[1,0] neg_lo:[0,1]
	v_pk_add_f32 v[184:185], v[112:113], v[128:129]
	v_pk_add_f32 v[102:103], v[112:113], v[128:129] neg_lo:[0,1] neg_hi:[0,1]
	v_pk_add_f32 v[104:105], v[174:175], v[184:185]
	v_pk_add_f32 v[120:121], v[174:175], v[184:185] neg_lo:[0,1] neg_hi:[0,1]
	v_pk_add_f32 v[112:113], v[166:167], v[102:103] op_sel:[0,1] op_sel_hi:[1,0] neg_hi:[0,1]
	v_pk_add_f32 v[128:129], v[166:167], v[102:103] op_sel:[0,1] op_sel_hi:[1,0] neg_lo:[0,1]
	v_pk_add_f32 v[180:181], v[106:107], v[122:123]
	v_pk_add_f32 v[168:169], v[106:107], v[122:123] neg_lo:[0,1] neg_hi:[0,1]
	v_pk_add_f32 v[176:177], v[114:115], v[130:131]
	v_pk_add_f32 v[178:179], v[114:115], v[130:131] neg_lo:[0,1] neg_hi:[0,1]
	v_pk_add_f32 v[106:107], v[180:181], v[176:177]
	v_pk_add_f32 v[122:123], v[180:181], v[176:177] neg_lo:[0,1] neg_hi:[0,1]
	v_pk_add_f32 v[114:115], v[168:169], v[178:179] op_sel:[0,1] op_sel_hi:[1,0] neg_hi:[0,1]
	v_pk_add_f32 v[130:131], v[168:169], v[178:179] op_sel:[0,1] op_sel_hi:[1,0] neg_lo:[0,1]
	ds_read_b64 v[188:189], v200
	ds_read_b64 v[184:185], v204
	ds_read_b64 v[186:187], v200 offset:16
	ds_read_b64 v[102:103], v202 offset:232
	ds_read_b64 v[174:175], v200 offset:32
	ds_read_b64 v[180:181], v202 offset:216
	ds_read_b64 v[166:167], v200 offset:48
	ds_read_b64 v[168:169], v202 offset:200
	s_waitcnt lgkmcnt(6)
	v_pk_add_f32 v[188:189], v[188:189], v[184:185] op_sel:[1,1] op_sel_hi:[0,0] neg_hi:[1,0]
	v_pk_mul_f32 v[176:177], v[100:101], v[188:189] op_sel:[1,1] op_sel_hi:[0,1]
	v_pk_fma_f32 v[100:101], v[100:101], v[188:189], v[176:177] op_sel_hi:[1,0,1] neg_lo:[0,0,1]
	s_waitcnt lgkmcnt(4)
	v_pk_add_f32 v[186:187], v[186:187], v[102:103] op_sel:[1,1] op_sel_hi:[0,0] neg_hi:[1,0]
	v_pk_mul_f32 v[178:179], v[126:127], v[186:187] op_sel:[1,1] op_sel_hi:[0,1]
	v_pk_fma_f32 v[126:127], v[126:127], v[186:187], v[178:179] op_sel_hi:[1,0,1] neg_lo:[0,0,1]
	s_waitcnt lgkmcnt(2)
	v_pk_add_f32 v[174:175], v[174:175], v[180:181] op_sel:[1,1] op_sel_hi:[0,0] neg_hi:[1,0]
	v_pk_mul_f32 v[176:177], v[104:105], v[174:175] op_sel:[1,1] op_sel_hi:[0,1]
	v_pk_fma_f32 v[104:105], v[104:105], v[174:175], v[176:177] op_sel_hi:[1,0,1] neg_lo:[0,0,1]
	s_waitcnt lgkmcnt(0)
	v_pk_add_f32 v[166:167], v[166:167], v[168:169] op_sel:[1,1] op_sel_hi:[0,0] neg_hi:[1,0]
	v_pk_mul_f32 v[178:179], v[106:107], v[166:167] op_sel:[1,1] op_sel_hi:[0,1]
	v_pk_fma_f32 v[106:107], v[106:107], v[166:167], v[178:179] op_sel_hi:[1,0,1] neg_lo:[0,0,1]
	ds_read_b64 v[176:177], v200 offset:64
	ds_read_b64 v[174:175], v202 offset:184
	ds_read_b64 v[178:179], v200 offset:80
	ds_read_b64 v[166:167], v202 offset:168
	ds_read_b64 v[188:189], v200 offset:96
	ds_read_b64 v[184:185], v202 offset:152
	ds_read_b64 v[186:187], v200 offset:112
	ds_read_b64 v[102:103], v202 offset:136
	s_waitcnt lgkmcnt(6)
	v_pk_add_f32 v[176:177], v[176:177], v[174:175] op_sel:[1,1] op_sel_hi:[0,0] neg_hi:[1,0]
	v_pk_mul_f32 v[180:181], v[108:109], v[176:177] op_sel:[1,1] op_sel_hi:[0,1]
	v_pk_fma_f32 v[108:109], v[108:109], v[176:177], v[180:181] op_sel_hi:[1,0,1] neg_lo:[0,0,1]
	s_waitcnt lgkmcnt(4)
	v_pk_add_f32 v[178:179], v[178:179], v[166:167] op_sel:[1,1] op_sel_hi:[0,0] neg_hi:[1,0]
	v_pk_mul_f32 v[168:169], v[118:119], v[178:179] op_sel:[1,1] op_sel_hi:[0,1]
	v_pk_fma_f32 v[118:119], v[118:119], v[178:179], v[168:169] op_sel_hi:[1,0,1] neg_lo:[0,0,1]
	s_waitcnt lgkmcnt(2)
	v_pk_add_f32 v[188:189], v[188:189], v[184:185] op_sel:[1,1] op_sel_hi:[0,0] neg_hi:[1,0]
	v_pk_mul_f32 v[180:181], v[112:113], v[188:189] op_sel:[1,1] op_sel_hi:[0,1]
	v_pk_fma_f32 v[112:113], v[112:113], v[188:189], v[180:181] op_sel_hi:[1,0,1] neg_lo:[0,0,1]
	s_waitcnt lgkmcnt(0)
	v_pk_add_f32 v[186:187], v[186:187], v[102:103] op_sel:[1,1] op_sel_hi:[0,0] neg_hi:[1,0]
	v_pk_mul_f32 v[168:169], v[114:115], v[186:187] op_sel:[1,1] op_sel_hi:[0,1]
	v_pk_fma_f32 v[114:115], v[114:115], v[186:187], v[168:169] op_sel_hi:[1,0,1] neg_lo:[0,0,1]
	ds_read_b64 v[180:181], v200 offset:128
	ds_read_b64 v[188:189], v202 offset:120
	ds_read_b64 v[168:169], v200 offset:144
	ds_read_b64 v[186:187], v202 offset:104
	ds_read_b64 v[176:177], v200 offset:160
	ds_read_b64 v[174:175], v202 offset:88
	ds_read_b64 v[178:179], v200 offset:176
	ds_read_b64 v[166:167], v202 offset:72
	s_waitcnt lgkmcnt(6)
; __device__ __forceinline__ f32x2 cmul(f32x2 a, f32x2 b) { return (f32x2){a.x * b.x - a.y * b.y, a.x * b.y + a.y * b.x}; }
; template <bool INV> __device__ __forceinline__ f32x2 cmul_tw(f32x2 a, f32x2 w) { return INV ? cmulc(a, w) : cmul(a, w); }
; template <bool INV> __device__ __forceinline__ void dft16(f32x2 (&x)[16]) {
;     constexpr float C1 = 0.92387953251128674f, S1 = 0.38268343236508977f, C2 = 0.70710678118654752f;
; #pragma unroll
;     for (int b = 0; b < 4; ++b) dft4<INV>(x[b], x[4 + b], x[8 + b], x[12 + b]);
;     const f32x2 w1 = {C1, -S1}, w2 = {C2, -C2}, w3 = {S1, -C1}, w4 = {0.f, -1.f}, w6 = {-C2, -C2}, w9 = {-C1, S1};
;     x[4 * 1 + 1] = cmul_tw<INV>(x[5], w1); x[4 * 1 + 2] = cmul_tw<INV>(x[6], w2); x[4 * 1 + 3] = cmul_tw<INV>(x[7], w3);
;     x[4 * 2 + 1] = cmul_tw<INV>(x[9], w2); x[4 * 2 + 2] = cmul_tw<INV>(x[10], w4); x[4 * 2 + 3] = cmul_tw<INV>(x[11], w6);
;     x[4 * 3 + 1] = cmul_tw<INV>(x[13], w3); x[4 * 3 + 2] = cmul_tw<INV>(x[14], w6); x[4 * 3 + 3] = cmul_tw<INV>(x[15], w9);
; template <int MODE> __device__ __forceinline__ void fft_pair32(LAS f32x2* B, const LAS f32x2* F, int wave, int lane) {
;     ...
;     for (int k = 0; k < 16; ++k) { const f32x2 A = fah[2 * k]; f32x2 Bm = fbh[31 - 2 * k];
;         if (k == 0) { const f32x2 m0 = b2 ? fb[31] : fa[0]; Bm = hi ? Bm : m0; }
;         const f32x2 H = MODE == 0 ? (f32x2){(A.x + Bm.x) * SC, (A.y - Bm.y) * SC} : (f32x2){(A.y + Bm.y) * SC, (Bm.x - A.x) * SC};
;         v[k] = cmul(v[k], H); }
;     dft16<true>(v);
	v_pk_add_f32 v[180:181], v[180:181], v[188:189] op_sel:[1,1] op_sel_hi:[0,0] neg_hi:[1,0]
	v_pk_mul_f32 v[184:185], v[116:117], v[180:181] op_sel:[1,1] op_sel_hi:[0,1]
	v_pk_fma_f32 v[116:117], v[116:117], v[180:181], v[184:185] op_sel_hi:[1,0,1] neg_lo:[0,0,1]
	s_waitcnt lgkmcnt(4)
	v_pk_add_f32 v[168:169], v[168:169], v[186:187] op_sel:[1,1] op_sel_hi:[0,0] neg_hi:[1,0]
	v_pk_mul_f32 v[102:103], v[182:183], v[168:169] op_sel:[1,1] op_sel_hi:[0,1]
	v_pk_fma_f32 v[182:183], v[182:183], v[168:169], v[102:103] op_sel_hi:[1,0,1] neg_lo:[0,0,1]
	s_waitcnt lgkmcnt(2)
	v_pk_add_f32 v[176:177], v[176:177], v[174:175] op_sel:[1,1] op_sel_hi:[0,0] neg_hi:[1,0]
	v_pk_mul_f32 v[184:185], v[120:121], v[176:177] op_sel:[1,1] op_sel_hi:[0,1]
	v_pk_fma_f32 v[120:121], v[120:121], v[176:177], v[184:185] op_sel_hi:[1,0,1] neg_lo:[0,0,1]
	s_waitcnt lgkmcnt(0)
	v_pk_add_f32 v[178:179], v[178:179], v[166:167] op_sel:[1,1] op_sel_hi:[0,0] neg_hi:[1,0]
	v_pk_mul_f32 v[102:103], v[122:123], v[178:179] op_sel:[1,1] op_sel_hi:[0,1]
	v_pk_fma_f32 v[122:123], v[122:123], v[178:179], v[102:103] op_sel_hi:[1,0,1] neg_lo:[0,0,1]
	ds_read_b64 v[184:185], v200 offset:192
	ds_read_b64 v[176:177], v202 offset:56
	ds_read_b64 v[102:103], v200 offset:208
	ds_read_b64 v[178:179], v202 offset:40
	ds_read_b64 v[180:181], v200 offset:224
	ds_read_b64 v[188:189], v202 offset:24
	ds_read_b64 v[168:169], v200 offset:240
	ds_read_b64 v[186:187], v202 offset:8
	s_waitcnt lgkmcnt(6)
	v_pk_add_f32 v[184:185], v[184:185], v[176:177] op_sel:[1,1] op_sel_hi:[0,0] neg_hi:[1,0]
	v_pk_mul_f32 v[174:175], v[124:125], v[184:185] op_sel:[1,1] op_sel_hi:[0,1]
	v_pk_fma_f32 v[124:125], v[124:125], v[184:185], v[174:175] op_sel_hi:[1,0,1] neg_lo:[0,0,1]
	s_waitcnt lgkmcnt(4)
	v_pk_add_f32 v[102:103], v[102:103], v[178:179] op_sel:[1,1] op_sel_hi:[0,0] neg_hi:[1,0]
	v_pk_mul_f32 v[166:167], v[110:111], v[102:103] op_sel:[1,1] op_sel_hi:[0,1]
	v_pk_fma_f32 v[110:111], v[110:111], v[102:103], v[166:167] op_sel_hi:[1,0,1] neg_lo:[0,0,1]
	s_waitcnt lgkmcnt(2)
	v_pk_add_f32 v[180:181], v[180:181], v[188:189] op_sel:[1,1] op_sel_hi:[0,0] neg_hi:[1,0]
	v_pk_mul_f32 v[174:175], v[128:129], v[180:181] op_sel:[1,1] op_sel_hi:[0,1]
	v_pk_fma_f32 v[128:129], v[128:129], v[180:181], v[174:175] op_sel_hi:[1,0,1] neg_lo:[0,0,1]
	s_waitcnt lgkmcnt(0)
	v_pk_add_f32 v[168:169], v[168:169], v[186:187] op_sel:[1,1] op_sel_hi:[0,0] neg_hi:[1,0]
	v_pk_mul_f32 v[166:167], v[130:131], v[168:169] op_sel:[1,1] op_sel_hi:[0,1]
	v_pk_fma_f32 v[130:131], v[130:131], v[168:169], v[166:167] op_sel_hi:[1,0,1] neg_lo:[0,0,1]
	v_pk_add_f32 v[174:175], v[100:101], v[116:117]
	v_pk_add_f32 v[166:167], v[100:101], v[116:117] neg_lo:[0,1] neg_hi:[0,1]
	v_pk_add_f32 v[184:185], v[108:109], v[124:125]
	v_pk_add_f32 v[102:103], v[108:109], v[124:125] neg_lo:[0,1] neg_hi:[0,1]
	v_pk_add_f32 v[100:101], v[174:175], v[184:185]
	v_pk_add_f32 v[116:117], v[174:175], v[184:185] neg_lo:[0,1] neg_hi:[0,1]
	v_pk_add_f32 v[108:109], v[166:167], v[102:103] op_sel:[0,1] op_sel_hi:[1,0] neg_lo:[0,1]
	v_pk_add_f32 v[124:125], v[166:167], v[102:103] op_sel:[0,1] op_sel_hi:[1,0] neg_hi:[0,1]
	v_pk_add_f32 v[180:181], v[126:127], v[182:183]
	v_pk_add_f32 v[168:169], v[126:127], v[182:183] neg_lo:[0,1] neg_hi:[0,1]
	v_pk_add_f32 v[176:177], v[118:119], v[110:111]
	v_pk_add_f32 v[178:179], v[118:119], v[110:111] neg_lo:[0,1] neg_hi:[0,1]
	v_pk_add_f32 v[126:127], v[180:181], v[176:177]
	v_pk_add_f32 v[182:183], v[180:181], v[176:177] neg_lo:[0,1] neg_hi:[0,1]
	v_pk_add_f32 v[118:119], v[168:169], v[178:179] op_sel:[0,1] op_sel_hi:[1,0] neg_lo:[0,1]
	v_pk_add_f32 v[110:111], v[168:169], v[178:179] op_sel:[0,1] op_sel_hi:[1,0] neg_hi:[0,1]
	v_pk_add_f32 v[188:189], v[104:105], v[120:121]
	v_pk_add_f32 v[186:187], v[104:105], v[120:121] neg_lo:[0,1] neg_hi:[0,1]
	v_pk_add_f32 v[174:175], v[112:113], v[128:129]
	v_pk_add_f32 v[166:167], v[112:113], v[128:129] neg_lo:[0,1] neg_hi:[0,1]
	v_pk_add_f32 v[104:105], v[188:189], v[174:175]
	v_pk_add_f32 v[120:121], v[188:189], v[174:175] neg_lo:[0,1] neg_hi:[0,1]
	v_pk_add_f32 v[112:113], v[186:187], v[166:167] op_sel:[0,1] op_sel_hi:[1,0] neg_lo:[0,1]
	v_pk_add_f32 v[128:129], v[186:187], v[166:167] op_sel:[0,1] op_sel_hi:[1,0] neg_hi:[0,1]
	v_pk_add_f32 v[184:185], v[106:107], v[122:123]
	v_pk_add_f32 v[102:103], v[106:107], v[122:123] neg_lo:[0,1] neg_hi:[0,1]
	v_pk_add_f32 v[180:181], v[114:115], v[130:131]
	v_pk_add_f32 v[168:169], v[114:115], v[130:131] neg_lo:[0,1] neg_hi:[0,1]
	v_pk_add_f32 v[106:107], v[184:185], v[180:181]
	v_pk_add_f32 v[122:123], v[184:185], v[180:181] neg_lo:[0,1] neg_hi:[0,1]
	v_pk_add_f32 v[114:115], v[102:103], v[168:169] op_sel:[0,1] op_sel_hi:[1,0] neg_lo:[0,1]
	v_pk_add_f32 v[130:131], v[102:103], v[168:169] op_sel:[0,1] op_sel_hi:[1,0] neg_hi:[0,1]
	v_pk_mul_f32 v[176:177], v[118:119], s[68:69] op_sel:[1,1] op_sel_hi:[0,1]
	v_pk_fma_f32 v[118:119], v[118:119], s[68:69], v[176:177] op_sel_hi:[1,0,1] neg_hi:[0,0,1]
	v_pk_mul_f32 v[178:179], v[112:113], s[84:85] op_sel:[1,1] op_sel_hi:[0,1]
	v_pk_fma_f32 v[112:113], v[112:113], s[84:85], v[178:179] op_sel_hi:[1,0,1] neg_hi:[0,0,1]
	v_pk_mul_f32 v[188:189], v[114:115], s[88:89] op_sel:[1,1] op_sel_hi:[0,1]
	v_pk_fma_f32 v[114:115], v[114:115], s[88:89], v[188:189] op_sel_hi:[1,0,1] neg_hi:[0,0,1]
	v_pk_mul_f32 v[186:187], v[182:183], s[84:85] op_sel:[1,1] op_sel_hi:[0,1]
	v_pk_fma_f32 v[182:183], v[182:183], s[84:85], v[186:187] op_sel_hi:[1,0,1] neg_hi:[0,0,1]
	v_pk_mul_f32 v[174:175], v[122:123], s[90:91] op_sel:[1,1] op_sel_hi:[0,1]
	v_pk_fma_f32 v[122:123], v[122:123], s[90:91], v[174:175] op_sel_hi:[1,0,1] neg_hi:[0,0,1]
; __device__ __forceinline__ f32x2 cmulc(f32x2 a, f32x2 b) { return (f32x2){a.x * b.x + a.y * b.y, a.y * b.x - a.x * b.y}; }
; template <bool INV> __device__ __forceinline__ void dft16(f32x2 (&x)[16]) {
;     ...
;     for (int c = 0; c < 4; ++c) dft4<INV>(x[4 * c], x[4 * c + 1], x[4 * c + 2], x[4 * c + 3]);
;     f32x2 y[16];
; #pragma unroll
;     for (int k = 0; k < 16; ++k) y[k] = x[4 * (k & 3) + (k >> 2)];
; #pragma unroll
;     for (int k = 0; k < 16; ++k) x[k] = y[k];
; template <int MODE> __device__ __forceinline__ void fft_pair32(LAS f32x2* B, const LAS f32x2* F, int wave, int lane) {
;     ...
;     for (int j = 0; j < 16; ++j) { const f32x2 w = {hi ? CS[j] : 1.f, hi ? -SN[j] : 0.f}; const f32x2 u = j == 0 ? v[j] : cmulc(v[j], w);
;         const auto rx = __builtin_amdgcn_permlane32_swap(__float_as_uint(u.x), __float_as_uint(u.x), false, false);
;         const auto ry = __builtin_amdgcn_permlane32_swap(__float_as_uint(u.y), __float_as_uint(u.y), false, false);
;         const f32x2 a = {__uint_as_float(rx[0]), __uint_as_float(ry[0])}, b = {__uint_as_float(rx[1]), __uint_as_float(ry[1])};
;         p[16 * hi + j] = a + b * sg; }
	v_pk_mul_f32 v[166:167], v[110:111], s[88:89] op_sel:[1,1] op_sel_hi:[0,1]
	v_pk_fma_f32 v[110:111], v[110:111], s[88:89], v[166:167] op_sel_hi:[1,0,1] neg_hi:[0,0,1]
	v_pk_mul_f32 v[184:185], v[128:129], s[90:91] op_sel:[1,1] op_sel_hi:[0,1]
	v_pk_fma_f32 v[128:129], v[128:129], s[90:91], v[184:185] op_sel_hi:[1,0,1] neg_hi:[0,0,1]
	v_pk_mul_f32 v[102:103], v[130:131], s[98:99] op_sel:[1,1] op_sel_hi:[0,1]
	v_pk_fma_f32 v[130:131], v[130:131], s[98:99], v[102:103] op_sel_hi:[1,0,1] neg_hi:[0,0,1]
	v_pk_add_f32 v[180:181], v[100:101], v[104:105]
	v_pk_add_f32 v[168:169], v[100:101], v[104:105] neg_lo:[0,1] neg_hi:[0,1]
	v_pk_add_f32 v[176:177], v[126:127], v[106:107]
	v_pk_add_f32 v[178:179], v[126:127], v[106:107] neg_lo:[0,1] neg_hi:[0,1]
	v_pk_add_f32 v[100:101], v[180:181], v[176:177]
	v_pk_add_f32 v[104:105], v[180:181], v[176:177] neg_lo:[0,1] neg_hi:[0,1]
	v_pk_add_f32 v[126:127], v[168:169], v[178:179] op_sel:[0,1] op_sel_hi:[1,0] neg_lo:[0,1]
	v_pk_add_f32 v[106:107], v[168:169], v[178:179] op_sel:[0,1] op_sel_hi:[1,0] neg_hi:[0,1]
	v_pk_add_f32 v[188:189], v[108:109], v[112:113]
	v_pk_add_f32 v[186:187], v[108:109], v[112:113] neg_lo:[0,1] neg_hi:[0,1]
	v_pk_add_f32 v[174:175], v[118:119], v[114:115]
	v_pk_add_f32 v[166:167], v[118:119], v[114:115] neg_lo:[0,1] neg_hi:[0,1]
	v_pk_add_f32 v[108:109], v[188:189], v[174:175]
	v_pk_add_f32 v[112:113], v[188:189], v[174:175] neg_lo:[0,1] neg_hi:[0,1]
	v_pk_add_f32 v[118:119], v[186:187], v[166:167] op_sel:[0,1] op_sel_hi:[1,0] neg_lo:[0,1]
	v_pk_add_f32 v[114:115], v[186:187], v[166:167] op_sel:[0,1] op_sel_hi:[1,0] neg_hi:[0,1]
	v_pk_add_f32 v[184:185], v[116:117], v[120:121] op_sel:[0,1] op_sel_hi:[1,0] neg_lo:[0,1]
	v_pk_add_f32 v[102:103], v[116:117], v[120:121] op_sel:[0,1] op_sel_hi:[1,0] neg_hi:[0,1]
	v_pk_add_f32 v[180:181], v[182:183], v[122:123]
	v_pk_add_f32 v[168:169], v[182:183], v[122:123] neg_lo:[0,1] neg_hi:[0,1]
	v_pk_add_f32 v[116:117], v[184:185], v[180:181]
	v_pk_add_f32 v[120:121], v[184:185], v[180:181] neg_lo:[0,1] neg_hi:[0,1]
	v_pk_add_f32 v[182:183], v[102:103], v[168:169] op_sel:[0,1] op_sel_hi:[1,0] neg_lo:[0,1]
	v_pk_add_f32 v[122:123], v[102:103], v[168:169] op_sel:[0,1] op_sel_hi:[1,0] neg_hi:[0,1]
	v_pk_add_f32 v[176:177], v[124:125], v[128:129]
	v_pk_add_f32 v[178:179], v[124:125], v[128:129] neg_lo:[0,1] neg_hi:[0,1]
	v_pk_add_f32 v[188:189], v[110:111], v[130:131]
	v_pk_add_f32 v[186:187], v[110:111], v[130:131] neg_lo:[0,1] neg_hi:[0,1]
	v_pk_add_f32 v[124:125], v[176:177], v[188:189]
	v_pk_add_f32 v[128:129], v[176:177], v[188:189] neg_lo:[0,1] neg_hi:[0,1]
	v_pk_add_f32 v[110:111], v[178:179], v[186:187] op_sel:[0,1] op_sel_hi:[1,0] neg_lo:[0,1]
	v_pk_add_f32 v[130:131], v[178:179], v[186:187] op_sel:[0,1] op_sel_hi:[1,0] neg_hi:[0,1]
	v_mov_b32_e32 v174, v100
	v_mov_b32_e32 v175, v101
	v_pk_mul_f32 v[180:181], v[108:109], v[36:37] op_sel:[1,1] op_sel_hi:[0,1]
	v_pk_fma_f32 v[166:167], v[108:109], v[36:37], v[180:181] op_sel_hi:[1,0,1] neg_hi:[0,0,1]
	v_pk_fma_f32 v[108:109], v[108:109], v[36:37], v[180:181] op_sel_hi:[1,0,1] neg_hi:[0,0,1]
	v_pk_mul_f32 v[168:169], v[116:117], v[38:39] op_sel:[1,1] op_sel_hi:[0,1]
	v_pk_fma_f32 v[184:185], v[116:117], v[38:39], v[168:169] op_sel_hi:[1,0,1] neg_hi:[0,0,1]
	v_pk_fma_f32 v[116:117], v[116:117], v[38:39], v[168:169] op_sel_hi:[1,0,1] neg_hi:[0,0,1]
	v_pk_mul_f32 v[176:177], v[124:125], v[40:41] op_sel:[1,1] op_sel_hi:[0,1]
	v_pk_fma_f32 v[102:103], v[124:125], v[40:41], v[176:177] op_sel_hi:[1,0,1] neg_hi:[0,0,1]
	v_pk_fma_f32 v[124:125], v[124:125], v[40:41], v[176:177] op_sel_hi:[1,0,1] neg_hi:[0,0,1]
	s_nop 1
	v_permlane32_swap_b32_e32 v100, v174
	v_permlane32_swap_b32_e32 v101, v175
	v_permlane32_swap_b32_e32 v108, v166
	v_permlane32_swap_b32_e32 v109, v167
	v_permlane32_swap_b32_e32 v116, v184
	v_permlane32_swap_b32_e32 v117, v185
	v_permlane32_swap_b32_e32 v124, v102
	v_permlane32_swap_b32_e32 v125, v103
	v_pk_fma_f32 v[100:101], v[174:175], v[190:191], v[100:101] op_sel_hi:[1,0,1]
	ds_write_b64 v198, v[100:101]
	v_pk_fma_f32 v[108:109], v[166:167], v[190:191], v[108:109] op_sel_hi:[1,0,1]
	ds_write_b64 v198, v[108:109] offset:8
	v_pk_fma_f32 v[116:117], v[184:185], v[190:191], v[116:117] op_sel_hi:[1,0,1]
	ds_write_b64 v198, v[116:117] offset:16
	v_pk_fma_f32 v[124:125], v[102:103], v[190:191], v[124:125] op_sel_hi:[1,0,1]
	ds_write_b64 v198, v[124:125] offset:24
	v_pk_mul_f32 v[168:169], v[126:127], v[42:43] op_sel:[1,1] op_sel_hi:[0,1]
	v_pk_fma_f32 v[178:179], v[126:127], v[42:43], v[168:169] op_sel_hi:[1,0,1] neg_hi:[0,0,1]
	v_pk_fma_f32 v[126:127], v[126:127], v[42:43], v[168:169] op_sel_hi:[1,0,1] neg_hi:[0,0,1]
	v_pk_mul_f32 v[176:177], v[118:119], v[44:45] op_sel:[1,1] op_sel_hi:[0,1]
	v_pk_fma_f32 v[188:189], v[118:119], v[44:45], v[176:177] op_sel_hi:[1,0,1] neg_hi:[0,0,1]
	v_pk_fma_f32 v[118:119], v[118:119], v[44:45], v[176:177] op_sel_hi:[1,0,1] neg_hi:[0,0,1]
	v_pk_mul_f32 v[174:175], v[182:183], v[46:47] op_sel:[1,1] op_sel_hi:[0,1]
	v_pk_fma_f32 v[186:187], v[182:183], v[46:47], v[174:175] op_sel_hi:[1,0,1] neg_hi:[0,0,1]
	v_pk_fma_f32 v[182:183], v[182:183], v[46:47], v[174:175] op_sel_hi:[1,0,1] neg_hi:[0,0,1]
	v_pk_mul_f32 v[166:167], v[110:111], v[48:49] op_sel:[1,1] op_sel_hi:[0,1]
	v_pk_fma_f32 v[180:181], v[110:111], v[48:49], v[166:167] op_sel_hi:[1,0,1] neg_hi:[0,0,1]
	v_pk_fma_f32 v[110:111], v[110:111], v[48:49], v[166:167] op_sel_hi:[1,0,1] neg_hi:[0,0,1]
	s_nop 1
	v_permlane32_swap_b32_e32 v126, v178
	v_permlane32_swap_b32_e32 v127, v179
	v_permlane32_swap_b32_e32 v118, v188
	v_permlane32_swap_b32_e32 v119, v189
	v_permlane32_swap_b32_e32 v182, v186
; #define LAS __attribute__((address_space(3)))
; __device__ __forceinline__ f32x2 cmulc(f32x2 a, f32x2 b) { return (f32x2){a.x * b.x + a.y * b.y, a.y * b.x - a.x * b.y}; }
; __device__ __forceinline__ void fft_inv2(LAS f32x2* B, const LAS f32x2* TW2, int tid) {
;     asm volatile("" : "+v"(tid));
;     const int b = tid >> 5, n2 = tid & 31, base = 512 * b + n2; f32x2 x[16];
;     x[0] = B[fpad(base)];
; #pragma unroll
;     for (int k = 1; k < 16; ++k) x[k] = cmulc(B[fpad(base + 32 * k)], TW2[k * 32 + n2]);
; template <int MODE> __device__ __forceinline__ void fft_pair32(LAS f32x2* B, const LAS f32x2* F, int wave, int lane) {
;     ...
;     for (int j = 0; j < 16; ++j) { const f32x2 w = {hi ? CS[j] : 1.f, hi ? -SN[j] : 0.f}; const f32x2 u = j == 0 ? v[j] : cmulc(v[j], w);
;         const auto rx = __builtin_amdgcn_permlane32_swap(__float_as_uint(u.x), __float_as_uint(u.x), false, false);
;         const auto ry = __builtin_amdgcn_permlane32_swap(__float_as_uint(u.y), __float_as_uint(u.y), false, false);
;         const f32x2 a = {__uint_as_float(rx[0]), __uint_as_float(ry[0])}, b = {__uint_as_float(rx[1]), __uint_as_float(ry[1])};
;         p[16 * hi + j] = a + b * sg; }
	v_permlane32_swap_b32_e32 v183, v187
	v_permlane32_swap_b32_e32 v110, v180
	v_permlane32_swap_b32_e32 v111, v181
	v_pk_fma_f32 v[126:127], v[178:179], v[190:191], v[126:127] op_sel_hi:[1,0,1]
	ds_write_b64 v198, v[126:127] offset:32
	v_pk_fma_f32 v[118:119], v[188:189], v[190:191], v[118:119] op_sel_hi:[1,0,1]
	ds_write_b64 v198, v[118:119] offset:40
	v_pk_fma_f32 v[182:183], v[186:187], v[190:191], v[182:183] op_sel_hi:[1,0,1]
	ds_write_b64 v198, v[182:183] offset:48
	v_pk_fma_f32 v[110:111], v[180:181], v[190:191], v[110:111] op_sel_hi:[1,0,1]
	ds_write_b64 v198, v[110:111] offset:56
	v_pk_mul_f32 v[174:175], v[104:105], v[50:51] op_sel:[1,1] op_sel_hi:[0,1]
	v_pk_fma_f32 v[184:185], v[104:105], v[50:51], v[174:175] op_sel_hi:[1,0,1] neg_hi:[0,0,1]
	v_pk_fma_f32 v[104:105], v[104:105], v[50:51], v[174:175] op_sel_hi:[1,0,1] neg_hi:[0,0,1]
	v_pk_mul_f32 v[166:167], v[112:113], v[52:53] op_sel:[1,1] op_sel_hi:[0,1]
	v_pk_fma_f32 v[102:103], v[112:113], v[52:53], v[166:167] op_sel_hi:[1,0,1] neg_hi:[0,0,1]
	v_pk_fma_f32 v[112:113], v[112:113], v[52:53], v[166:167] op_sel_hi:[1,0,1] neg_hi:[0,0,1]
	v_pk_mul_f32 v[178:179], v[120:121], v[54:55] op_sel:[1,1] op_sel_hi:[0,1]
	v_pk_fma_f32 v[168:169], v[120:121], v[54:55], v[178:179] op_sel_hi:[1,0,1] neg_hi:[0,0,1]
	v_pk_fma_f32 v[120:121], v[120:121], v[54:55], v[178:179] op_sel_hi:[1,0,1] neg_hi:[0,0,1]
	v_pk_mul_f32 v[188:189], v[128:129], v[90:91] op_sel:[1,1] op_sel_hi:[0,1]
	v_pk_fma_f32 v[176:177], v[128:129], v[90:91], v[188:189] op_sel_hi:[1,0,1] neg_hi:[0,0,1]
	v_pk_fma_f32 v[128:129], v[128:129], v[90:91], v[188:189] op_sel_hi:[1,0,1] neg_hi:[0,0,1]
	s_nop 1
	v_permlane32_swap_b32_e32 v104, v184
	v_permlane32_swap_b32_e32 v105, v185
	v_permlane32_swap_b32_e32 v112, v102
	v_permlane32_swap_b32_e32 v113, v103
	v_permlane32_swap_b32_e32 v120, v168
	v_permlane32_swap_b32_e32 v121, v169
	v_permlane32_swap_b32_e32 v128, v176
	v_permlane32_swap_b32_e32 v129, v177
	v_pk_fma_f32 v[104:105], v[184:185], v[190:191], v[104:105] op_sel_hi:[1,0,1]
	ds_write_b64 v198, v[104:105] offset:64
	v_pk_fma_f32 v[112:113], v[102:103], v[190:191], v[112:113] op_sel_hi:[1,0,1]
	ds_write_b64 v198, v[112:113] offset:72
	v_pk_fma_f32 v[120:121], v[168:169], v[190:191], v[120:121] op_sel_hi:[1,0,1]
	ds_write_b64 v198, v[120:121] offset:80
	v_pk_fma_f32 v[128:129], v[176:177], v[190:191], v[128:129] op_sel_hi:[1,0,1]
	ds_write_b64 v198, v[128:129] offset:88
	v_pk_mul_f32 v[178:179], v[106:107], v[92:93] op_sel:[1,1] op_sel_hi:[0,1]
	v_pk_fma_f32 v[186:187], v[106:107], v[92:93], v[178:179] op_sel_hi:[1,0,1] neg_hi:[0,0,1]
	v_pk_fma_f32 v[106:107], v[106:107], v[92:93], v[178:179] op_sel_hi:[1,0,1] neg_hi:[0,0,1]
	v_pk_mul_f32 v[188:189], v[114:115], v[94:95] op_sel:[1,1] op_sel_hi:[0,1]
	v_pk_fma_f32 v[180:181], v[114:115], v[94:95], v[188:189] op_sel_hi:[1,0,1] neg_hi:[0,0,1]
	v_pk_fma_f32 v[114:115], v[114:115], v[94:95], v[188:189] op_sel_hi:[1,0,1] neg_hi:[0,0,1]
	v_pk_mul_f32 v[184:185], v[122:123], v[96:97] op_sel:[1,1] op_sel_hi:[0,1]
	v_pk_fma_f32 v[174:175], v[122:123], v[96:97], v[184:185] op_sel_hi:[1,0,1] neg_hi:[0,0,1]
	v_pk_fma_f32 v[122:123], v[122:123], v[96:97], v[184:185] op_sel_hi:[1,0,1] neg_hi:[0,0,1]
	v_pk_mul_f32 v[102:103], v[130:131], v[98:99] op_sel:[1,1] op_sel_hi:[0,1]
	v_pk_fma_f32 v[166:167], v[130:131], v[98:99], v[102:103] op_sel_hi:[1,0,1] neg_hi:[0,0,1]
	v_pk_fma_f32 v[130:131], v[130:131], v[98:99], v[102:103] op_sel_hi:[1,0,1] neg_hi:[0,0,1]
	s_nop 1
	v_permlane32_swap_b32_e32 v106, v186
	v_permlane32_swap_b32_e32 v107, v187
	v_permlane32_swap_b32_e32 v114, v180
	v_permlane32_swap_b32_e32 v115, v181
	v_permlane32_swap_b32_e32 v122, v174
	v_permlane32_swap_b32_e32 v123, v175
	v_permlane32_swap_b32_e32 v130, v166
	v_permlane32_swap_b32_e32 v131, v167
	v_pk_fma_f32 v[106:107], v[186:187], v[190:191], v[106:107] op_sel_hi:[1,0,1]
	ds_write_b64 v198, v[106:107] offset:96
	v_pk_fma_f32 v[114:115], v[180:181], v[190:191], v[114:115] op_sel_hi:[1,0,1]
	ds_write_b64 v198, v[114:115] offset:104
	v_pk_fma_f32 v[122:123], v[174:175], v[190:191], v[122:123] op_sel_hi:[1,0,1]
	ds_write_b64 v198, v[122:123] offset:112
	v_pk_fma_f32 v[130:131], v[166:167], v[190:191], v[130:131] op_sel_hi:[1,0,1]
	ds_write_b64 v198, v[130:131] offset:120
	s_waitcnt lgkmcnt(0)
	ds_read_b64 v[100:101], v5
	ds_read_b64 v[108:109], v5 offset:264
	ds_read_b64 v[168:169], v56 offset:256
	ds_read_b64 v[116:117], v5 offset:528
	ds_read_b64 v[176:177], v56 offset:512
	ds_read_b64 v[124:125], v5 offset:792
	ds_read_b64 v[178:179], v56 offset:768
	ds_read_b64 v[126:127], v5 offset:1056
	ds_read_b64 v[188:189], v56 offset:1024
	ds_read_b64 v[118:119], v5 offset:1320
	ds_read_b64 v[184:185], v56 offset:1280
	s_waitcnt lgkmcnt(8)
	v_pk_mul_f32 v[102:103], v[108:109], v[168:169] op_sel:[1,1] op_sel_hi:[0,1]
	v_pk_fma_f32 v[108:109], v[108:109], v[168:169], v[102:103] op_sel_hi:[1,0,1] neg_hi:[0,0,1]
	s_waitcnt lgkmcnt(6)
	v_pk_mul_f32 v[186:187], v[116:117], v[176:177] op_sel:[1,1] op_sel_hi:[0,1]
	v_pk_fma_f32 v[116:117], v[116:117], v[176:177], v[186:187] op_sel_hi:[1,0,1] neg_hi:[0,0,1]
	s_waitcnt lgkmcnt(4)
	v_pk_mul_f32 v[180:181], v[124:125], v[178:179] op_sel:[1,1] op_sel_hi:[0,1]
	v_pk_fma_f32 v[124:125], v[124:125], v[178:179], v[180:181] op_sel_hi:[1,0,1] neg_hi:[0,0,1]
	s_waitcnt lgkmcnt(2)
	v_pk_mul_f32 v[174:175], v[126:127], v[188:189] op_sel:[1,1] op_sel_hi:[0,1]
	v_pk_fma_f32 v[126:127], v[126:127], v[188:189], v[174:175] op_sel_hi:[1,0,1] neg_hi:[0,0,1]
	s_waitcnt lgkmcnt(0)
; __device__ __forceinline__ f32x2 cmulc(f32x2 a, f32x2 b) { return (f32x2){a.x * b.x + a.y * b.y, a.y * b.x - a.x * b.y}; }
; template <bool INV> __device__ __forceinline__ f32x2 cmul_tw(f32x2 a, f32x2 w) { return INV ? cmulc(a, w) : cmul(a, w); }
; template <bool INV> __device__ __forceinline__ void dft16(f32x2 (&x)[16]) {
;     constexpr float C1 = 0.92387953251128674f, S1 = 0.38268343236508977f, C2 = 0.70710678118654752f;
; #pragma unroll
;     for (int b = 0; b < 4; ++b) dft4<INV>(x[b], x[4 + b], x[8 + b], x[12 + b]);
;     const f32x2 w1 = {C1, -S1}, w2 = {C2, -C2}, w3 = {S1, -C1}, w4 = {0.f, -1.f}, w6 = {-C2, -C2}, w9 = {-C1, S1};
;     x[4 * 1 + 1] = cmul_tw<INV>(x[5], w1); x[4 * 1 + 2] = cmul_tw<INV>(x[6], w2); x[4 * 1 + 3] = cmul_tw<INV>(x[7], w3);
;     x[4 * 2 + 1] = cmul_tw<INV>(x[9], w2); x[4 * 2 + 2] = cmul_tw<INV>(x[10], w4); x[4 * 2 + 3] = cmul_tw<INV>(x[11], w6);
;     x[4 * 3 + 1] = cmul_tw<INV>(x[13], w3); x[4 * 3 + 2] = cmul_tw<INV>(x[14], w6); x[4 * 3 + 3] = cmul_tw<INV>(x[15], w9);
; __device__ __forceinline__ void fft_inv2(LAS f32x2* B, const LAS f32x2* TW2, int tid) {
;     ...
;     x[0] = B[fpad(base)];
; #pragma unroll
;     for (int k = 1; k < 16; ++k) x[k] = cmulc(B[fpad(base + 32 * k)], TW2[k * 32 + n2]);
;     dft16<true>(x);
	v_pk_mul_f32 v[166:167], v[118:119], v[184:185] op_sel:[1,1] op_sel_hi:[0,1]
	v_pk_fma_f32 v[118:119], v[118:119], v[184:185], v[166:167] op_sel_hi:[1,0,1] neg_hi:[0,0,1]
	ds_read_b64 v[182:183], v5 offset:1584
	ds_read_b64 v[102:103], v56 offset:1536
	ds_read_b64 v[110:111], v5 offset:1848
	ds_read_b64 v[186:187], v56 offset:1792
	ds_read_b64 v[104:105], v5 offset:2112
	ds_read_b64 v[180:181], v56 offset:2048
	ds_read_b64 v[112:113], v5 offset:2376
	ds_read_b64 v[174:175], v56 offset:2304
	ds_read_b64 v[120:121], v5 offset:2640
	ds_read_b64 v[166:167], v56 offset:2560
	s_waitcnt lgkmcnt(8)
	v_pk_mul_f32 v[168:169], v[182:183], v[102:103] op_sel:[1,1] op_sel_hi:[0,1]
	v_pk_fma_f32 v[182:183], v[182:183], v[102:103], v[168:169] op_sel_hi:[1,0,1] neg_hi:[0,0,1]
	s_waitcnt lgkmcnt(6)
	v_pk_mul_f32 v[176:177], v[110:111], v[186:187] op_sel:[1,1] op_sel_hi:[0,1]
	v_pk_fma_f32 v[110:111], v[110:111], v[186:187], v[176:177] op_sel_hi:[1,0,1] neg_hi:[0,0,1]
	s_waitcnt lgkmcnt(4)
	v_pk_mul_f32 v[178:179], v[104:105], v[180:181] op_sel:[1,1] op_sel_hi:[0,1]
	v_pk_fma_f32 v[104:105], v[104:105], v[180:181], v[178:179] op_sel_hi:[1,0,1] neg_hi:[0,0,1]
	s_waitcnt lgkmcnt(2)
	v_pk_mul_f32 v[188:189], v[112:113], v[174:175] op_sel:[1,1] op_sel_hi:[0,1]
	v_pk_fma_f32 v[112:113], v[112:113], v[174:175], v[188:189] op_sel_hi:[1,0,1] neg_hi:[0,0,1]
	s_waitcnt lgkmcnt(0)
	v_pk_mul_f32 v[184:185], v[120:121], v[166:167] op_sel:[1,1] op_sel_hi:[0,1]
	v_pk_fma_f32 v[120:121], v[120:121], v[166:167], v[184:185] op_sel_hi:[1,0,1] neg_hi:[0,0,1]
	ds_read_b64 v[128:129], v5 offset:2904
	ds_read_b64 v[168:169], v56 offset:2816
	ds_read_b64 v[106:107], v5 offset:3168
	ds_read_b64 v[176:177], v56 offset:3072
	ds_read_b64 v[114:115], v5 offset:3432
	ds_read_b64 v[178:179], v56 offset:3328
	ds_read_b64 v[122:123], v5 offset:3696
	ds_read_b64 v[188:189], v56 offset:3584
	ds_read_b64 v[130:131], v5 offset:3960
	ds_read_b64 v[184:185], v56 offset:3840
	s_waitcnt lgkmcnt(8)
	v_pk_mul_f32 v[102:103], v[128:129], v[168:169] op_sel:[1,1] op_sel_hi:[0,1]
	v_pk_fma_f32 v[128:129], v[128:129], v[168:169], v[102:103] op_sel_hi:[1,0,1] neg_hi:[0,0,1]
	s_waitcnt lgkmcnt(6)
	v_pk_mul_f32 v[186:187], v[106:107], v[176:177] op_sel:[1,1] op_sel_hi:[0,1]
	v_pk_fma_f32 v[106:107], v[106:107], v[176:177], v[186:187] op_sel_hi:[1,0,1] neg_hi:[0,0,1]
	s_waitcnt lgkmcnt(4)
	v_pk_mul_f32 v[180:181], v[114:115], v[178:179] op_sel:[1,1] op_sel_hi:[0,1]
	v_pk_fma_f32 v[114:115], v[114:115], v[178:179], v[180:181] op_sel_hi:[1,0,1] neg_hi:[0,0,1]
	s_waitcnt lgkmcnt(2)
	v_pk_mul_f32 v[174:175], v[122:123], v[188:189] op_sel:[1,1] op_sel_hi:[0,1]
	v_pk_fma_f32 v[122:123], v[122:123], v[188:189], v[174:175] op_sel_hi:[1,0,1] neg_hi:[0,0,1]
	s_waitcnt lgkmcnt(0)
	v_pk_mul_f32 v[166:167], v[130:131], v[184:185] op_sel:[1,1] op_sel_hi:[0,1]
	v_pk_fma_f32 v[130:131], v[130:131], v[184:185], v[166:167] op_sel_hi:[1,0,1] neg_hi:[0,0,1]
	v_pk_add_f32 v[102:103], v[100:101], v[104:105]
	v_pk_add_f32 v[186:187], v[100:101], v[104:105] neg_lo:[0,1] neg_hi:[0,1]
	v_pk_add_f32 v[180:181], v[126:127], v[106:107]
	v_pk_add_f32 v[174:175], v[126:127], v[106:107] neg_lo:[0,1] neg_hi:[0,1]
	v_pk_add_f32 v[100:101], v[102:103], v[180:181]
	v_pk_add_f32 v[104:105], v[102:103], v[180:181] neg_lo:[0,1] neg_hi:[0,1]
	v_pk_add_f32 v[126:127], v[186:187], v[174:175] op_sel:[0,1] op_sel_hi:[1,0] neg_lo:[0,1]
	v_pk_add_f32 v[106:107], v[186:187], v[174:175] op_sel:[0,1] op_sel_hi:[1,0] neg_hi:[0,1]
	v_pk_add_f32 v[166:167], v[108:109], v[112:113]
	v_pk_add_f32 v[168:169], v[108:109], v[112:113] neg_lo:[0,1] neg_hi:[0,1]
	v_pk_add_f32 v[176:177], v[118:119], v[114:115]
	v_pk_add_f32 v[178:179], v[118:119], v[114:115] neg_lo:[0,1] neg_hi:[0,1]
	v_pk_add_f32 v[108:109], v[166:167], v[176:177]
	v_pk_add_f32 v[112:113], v[166:167], v[176:177] neg_lo:[0,1] neg_hi:[0,1]
	v_pk_add_f32 v[118:119], v[168:169], v[178:179] op_sel:[0,1] op_sel_hi:[1,0] neg_lo:[0,1]
	v_pk_add_f32 v[114:115], v[168:169], v[178:179] op_sel:[0,1] op_sel_hi:[1,0] neg_hi:[0,1]
	v_pk_add_f32 v[188:189], v[116:117], v[120:121]
	v_pk_add_f32 v[184:185], v[116:117], v[120:121] neg_lo:[0,1] neg_hi:[0,1]
	v_pk_add_f32 v[102:103], v[182:183], v[122:123]
	v_pk_add_f32 v[186:187], v[182:183], v[122:123] neg_lo:[0,1] neg_hi:[0,1]
	v_pk_add_f32 v[116:117], v[188:189], v[102:103]
	v_pk_add_f32 v[120:121], v[188:189], v[102:103] neg_lo:[0,1] neg_hi:[0,1]
	v_pk_add_f32 v[182:183], v[184:185], v[186:187] op_sel:[0,1] op_sel_hi:[1,0] neg_lo:[0,1]
	v_pk_add_f32 v[122:123], v[184:185], v[186:187] op_sel:[0,1] op_sel_hi:[1,0] neg_hi:[0,1]
	v_pk_add_f32 v[180:181], v[124:125], v[128:129]
	v_pk_add_f32 v[174:175], v[124:125], v[128:129] neg_lo:[0,1] neg_hi:[0,1]
	v_pk_add_f32 v[166:167], v[110:111], v[130:131]
	v_pk_add_f32 v[168:169], v[110:111], v[130:131] neg_lo:[0,1] neg_hi:[0,1]
	v_pk_add_f32 v[124:125], v[180:181], v[166:167]
	v_pk_add_f32 v[128:129], v[180:181], v[166:167] neg_lo:[0,1] neg_hi:[0,1]
	v_pk_add_f32 v[110:111], v[174:175], v[168:169] op_sel:[0,1] op_sel_hi:[1,0] neg_lo:[0,1]
	v_pk_add_f32 v[130:131], v[174:175], v[168:169] op_sel:[0,1] op_sel_hi:[1,0] neg_hi:[0,1]
	v_pk_mul_f32 v[176:177], v[118:119], s[68:69] op_sel:[1,1] op_sel_hi:[0,1]
	v_pk_fma_f32 v[118:119], v[118:119], s[68:69], v[176:177] op_sel_hi:[1,0,1] neg_hi:[0,0,1]
	v_pk_mul_f32 v[178:179], v[182:183], s[84:85] op_sel:[1,1] op_sel_hi:[0,1]
	v_pk_fma_f32 v[182:183], v[182:183], s[84:85], v[178:179] op_sel_hi:[1,0,1] neg_hi:[0,0,1]
	v_pk_mul_f32 v[188:189], v[110:111], s[88:89] op_sel:[1,1] op_sel_hi:[0,1]
	v_pk_fma_f32 v[110:111], v[110:111], s[88:89], v[188:189] op_sel_hi:[1,0,1] neg_hi:[0,0,1]
; #define LAS __attribute__((address_space(3)))
; __device__ __forceinline__ f32x2 cmulc(f32x2 a, f32x2 b) { return (f32x2){a.x * b.x + a.y * b.y, a.y * b.x - a.x * b.y}; }
; template <bool INV> __device__ __forceinline__ f32x2 cmul_tw(f32x2 a, f32x2 w) { return INV ? cmulc(a, w) : cmul(a, w); }
; #define WG_SYNC() do { asm volatile("s_waitcnt lgkmcnt(0)" ::: "memory"); __builtin_amdgcn_s_barrier(); asm volatile("" ::: "memory"); } while (0)
; template <bool INV> __device__ __forceinline__ void dft16(f32x2 (&x)[16]) {
;     ...
;     const f32x2 w1 = {C1, -S1}, w2 = {C2, -C2}, w3 = {S1, -C1}, w4 = {0.f, -1.f}, w6 = {-C2, -C2}, w9 = {-C1, S1};
;     x[4 * 1 + 1] = cmul_tw<INV>(x[5], w1); x[4 * 1 + 2] = cmul_tw<INV>(x[6], w2); x[4 * 1 + 3] = cmul_tw<INV>(x[7], w3);
;     x[4 * 2 + 1] = cmul_tw<INV>(x[9], w2); x[4 * 2 + 2] = cmul_tw<INV>(x[10], w4); x[4 * 2 + 3] = cmul_tw<INV>(x[11], w6);
;     x[4 * 3 + 1] = cmul_tw<INV>(x[13], w3); x[4 * 3 + 2] = cmul_tw<INV>(x[14], w6); x[4 * 3 + 3] = cmul_tw<INV>(x[15], w9);
; #pragma unroll
;     for (int c = 0; c < 4; ++c) dft4<INV>(x[4 * c], x[4 * c + 1], x[4 * c + 2], x[4 * c + 3]);
;     f32x2 y[16];
; #pragma unroll
;     for (int k = 0; k < 16; ++k) y[k] = x[4 * (k & 3) + (k >> 2)];
; #pragma unroll
;     for (int k = 0; k < 16; ++k) x[k] = y[k];
; __device__ __forceinline__ void fft_inv2(LAS f32x2* B, const LAS f32x2* TW2, int tid) {
;     ...
;     for (int r = 0; r < 16; ++r) B[fpad(base + 32 * r)] = x[r];
; }
; __device__ __forceinline__ void fft_inv1(f32x2 (&x)[16], const LAS f32x2* B, int n2, const f32x2 (&w)[16]) {
;     asm volatile("" : "+v"(n2));
;     x[0] = B[fpad(n2)];
; #pragma unroll
;     for (int k = 1; k < 16; ++k) x[k] = cmulc(B[fpad(512 * k + n2)], w[k]);
; __device__ __forceinline__ void hyena_fft(LAS unsigned char* lds, int layer, int G, const int wave_s) {
;     ...
;             WG_SYNC(); fft_inv1(x, Db, n2, w1p);
	v_pk_mul_f32 v[184:185], v[112:113], s[84:85] op_sel:[1,1] op_sel_hi:[0,1]
	v_pk_fma_f32 v[112:113], v[112:113], s[84:85], v[184:185] op_sel_hi:[1,0,1] neg_hi:[0,0,1]
	v_pk_mul_f32 v[102:103], v[128:129], s[90:91] op_sel:[1,1] op_sel_hi:[0,1]
	v_pk_fma_f32 v[128:129], v[128:129], s[90:91], v[102:103] op_sel_hi:[1,0,1] neg_hi:[0,0,1]
	v_pk_mul_f32 v[186:187], v[114:115], s[88:89] op_sel:[1,1] op_sel_hi:[0,1]
	v_pk_fma_f32 v[114:115], v[114:115], s[88:89], v[186:187] op_sel_hi:[1,0,1] neg_hi:[0,0,1]
	v_pk_mul_f32 v[180:181], v[122:123], s[90:91] op_sel:[1,1] op_sel_hi:[0,1]
	v_pk_fma_f32 v[122:123], v[122:123], s[90:91], v[180:181] op_sel_hi:[1,0,1] neg_hi:[0,0,1]
	v_pk_mul_f32 v[174:175], v[130:131], s[98:99] op_sel:[1,1] op_sel_hi:[0,1]
	v_pk_fma_f32 v[130:131], v[130:131], s[98:99], v[174:175] op_sel_hi:[1,0,1] neg_hi:[0,0,1]
	v_pk_add_f32 v[166:167], v[100:101], v[116:117]
	v_pk_add_f32 v[168:169], v[100:101], v[116:117] neg_lo:[0,1] neg_hi:[0,1]
	v_pk_add_f32 v[176:177], v[108:109], v[124:125]
	v_pk_add_f32 v[178:179], v[108:109], v[124:125] neg_lo:[0,1] neg_hi:[0,1]
	v_pk_add_f32 v[100:101], v[166:167], v[176:177]
	v_pk_add_f32 v[116:117], v[166:167], v[176:177] neg_lo:[0,1] neg_hi:[0,1]
	v_pk_add_f32 v[108:109], v[168:169], v[178:179] op_sel:[0,1] op_sel_hi:[1,0] neg_lo:[0,1]
	v_pk_add_f32 v[124:125], v[168:169], v[178:179] op_sel:[0,1] op_sel_hi:[1,0] neg_hi:[0,1]
	v_pk_add_f32 v[188:189], v[126:127], v[182:183]
	v_pk_add_f32 v[184:185], v[126:127], v[182:183] neg_lo:[0,1] neg_hi:[0,1]
	v_pk_add_f32 v[102:103], v[118:119], v[110:111]
	v_pk_add_f32 v[186:187], v[118:119], v[110:111] neg_lo:[0,1] neg_hi:[0,1]
	v_pk_add_f32 v[126:127], v[188:189], v[102:103]
	v_pk_add_f32 v[182:183], v[188:189], v[102:103] neg_lo:[0,1] neg_hi:[0,1]
	v_pk_add_f32 v[118:119], v[184:185], v[186:187] op_sel:[0,1] op_sel_hi:[1,0] neg_lo:[0,1]
	v_pk_add_f32 v[110:111], v[184:185], v[186:187] op_sel:[0,1] op_sel_hi:[1,0] neg_hi:[0,1]
	v_pk_add_f32 v[180:181], v[104:105], v[120:121] op_sel:[0,1] op_sel_hi:[1,0] neg_lo:[0,1]
	v_pk_add_f32 v[174:175], v[104:105], v[120:121] op_sel:[0,1] op_sel_hi:[1,0] neg_hi:[0,1]
	v_pk_add_f32 v[166:167], v[112:113], v[128:129]
	v_pk_add_f32 v[168:169], v[112:113], v[128:129] neg_lo:[0,1] neg_hi:[0,1]
	v_pk_add_f32 v[104:105], v[180:181], v[166:167]
	v_pk_add_f32 v[120:121], v[180:181], v[166:167] neg_lo:[0,1] neg_hi:[0,1]
	v_pk_add_f32 v[112:113], v[174:175], v[168:169] op_sel:[0,1] op_sel_hi:[1,0] neg_lo:[0,1]
	v_pk_add_f32 v[128:129], v[174:175], v[168:169] op_sel:[0,1] op_sel_hi:[1,0] neg_hi:[0,1]
	v_pk_add_f32 v[176:177], v[106:107], v[122:123]
	v_pk_add_f32 v[178:179], v[106:107], v[122:123] neg_lo:[0,1] neg_hi:[0,1]
	v_pk_add_f32 v[188:189], v[114:115], v[130:131]
	v_pk_add_f32 v[184:185], v[114:115], v[130:131] neg_lo:[0,1] neg_hi:[0,1]
	v_pk_add_f32 v[106:107], v[176:177], v[188:189]
	v_pk_add_f32 v[122:123], v[176:177], v[188:189] neg_lo:[0,1] neg_hi:[0,1]
	v_pk_add_f32 v[114:115], v[178:179], v[184:185] op_sel:[0,1] op_sel_hi:[1,0] neg_lo:[0,1]
	v_pk_add_f32 v[130:131], v[178:179], v[184:185] op_sel:[0,1] op_sel_hi:[1,0] neg_hi:[0,1]
	ds_write_b64 v5, v[100:101]
	ds_write_b64 v5, v[126:127] offset:264
	ds_write_b64 v5, v[104:105] offset:528
	ds_write_b64 v5, v[106:107] offset:792
	ds_write_b64 v5, v[108:109] offset:1056
	ds_write_b64 v5, v[118:119] offset:1320
	ds_write_b64 v5, v[112:113] offset:1584
	ds_write_b64 v5, v[114:115] offset:1848
	ds_write_b64 v5, v[116:117] offset:2112
	ds_write_b64 v5, v[182:183] offset:2376
	ds_write_b64 v5, v[120:121] offset:2640
	ds_write_b64 v5, v[122:123] offset:2904
	ds_write_b64 v5, v[124:125] offset:3168
	ds_write_b64 v5, v[110:111] offset:3432
	ds_write_b64 v5, v[128:129] offset:3696
	ds_write_b64 v5, v[130:131] offset:3960
	s_waitcnt lgkmcnt(0)
	s_barrier
	ds_read_b64 v[100:101], v3
	ds_read_b64 v[108:109], v3 offset:16896
	ds_read_b64 v[116:117], v3 offset:33792
	ds_read_b64 v[124:125], v3 offset:50688
	ds_read_b64 v[126:127], v3 offset:4224
	ds_read_b64 v[118:119], v3 offset:21120
	ds_read_b64 v[182:183], v3 offset:38016
	ds_read_b64 v[110:111], v3 offset:54912
	ds_read_b64 v[104:105], v3 offset:8448
	ds_read_b64 v[112:113], v3 offset:25344
	ds_read_b64 v[120:121], v3 offset:42240
	ds_read_b64 v[128:129], v3 offset:59136
	ds_read_b64 v[106:107], v3 offset:12672
	ds_read_b64 v[114:115], v3 offset:29568
	ds_read_b64 v[122:123], v3 offset:46464
	ds_read_b64 v[130:131], v3 offset:63360
	s_waitcnt lgkmcnt(14)
	v_pk_mul_f32 v[102:103], v[108:109], v[12:13] op_sel:[1,1] op_sel_hi:[0,1]
	v_pk_fma_f32 v[108:109], v[108:109], v[12:13], v[102:103] op_sel_hi:[1,0,1] neg_hi:[0,0,1]
	s_waitcnt lgkmcnt(13)
	v_pk_mul_f32 v[186:187], v[116:117], v[20:21] op_sel:[1,1] op_sel_hi:[0,1]
	v_pk_fma_f32 v[116:117], v[116:117], v[20:21], v[186:187] op_sel_hi:[1,0,1] neg_hi:[0,0,1]
	s_waitcnt lgkmcnt(12)
	v_pk_mul_f32 v[180:181], v[124:125], v[28:29] op_sel:[1,1] op_sel_hi:[0,1]
	v_pk_fma_f32 v[124:125], v[124:125], v[28:29], v[180:181] op_sel_hi:[1,0,1] neg_hi:[0,0,1]
	s_waitcnt lgkmcnt(11)
	v_pk_mul_f32 v[174:175], v[126:127], v[6:7] op_sel:[1,1] op_sel_hi:[0,1]
	v_pk_fma_f32 v[126:127], v[126:127], v[6:7], v[174:175] op_sel_hi:[1,0,1] neg_hi:[0,0,1]
	s_waitcnt lgkmcnt(10)
	v_pk_mul_f32 v[166:167], v[118:119], v[14:15] op_sel:[1,1] op_sel_hi:[0,1]
	v_pk_fma_f32 v[118:119], v[118:119], v[14:15], v[166:167] op_sel_hi:[1,0,1] neg_hi:[0,0,1]
	s_waitcnt lgkmcnt(9)
	v_pk_mul_f32 v[168:169], v[182:183], v[22:23] op_sel:[1,1] op_sel_hi:[0,1]
	v_pk_fma_f32 v[182:183], v[182:183], v[22:23], v[168:169] op_sel_hi:[1,0,1] neg_hi:[0,0,1]
	s_waitcnt lgkmcnt(8)
; __device__ __forceinline__ f32x2 cmulc(f32x2 a, f32x2 b) { return (f32x2){a.x * b.x + a.y * b.y, a.y * b.x - a.x * b.y}; }
; __device__ __forceinline__ void dft16_inv_lo(f32x2 (&x)[16]) {
;     constexpr float C1 = 0.92387953251128674f, S1 = 0.38268343236508977f, C2 = 0.70710678118654752f;
; #pragma unroll
;     for (int b = 0; b < 4; ++b) dft4<true>(x[b], x[4 + b], x[8 + b], x[12 + b]);
;     const f32x2 w1 = {C1, -S1}, w2 = {C2, -C2}, w3 = {S1, -C1}, w4 = {0.f, -1.f}, w6 = {-C2, -C2}, w9 = {-C1, S1};
;     x[5] = cmulc(x[5], w1); x[6] = cmulc(x[6], w2); x[7] = cmulc(x[7], w3);
;     x[9] = cmulc(x[9], w2); x[10] = cmulc(x[10], w4); x[11] = cmulc(x[11], w6);
;     x[13] = cmulc(x[13], w3); x[14] = cmulc(x[14], w6); x[15] = cmulc(x[15], w9);
;     f32x2 y[8];
; #pragma unroll
;     for (int c = 0; c < 4; ++c) { const f32x2 t0 = x[4 * c] + x[4 * c + 2], t1 = x[4 * c] - x[4 * c + 2], t2 = x[4 * c + 1] + x[4 * c + 3], t3 = x[4 * c + 1] - x[4 * c + 3];
;         y[c] = t0 + t2; y[4 + c] = t1 + (f32x2){-t3.y, t3.x}; }
; #pragma unroll
;     for (int k = 0; k < 8; ++k) x[k] = y[k];
; __device__ __forceinline__ void hyena_fft(LAS unsigned char* lds, int layer, int G, const int wave_s) {
;     ...
;             { const float fb1 = fbias[HY + c]; float* zo = ZT + (size_t)c * MT;
	v_pk_mul_f32 v[176:177], v[110:111], v[30:31] op_sel:[1,1] op_sel_hi:[0,1]
	v_pk_fma_f32 v[110:111], v[110:111], v[30:31], v[176:177] op_sel_hi:[1,0,1] neg_hi:[0,0,1]
	s_waitcnt lgkmcnt(7)
	v_pk_mul_f32 v[178:179], v[104:105], v[8:9] op_sel:[1,1] op_sel_hi:[0,1]
	v_pk_fma_f32 v[104:105], v[104:105], v[8:9], v[178:179] op_sel_hi:[1,0,1] neg_hi:[0,0,1]
	s_waitcnt lgkmcnt(6)
	v_pk_mul_f32 v[188:189], v[112:113], v[16:17] op_sel:[1,1] op_sel_hi:[0,1]
	v_pk_fma_f32 v[112:113], v[112:113], v[16:17], v[188:189] op_sel_hi:[1,0,1] neg_hi:[0,0,1]
	s_waitcnt lgkmcnt(5)
	v_pk_mul_f32 v[184:185], v[120:121], v[24:25] op_sel:[1,1] op_sel_hi:[0,1]
	v_pk_fma_f32 v[120:121], v[120:121], v[24:25], v[184:185] op_sel_hi:[1,0,1] neg_hi:[0,0,1]
	s_waitcnt lgkmcnt(4)
	v_pk_mul_f32 v[102:103], v[128:129], v[32:33] op_sel:[1,1] op_sel_hi:[0,1]
	v_pk_fma_f32 v[128:129], v[128:129], v[32:33], v[102:103] op_sel_hi:[1,0,1] neg_hi:[0,0,1]
	s_waitcnt lgkmcnt(3)
	v_pk_mul_f32 v[186:187], v[106:107], v[10:11] op_sel:[1,1] op_sel_hi:[0,1]
	v_pk_fma_f32 v[106:107], v[106:107], v[10:11], v[186:187] op_sel_hi:[1,0,1] neg_hi:[0,0,1]
	s_waitcnt lgkmcnt(2)
	v_pk_mul_f32 v[180:181], v[114:115], v[18:19] op_sel:[1,1] op_sel_hi:[0,1]
	v_pk_fma_f32 v[114:115], v[114:115], v[18:19], v[180:181] op_sel_hi:[1,0,1] neg_hi:[0,0,1]
	s_waitcnt lgkmcnt(1)
	v_pk_mul_f32 v[174:175], v[122:123], v[26:27] op_sel:[1,1] op_sel_hi:[0,1]
	v_pk_fma_f32 v[122:123], v[122:123], v[26:27], v[174:175] op_sel_hi:[1,0,1] neg_hi:[0,0,1]
	s_waitcnt lgkmcnt(0)
	v_pk_mul_f32 v[166:167], v[130:131], v[34:35] op_sel:[1,1] op_sel_hi:[0,1]
	v_pk_fma_f32 v[130:131], v[130:131], v[34:35], v[166:167] op_sel_hi:[1,0,1] neg_hi:[0,0,1]
	v_pk_add_f32 v[168:169], v[100:101], v[116:117]
	v_pk_add_f32 v[176:177], v[100:101], v[116:117] neg_lo:[0,1] neg_hi:[0,1]
	v_pk_add_f32 v[178:179], v[108:109], v[124:125]
	v_pk_add_f32 v[188:189], v[108:109], v[124:125] neg_lo:[0,1] neg_hi:[0,1]
	v_pk_add_f32 v[100:101], v[168:169], v[178:179]
	v_pk_add_f32 v[116:117], v[168:169], v[178:179] neg_lo:[0,1] neg_hi:[0,1]
	v_pk_add_f32 v[108:109], v[176:177], v[188:189] op_sel:[0,1] op_sel_hi:[1,0] neg_lo:[0,1]
	v_pk_add_f32 v[124:125], v[176:177], v[188:189] op_sel:[0,1] op_sel_hi:[1,0] neg_hi:[0,1]
	v_pk_add_f32 v[184:185], v[126:127], v[182:183]
	v_pk_add_f32 v[102:103], v[126:127], v[182:183] neg_lo:[0,1] neg_hi:[0,1]
	v_pk_add_f32 v[186:187], v[118:119], v[110:111]
	v_pk_add_f32 v[180:181], v[118:119], v[110:111] neg_lo:[0,1] neg_hi:[0,1]
	v_pk_add_f32 v[126:127], v[184:185], v[186:187]
	v_pk_add_f32 v[182:183], v[184:185], v[186:187] neg_lo:[0,1] neg_hi:[0,1]
	v_pk_add_f32 v[118:119], v[102:103], v[180:181] op_sel:[0,1] op_sel_hi:[1,0] neg_lo:[0,1]
	v_pk_add_f32 v[110:111], v[102:103], v[180:181] op_sel:[0,1] op_sel_hi:[1,0] neg_hi:[0,1]
	v_pk_add_f32 v[174:175], v[104:105], v[120:121]
	v_pk_add_f32 v[166:167], v[104:105], v[120:121] neg_lo:[0,1] neg_hi:[0,1]
	v_pk_add_f32 v[168:169], v[112:113], v[128:129]
	v_pk_add_f32 v[176:177], v[112:113], v[128:129] neg_lo:[0,1] neg_hi:[0,1]
	v_pk_add_f32 v[104:105], v[174:175], v[168:169]
	v_pk_add_f32 v[120:121], v[174:175], v[168:169] neg_lo:[0,1] neg_hi:[0,1]
	v_pk_add_f32 v[112:113], v[166:167], v[176:177] op_sel:[0,1] op_sel_hi:[1,0] neg_lo:[0,1]
	v_pk_add_f32 v[128:129], v[166:167], v[176:177] op_sel:[0,1] op_sel_hi:[1,0] neg_hi:[0,1]
	v_pk_add_f32 v[178:179], v[106:107], v[122:123]
	v_pk_add_f32 v[188:189], v[106:107], v[122:123] neg_lo:[0,1] neg_hi:[0,1]
	v_pk_add_f32 v[184:185], v[114:115], v[130:131]
	v_pk_add_f32 v[102:103], v[114:115], v[130:131] neg_lo:[0,1] neg_hi:[0,1]
	v_pk_add_f32 v[106:107], v[178:179], v[184:185]
	v_pk_add_f32 v[122:123], v[178:179], v[184:185] neg_lo:[0,1] neg_hi:[0,1]
	v_pk_add_f32 v[114:115], v[188:189], v[102:103] op_sel:[0,1] op_sel_hi:[1,0] neg_lo:[0,1]
	v_pk_add_f32 v[130:131], v[188:189], v[102:103] op_sel:[0,1] op_sel_hi:[1,0] neg_hi:[0,1]
	v_pk_mul_f32 v[186:187], v[118:119], s[68:69] op_sel:[1,1] op_sel_hi:[0,1]
	v_pk_fma_f32 v[118:119], v[118:119], s[68:69], v[186:187] op_sel_hi:[1,0,1] neg_hi:[0,0,1]
	v_pk_mul_f32 v[180:181], v[112:113], s[84:85] op_sel:[1,1] op_sel_hi:[0,1]
	v_pk_fma_f32 v[112:113], v[112:113], s[84:85], v[180:181] op_sel_hi:[1,0,1] neg_hi:[0,0,1]
	v_pk_mul_f32 v[174:175], v[114:115], s[88:89] op_sel:[1,1] op_sel_hi:[0,1]
	v_pk_fma_f32 v[114:115], v[114:115], s[88:89], v[174:175] op_sel_hi:[1,0,1] neg_hi:[0,0,1]
	v_pk_mul_f32 v[166:167], v[182:183], s[84:85] op_sel:[1,1] op_sel_hi:[0,1]
	v_pk_fma_f32 v[182:183], v[182:183], s[84:85], v[166:167] op_sel_hi:[1,0,1] neg_hi:[0,0,1]
	v_pk_mul_f32 v[168:169], v[122:123], s[90:91] op_sel:[1,1] op_sel_hi:[0,1]
	v_pk_fma_f32 v[122:123], v[122:123], s[90:91], v[168:169] op_sel_hi:[1,0,1] neg_hi:[0,0,1]
	v_pk_mul_f32 v[176:177], v[110:111], s[88:89] op_sel:[1,1] op_sel_hi:[0,1]
	v_pk_fma_f32 v[110:111], v[110:111], s[88:89], v[176:177] op_sel_hi:[1,0,1] neg_hi:[0,0,1]
	v_pk_mul_f32 v[178:179], v[128:129], s[90:91] op_sel:[1,1] op_sel_hi:[0,1]
	v_pk_fma_f32 v[128:129], v[128:129], s[90:91], v[178:179] op_sel_hi:[1,0,1] neg_hi:[0,0,1]
	v_pk_mul_f32 v[188:189], v[130:131], s[98:99] op_sel:[1,1] op_sel_hi:[0,1]
	v_pk_fma_f32 v[130:131], v[130:131], s[98:99], v[188:189] op_sel_hi:[1,0,1] neg_hi:[0,0,1]
	v_pk_add_f32 v[184:185], v[100:101], v[104:105]
	v_pk_add_f32 v[102:103], v[100:101], v[104:105] neg_lo:[0,1] neg_hi:[0,1]
	v_pk_add_f32 v[186:187], v[126:127], v[106:107]
	v_pk_add_f32 v[180:181], v[126:127], v[106:107] neg_lo:[0,1] neg_hi:[0,1]
	v_pk_add_f32 v[100:101], v[184:185], v[186:187]
	v_pk_add_f32 v[126:127], v[102:103], v[180:181] op_sel:[0,1] op_sel_hi:[1,0] neg_lo:[0,1]
	v_pk_add_f32 v[174:175], v[108:109], v[112:113]
	v_pk_add_f32 v[166:167], v[108:109], v[112:113] neg_lo:[0,1] neg_hi:[0,1]
	v_pk_add_f32 v[168:169], v[118:119], v[114:115]
	v_pk_add_f32 v[176:177], v[118:119], v[114:115] neg_lo:[0,1] neg_hi:[0,1]
	v_pk_add_f32 v[108:109], v[174:175], v[168:169]
	v_pk_add_f32 v[118:119], v[166:167], v[176:177] op_sel:[0,1] op_sel_hi:[1,0] neg_lo:[0,1]
	v_pk_add_f32 v[178:179], v[116:117], v[120:121] op_sel:[0,1] op_sel_hi:[1,0] neg_lo:[0,1]
	v_pk_add_f32 v[188:189], v[116:117], v[120:121] op_sel:[0,1] op_sel_hi:[1,0] neg_hi:[0,1]
	v_pk_add_f32 v[184:185], v[182:183], v[122:123]
	v_pk_add_f32 v[102:103], v[182:183], v[122:123] neg_lo:[0,1] neg_hi:[0,1]
	v_pk_add_f32 v[116:117], v[178:179], v[184:185]
	v_pk_add_f32 v[182:183], v[188:189], v[102:103] op_sel:[0,1] op_sel_hi:[1,0] neg_lo:[0,1]
	v_pk_add_f32 v[186:187], v[124:125], v[128:129]
	v_pk_add_f32 v[180:181], v[124:125], v[128:129] neg_lo:[0,1] neg_hi:[0,1]
	v_pk_add_f32 v[174:175], v[110:111], v[130:131]
	v_pk_add_f32 v[166:167], v[110:111], v[130:131] neg_lo:[0,1] neg_hi:[0,1]
	v_pk_add_f32 v[124:125], v[186:187], v[174:175]
	v_pk_add_f32 v[110:111], v[180:181], v[166:167] op_sel:[0,1] op_sel_hi:[1,0] neg_lo:[0,1]
	s_load_dword s35, s[50:51], 0x1000
	s_mul_i32 s43, s80, 0x8800
	s_add_u32 s46, s40, s43
	s_addc_u32 s47, s41, 0
	s_waitcnt lgkmcnt(0)
; __device__ __forceinline__ void hyena_fft(LAS unsigned char* lds, int layer, int G, const int wave_s) {
;     ...
;             { const float fb1 = fbias[HY + c]; float* zo = ZT + (size_t)c * MT;
; #pragma unroll
;               for (int r = 0; r < 8; ++r) { const int t = n2 + 512 * r;
;                   zo[t] = ux[r][0] * (x[r].x + fb1 * uz[r][0]); zo[SEQ + t] = ux[r][1] * (x[r].y + fb1 * uz[r][1]); } }
;         }
	v_mov_b32_e32 v194, s35
	v_pk_fma_f32 v[168:169], v[132:133], v[194:195], v[100:101] op_sel_hi:[1,0,1]
	v_pk_mul_f32 v[168:169], v[148:149], v[168:169]
	s_add_u32 s60, s46, 0
	s_addc_u32 s61, s47, 0
	s_add_u32 s62, s60, 0x4000
	s_addc_u32 s63, s61, 0
	global_store_dword v212, v168, s[60:61]
	global_store_dword v212, v169, s[62:63]
	v_pk_fma_f32 v[176:177], v[134:135], v[194:195], v[108:109] op_sel_hi:[1,0,1]
	v_pk_mul_f32 v[176:177], v[150:151], v[176:177]
	global_store_dword v212, v176, s[60:61] offset:2048
	global_store_dword v212, v177, s[62:63] offset:2048
	v_pk_fma_f32 v[178:179], v[136:137], v[194:195], v[116:117] op_sel_hi:[1,0,1]
	v_pk_mul_f32 v[178:179], v[152:153], v[178:179]
	s_add_u32 s60, s46, 0x1000
	s_addc_u32 s61, s47, 0
	s_add_u32 s62, s60, 0x4000
	s_addc_u32 s63, s61, 0
	global_store_dword v212, v178, s[60:61]
	global_store_dword v212, v179, s[62:63]
	v_pk_fma_f32 v[188:189], v[138:139], v[194:195], v[124:125] op_sel_hi:[1,0,1]
	v_pk_mul_f32 v[188:189], v[154:155], v[188:189]
	global_store_dword v212, v188, s[60:61] offset:2048
	global_store_dword v212, v189, s[62:63] offset:2048
	v_pk_fma_f32 v[184:185], v[140:141], v[194:195], v[126:127] op_sel_hi:[1,0,1]
	v_pk_mul_f32 v[184:185], v[158:159], v[184:185]
	s_add_u32 s60, s46, 0x2000
	s_addc_u32 s61, s47, 0
	s_add_u32 s62, s60, 0x4000
	s_addc_u32 s63, s61, 0
	global_store_dword v212, v184, s[60:61]
	global_store_dword v212, v185, s[62:63]
	v_pk_fma_f32 v[102:103], v[142:143], v[194:195], v[118:119] op_sel_hi:[1,0,1]
	v_pk_mul_f32 v[102:103], v[160:161], v[102:103]
	global_store_dword v212, v102, s[60:61] offset:2048
	global_store_dword v212, v103, s[62:63] offset:2048
	v_pk_fma_f32 v[186:187], v[144:145], v[194:195], v[182:183] op_sel_hi:[1,0,1]
	v_pk_mul_f32 v[186:187], v[162:163], v[186:187]
	s_add_u32 s60, s46, 0x3000
	s_addc_u32 s61, s47, 0
	s_add_u32 s62, s60, 0x4000
	s_addc_u32 s63, s61, 0
	global_store_dword v212, v186, s[60:61]
	global_store_dword v212, v187, s[62:63]
	v_pk_fma_f32 v[180:181], v[146:147], v[194:195], v[110:111] op_sel_hi:[1,0,1]
	v_pk_mul_f32 v[180:181], v[164:165], v[180:181]
	global_store_dword v212, v180, s[60:61] offset:2048
	global_store_dword v212, v181, s[62:63] offset:2048
	s_add_u32 s80, s80, 1
	s_cmp_lt_i32 s80, s93
	s_cbranch_scc1 .Lhfft_loop
	s_waitcnt vmcnt(0) lgkmcnt(0)
